# combo21 + FFT: rotated butterfly differences written directly by one v_pk_add_f32 (op_sel/neg modifiers) instead of sub + v_xor + v_mov (91 sites)
# speedup vs baseline: 1.0025x; 1.0000x over previous
.Lmy_fft_kj:
	v_mov_b32 v66, 0
	v_mov_b32_e32 v68, v1
	v_add_u32_e32 v0, v66, v0
	v_cvt_f32_i32_e32 v70, v0
	v_ashrrev_i32_e32 v66, 5, v0
	v_lshlrev_b32_e32 v69, 3, v0
	v_add_u32_e32 v73, 0x400, v0
	v_add_u32_e32 v75, 0x800, v0
	v_add_u32_e32 v76, 0xc00, v0
	v_add_u32_e32 v78, 0x1000, v0
	v_add_u32_e32 v80, 0x1400, v0
	v_add_u32_e32 v82, 0x1800, v0
	v_add_u32_e32 v85, 0x1c00, v0
	v_add_u32_e32 v87, 0x2000, v0
	v_add_u32_e32 v89, 0x2400, v0
	v_add_u32_e32 v91, 0x2800, v0
	v_add_u32_e32 v92, 0x2c00, v0
	v_add_u32_e32 v95, 0x3000, v0
	v_add_u32_e32 v96, 0x3400, v0
	v_add_u32_e32 v99, 0x3800, v0
	v_add_u32_e32 v0, 0x3c00, v0
	v_lshlrev_b32_e32 v66, 3, v66
	v_ashrrev_i32_e32 v73, 5, v73
	v_ashrrev_i32_e32 v75, 5, v75
	v_ashrrev_i32_e32 v76, 5, v76
	v_ashrrev_i32_e32 v78, 5, v78
	v_ashrrev_i32_e32 v80, 5, v80
	v_ashrrev_i32_e32 v82, 5, v82
	v_ashrrev_i32_e32 v85, 5, v85
	v_ashrrev_i32_e32 v100, 5, v87
	v_ashrrev_i32_e32 v103, 5, v89
	v_ashrrev_i32_e32 v105, 5, v91
	v_ashrrev_i32_e32 v106, 5, v92
	v_ashrrev_i32_e32 v107, 5, v95
	v_ashrrev_i32_e32 v124, 5, v96
	v_ashrrev_i32_e32 v125, 5, v99
	v_ashrrev_i32_e32 v126, 5, v0
	v_lshlrev_b32_e32 v0, 3, v0
	v_add3_u32 v127, 0, v66, v69
	v_lshlrev_b32_e32 v66, 3, v73
	v_lshlrev_b32_e32 v73, 3, v75
	v_lshlrev_b32_e32 v75, 3, v76
	v_lshlrev_b32_e32 v76, 3, v78
	v_lshlrev_b32_e32 v78, 3, v80
	v_lshlrev_b32_e32 v80, 3, v82
	v_lshlrev_b32_e32 v82, 3, v85
	v_lshlrev_b32_e32 v85, 3, v100
	v_lshlrev_b32_e32 v100, 3, v103
	v_lshlrev_b32_e32 v103, 3, v105
	v_lshlrev_b32_e32 v105, 3, v106
	v_lshlrev_b32_e32 v106, 3, v107
	v_lshlrev_b32_e32 v107, 3, v124
	v_lshlrev_b32_e32 v124, 3, v125
	v_lshlrev_b32_e32 v125, 3, v126
	v_lshlrev_b32_e32 v96, 3, v96
	v_add3_u32 v196, 0, v125, v0
	v_mul_f32_e32 v0, 0x38800000, v70
	v_lshlrev_b32_e32 v95, 3, v95
	v_add3_u32 v194, 0, v107, v96
	v_sin_f32_e32 v107, v0
	v_add3_u32 v193, 0, v106, v95
	v_cos_f32_e32 v106, v0
	v_lshlrev_b32_e32 v99, 3, v99
	v_add3_u32 v195, 0, v124, v99
	v_xor_b32_e32 v124, 0x80000000, v107
	v_mov_b32_e32 v125, v107
	v_pk_mul_f32 v[128:129], v[124:125], v[106:107] op_sel:[0,1] op_sel_hi:[1,0]
	v_lshlrev_b32_e32 v87, 3, v87
	v_pk_fma_f32 v[128:129], v[106:107], v[106:107], v[128:129] op_sel_hi:[1,0,1]
	v_add3_u32 v186, 0, v76, v69
	v_pk_mul_f32 v[132:133], v[124:125], v[128:129] op_sel:[0,1] op_sel_hi:[1,0]
	s_waitcnt vmcnt(21)
	v_sub_f32_e32 v70, v112, v120
	v_pk_fma_f32 v[132:133], v[128:129], v[106:107], v[132:133] op_sel_hi:[1,0,1]
	s_waitcnt vmcnt(20)
	v_sub_f32_e32 v76, v113, v121
	v_pk_mul_f32 v[136:137], v[124:125], v[132:133] op_sel:[0,1] op_sel_hi:[1,0]
	v_add3_u32 v171, 0, v66, v69
	v_pk_fma_f32 v[136:137], v[132:133], v[106:107], v[136:137] op_sel_hi:[1,0,1]
	v_add3_u32 v184, 0, v73, v69
	v_pk_mul_f32 v[140:141], v[124:125], v[136:137] op_sel:[0,1] op_sel_hi:[1,0]
	v_add3_u32 v190, 0, v85, v87
	v_pk_fma_f32 v[140:141], v[136:137], v[106:107], v[140:141] op_sel_hi:[1,0,1]
	v_sub_f32_e32 v66, v109, v119
	v_pk_mul_f32 v[144:145], v[124:125], v[140:141] op_sel:[0,1] op_sel_hi:[1,0]
	v_mul_f32_e32 v73, 0xbf3504f3, v70
	v_pk_fma_f32 v[144:145], v[140:141], v[106:107], v[144:145] op_sel_hi:[1,0,1]
	v_mul_f32_e32 v85, 0xbf6c835e, v76
	v_pk_mul_f32 v[148:149], v[124:125], v[144:145] op_sel:[0,1] op_sel_hi:[1,0]
	v_lshlrev_b32_e32 v91, 3, v91
	v_pk_fma_f32 v[148:149], v[144:145], v[106:107], v[148:149] op_sel_hi:[1,0,1]
	v_add3_u32 v185, 0, v75, v69
	v_pk_mul_f32 v[152:153], v[124:125], v[148:149] op_sel:[0,1] op_sel_hi:[1,0]
	v_add3_u32 v187, 0, v78, v69
	v_pk_fma_f32 v[152:153], v[148:149], v[106:107], v[152:153] op_sel_hi:[1,0,1]
	v_add3_u32 v188, 0, v80, v69
	v_pk_mul_f32 v[156:157], v[124:125], v[152:153] op_sel:[0,1] op_sel_hi:[1,0]
	v_add3_u32 v189, 0, v82, v69
	v_pk_fma_f32 v[156:157], v[152:153], v[106:107], v[156:157] op_sel_hi:[1,0,1]
	v_sub_f32_e32 v0, v108, v118
	v_pk_mul_f32 v[160:161], v[124:125], v[156:157] op_sel:[0,1] op_sel_hi:[1,0]
	v_pk_add_f32 v[108:109], v[108:109], v[118:119]
	v_pk_fma_f32 v[160:161], v[156:157], v[106:107], v[160:161] op_sel_hi:[1,0,1]
	v_mul_f32_e32 v69, 0xbec3ef15, v66
	v_pk_mul_f32 v[164:165], v[124:125], v[160:161] op_sel:[0,1] op_sel_hi:[1,0]
	v_pk_fma_f32 v[70:71], v[70:71], s[10:11], v[72:73] op_sel_hi:[1,0,1]
	v_pk_fma_f32 v[72:73], v[76:77], s[14:15], v[84:85] op_sel_hi:[1,0,1]
	s_waitcnt vmcnt(18)
	v_sub_f32_e32 v82, v115, v123
	v_pk_add_f32 v[76:77], v[114:115], v[122:123]
	v_mov_b32_e32 v83, v1
	v_mov_b32_e32 v90, v1
	s_movk_i32 s5, 0x200
	v_lshlrev_b32_e32 v89, 3, v89
	v_add3_u32 v192, 0, v103, v91
	v_pk_fma_f32 v[164:165], v[160:161], v[106:107], v[164:165] op_sel_hi:[1,0,1]
	v_pk_fma_f32 v[66:67], v[66:67], s[6:7], v[68:69] op_sel_hi:[1,0,1]
	v_pk_add_f32 v[68:69], v[112:113], v[120:121]
	v_mul_f32_e32 v91, 0xbf6c835e, v82
	s_waitcnt vmcnt(17)
	v_sub_f32_e32 v80, v116, v110
	v_pk_add_f32 v[112:113], v[108:109], v[76:77] neg_lo:[0,1] neg_hi:[0,1]
	v_mov_b32_e32 v81, v1
	v_mov_b32_e32 v88, v1
	v_mov_b32_e32 v101, v1
	v_mov_b32_e32 v102, v1
	v_add3_u32 v191, 0, v100, v89
	v_pk_mul_f32 v[168:169], v[124:125], v[164:165] op_sel:[0,1] op_sel_hi:[1,0]
	v_pk_fma_f32 v[82:83], v[82:83], s[4:5], v[90:91] op_sel_hi:[1,0,1]
	v_mul_f32_e32 v89, 0xbf3504f3, v80
	s_waitcnt vmcnt(16)
	v_sub_f32_e32 v78, v117, v111
	v_pk_add_f32 v[90:91], v[116:117], v[110:111]
	v_mov_b32_e32 v100, v113
	v_mul_f32_e32 v103, 0xbf3504f3, v113
	v_mov_b32_e32 v79, v1
	v_mov_b32_e32 v86, v1
	v_pk_fma_f32 v[168:169], v[164:165], v[106:107], v[168:169] op_sel_hi:[1,0,1]
	v_sub_f32_e32 v75, v114, v122
	v_pk_fma_f32 v[80:81], v[80:81], s[8:9], v[88:89] op_sel_hi:[1,0,1]
	v_mul_f32_e32 v87, 0xbec3ef15, v78
	v_pk_add_f32 v[88:89], v[66:67], v[82:83]
	v_pk_add_f32 v[66:67], v[66:67], v[82:83] neg_lo:[0,1] neg_hi:[0,1]
	v_pk_fma_f32 v[82:83], v[100:101], s[10:11], v[102:103] op_sel_hi:[1,0,1]
	v_pk_add_f32 v[100:101], v[68:69], v[90:91] neg_lo:[0,1] neg_hi:[0,1]
	v_mov_b32_e32 v74, v1
	v_mov_b32_e32 v97, v1
	v_mov_b32_e32 v98, v1
	v_pk_mul_f32 v[174:175], v[124:125], v[168:169] op_sel:[0,1] op_sel_hi:[1,0]
	v_xor_b32_e32 v75, 0x80000000, v75
	v_pk_add_f32 v[76:77], v[108:109], v[76:77]
	v_pk_add_f32 v[68:69], v[68:69], v[90:91]
	v_pk_fma_f32 v[78:79], v[78:79], s[12:13], v[86:87] op_sel_hi:[1,0,1]
	v_pk_add_f32 v[90:91], v[70:71], v[80:81]
	v_pk_add_f32 v[70:71], v[70:71], v[80:81] neg_lo:[0,1] neg_hi:[0,1]
	v_mov_b32_e32 v96, v101
	v_mul_f32_e32 v99, 0xbf3504f3, v101
	v_lshlrev_b32_e32 v92, 3, v92
	v_pk_fma_f32 v[174:175], v[168:169], v[106:107], v[174:175] op_sel_hi:[1,0,1]
	v_pk_add_f32 v[84:85], v[0:1], v[74:75]
	v_pk_add_f32 v[80:81], v[76:77], v[68:69] neg_lo:[0,1] neg_hi:[0,1]
	v_pk_add_f32 v[68:69], v[76:77], v[68:69]
	v_xor_b32_e32 v77, 0x80000000, v70
	v_mov_b32_e32 v76, v71
	v_pk_add_f32 v[70:71], v[72:73], v[78:79]
	v_pk_add_f32 v[72:73], v[72:73], v[78:79] neg_lo:[0,1] neg_hi:[0,1]
	v_pk_fma_f32 v[78:79], v[96:97], s[8:9], v[98:99] op_sel_hi:[1,0,1]
	v_mov_b32_e32 v94, v1
	v_add3_u32 v105, 0, v105, v92
	v_pk_mul_f32 v[178:179], v[124:125], v[174:175] op_sel:[0,1] op_sel_hi:[1,0]
	v_pk_add_f32 v[74:75], v[0:1], v[74:75] neg_lo:[0,1] neg_hi:[0,1]
	v_mov_b32_e32 v0, v112
	v_pk_mul_f32 v[86:87], v[66:67], s[16:17]
	v_xor_b32_e32 v95, 0x80000000, v100
	v_mov_b32_e32 v92, v80
	v_pk_add_f32 v[80:81], v[80:81], 0 neg_lo:[1,1] neg_hi:[1,1]
	v_pk_add_f32 v[96:97], v[84:85], v[90:91]
	v_pk_add_f32 v[84:85], v[84:85], v[90:91] neg_lo:[0,1] neg_hi:[0,1]
	v_pk_add_f32 v[90:91], v[68:69], v[68:69] op_sel:[0,1] op_sel_hi:[1,0]
	v_pk_mul_f32 v[98:99], v[72:73], s[16:17]
	v_pk_add_f32 v[100:101], v[82:83], v[78:79]
	v_pk_add_f32 v[78:79], v[82:83], v[78:79] neg_lo:[0,1] neg_hi:[0,1]
	v_pk_add_f32 v[82:83], v[88:89], v[70:71]
	v_pk_add_f32 v[70:71], v[88:89], v[70:71] neg_lo:[0,1] neg_hi:[0,1]
	v_mov_b32_e32 v93, v1
	v_mov_b32_e32 v126, v107
	v_pk_add_f32 v[130:131], v[128:129], 0 neg_lo:[1,1] neg_hi:[1,1]
	v_pk_add_f32 v[158:159], v[156:157], 0 neg_lo:[1,1] neg_hi:[1,1]
	v_pk_fma_f32 v[178:179], v[174:175], v[106:107], v[178:179] op_sel_hi:[1,0,1]
	v_pk_fma_f32 v[66:67], v[66:67], s[10:11], v[86:87] op_sel:[0,0,1] op_sel_hi:[1,0,0]
	v_pk_add_f32 v[86:87], v[0:1], v[94:95]
	v_pk_add_f32 v[94:95], v[0:1], v[94:95] neg_lo:[0,1] neg_hi:[0,1]
	v_mov_b32_e32 v80, v1
	v_pk_add_f32 v[88:89], v[74:75], v[76:77]
	v_pk_add_f32 v[74:75], v[74:75], v[76:77] neg_lo:[0,1] neg_hi:[0,1]
	v_mov_b32_e32 v91, v1
	v_pk_fma_f32 v[72:73], v[72:73], s[8:9], v[98:99] op_sel:[0,0,1] op_sel_hi:[1,0,0]
	v_xor_b32_e32 v77, 0x80000000, v78
	v_mov_b32_e32 v76, v79
	v_xor_b32_e32 v79, 0x80000000, v70
	v_mov_b32_e32 v78, v71
	v_pk_add_f32 v[98:99], v[96:97], v[82:83]
	v_mov_b32_e32 v130, v129
	v_pk_add_f32 v[134:135], v[132:133], 0 neg_lo:[1,1] neg_hi:[1,1]
	v_pk_add_f32 v[142:143], v[140:141], 0 neg_lo:[1,1] neg_hi:[1,1]
	v_mov_b32_e32 v158, v157
	v_pk_mul_f32 v[124:125], v[124:125], v[178:179] op_sel:[0,1] op_sel_hi:[1,0]
	v_pk_add_f32 v[70:71], v[92:93], v[80:81]
	v_pk_add_f32 v[80:81], v[92:93], v[80:81] neg_lo:[0,1] neg_hi:[0,1]
	v_pk_add_f32 v[92:93], v[86:87], v[100:101]
	v_pk_add_f32 v[82:83], v[96:97], v[82:83] neg_lo:[0,1] neg_hi:[0,1]
	ds_write_b64 v127, v[90:91]
	v_pk_add_f32 v[90:91], v[66:67], v[72:73]
	v_pk_add_f32 v[112:113], v[66:67], v[72:73] op_sel:[1,1] op_sel_hi:[0,0] neg_lo:[0,1] neg_hi:[1,0]
	v_pk_add_f32 v[72:73], v[94:95], v[76:77]
	v_pk_add_f32 v[76:77], v[94:95], v[76:77] neg_lo:[0,1] neg_hi:[0,1]
	v_pk_add_f32 v[94:95], v[84:85], v[78:79]
	v_pk_add_f32 v[78:79], v[84:85], v[78:79] neg_lo:[0,1] neg_hi:[0,1]
	v_pk_mul_f32 v[84:85], v[126:127], v[98:99] op_sel:[0,1] op_sel_hi:[0,0] neg_hi:[1,0]
	v_mov_b32_e32 v134, v133
	v_pk_add_f32 v[138:139], v[136:137], 0 neg_lo:[1,1] neg_hi:[1,1]
	v_mov_b32_e32 v142, v141
	v_pk_add_f32 v[146:147], v[144:145], 0 neg_lo:[1,1] neg_hi:[1,1]
	v_pk_add_f32 v[150:151], v[148:149], 0 neg_lo:[1,1] neg_hi:[1,1]
	v_pk_add_f32 v[166:167], v[164:165], 0 neg_lo:[1,1] neg_hi:[1,1]
	v_pk_fma_f32 v[124:125], v[178:179], v[106:107], v[124:125] op_sel_hi:[1,0,1]
	v_pk_mul_f32 v[96:97], v[92:93], v[130:131] op_sel:[1,0] op_sel_hi:[0,1]
	v_pk_mul_f32 v[102:103], v[82:83], v[158:159] op_sel:[1,0] op_sel_hi:[0,1]
	v_pk_add_f32 v[66:67], v[88:89], v[90:91]
	v_pk_fma_f32 v[84:85], v[98:99], v[106:107], v[84:85] op_sel_hi:[1,0,1]
	v_mov_b32_e32 v138, v137
	v_mov_b32_e32 v146, v145
	v_mov_b32_e32 v150, v149
	v_pk_add_f32 v[154:155], v[152:153], 0 neg_lo:[1,1] neg_hi:[1,1]
	v_pk_add_f32 v[162:163], v[160:161], 0 neg_lo:[1,1] neg_hi:[1,1]
	v_mov_b32_e32 v166, v165
	v_pk_add_f32 v[172:173], v[168:169], 0 neg_lo:[1,1] neg_hi:[1,1]
	v_pk_add_f32 v[176:177], v[174:175], 0 neg_lo:[1,1] neg_hi:[1,1]
	v_pk_add_f32 v[180:181], v[178:179], 0 neg_lo:[1,1] neg_hi:[1,1]
	v_pk_add_f32 v[182:183], v[124:125], 0 neg_lo:[1,1] neg_hi:[1,1]
	v_pk_add_f32 v[68:69], v[68:69], v[68:69] op_sel:[0,1] op_sel_hi:[1,0] neg_lo:[0,1] neg_hi:[0,1]
	v_pk_add_f32 v[88:89], v[88:89], v[90:91] neg_lo:[0,1] neg_hi:[0,1]
	v_pk_fma_f32 v[90:91], v[92:93], v[128:129], v[96:97] op_sel_hi:[1,0,1]
	v_pk_mul_f32 v[92:93], v[94:95], v[142:143] op_sel:[1,0] op_sel_hi:[0,1]
	v_pk_fma_f32 v[82:83], v[82:83], v[156:157], v[102:103] op_sel_hi:[1,0,1]
	v_pk_add_f32 v[102:103], v[74:75], v[112:113]
	ds_write_b64 v171, v[84:85] offset:8192
	ds_write_b64 v184, v[90:91] offset:16384
	v_pk_mul_f32 v[84:85], v[66:67], v[134:135] op_sel:[1,0] op_sel_hi:[0,1]
	v_mov_b32_e32 v154, v153
	v_mov_b32_e32 v162, v161
	v_mov_b32_e32 v172, v169
	v_mov_b32_e32 v176, v175
	v_mov_b32_e32 v180, v179
	v_mov_b32_e32 v182, v125
	v_mov_b32_e32 v0, v68
	v_pk_mov_b32 v[68:69], s[2:3], v[68:69] op_sel:[1,0]
	v_pk_add_f32 v[86:87], v[86:87], v[100:101] neg_lo:[0,1] neg_hi:[0,1]
	v_pk_mul_f32 v[100:101], v[70:71], v[138:139] op_sel:[1,0] op_sel_hi:[0,1]
	v_pk_mul_f32 v[96:97], v[72:73], v[146:147] op_sel:[1,0] op_sel_hi:[0,1]
	v_pk_add_f32 v[74:75], v[74:75], v[112:113] neg_lo:[0,1] neg_hi:[0,1]
	v_pk_fma_f32 v[90:91], v[94:95], v[140:141], v[92:93] op_sel_hi:[1,0,1]
	v_pk_mul_f32 v[92:93], v[88:89], v[166:167] op_sel:[1,0] op_sel_hi:[0,1]
	v_pk_fma_f32 v[66:67], v[66:67], v[132:133], v[84:85] op_sel_hi:[1,0,1]
	v_pk_mul_f32 v[84:85], v[102:103], v[150:151] op_sel:[1,0] op_sel_hi:[0,1]
	s_mov_b64 s[46:47], 0
	s_and_b64 vcc, exec, s[0:1]
	v_pk_mul_f32 v[68:69], v[68:69], v[154:155]
	v_pk_mul_f32 v[108:109], v[86:87], v[162:163] op_sel:[1,0] op_sel_hi:[0,1]
	v_pk_mul_f32 v[110:111], v[80:81], v[172:173] op_sel:[1,0] op_sel_hi:[0,1]
	v_pk_fma_f32 v[70:71], v[70:71], v[136:137], v[100:101] op_sel_hi:[1,0,1]
	v_pk_mul_f32 v[98:99], v[78:79], v[176:177] op_sel:[1,0] op_sel_hi:[0,1]
	v_pk_mul_f32 v[100:101], v[76:77], v[180:181] op_sel:[1,0] op_sel_hi:[0,1]
	v_pk_fma_f32 v[72:73], v[72:73], v[144:145], v[96:97] op_sel_hi:[1,0,1]
	v_pk_fma_f32 v[88:89], v[88:89], v[164:165], v[92:93] op_sel_hi:[1,0,1]
	v_pk_mul_f32 v[92:93], v[74:75], v[182:183] op_sel:[1,0] op_sel_hi:[0,1]
	ds_write_b64 v185, v[66:67] offset:24576
	ds_write_b64 v186, v[70:71] offset:32768
	ds_write_b64 v187, v[90:91] offset:40960
	ds_write_b64 v188, v[72:73] offset:49152
	v_pk_fma_f32 v[66:67], v[102:103], v[148:149], v[84:85] op_sel_hi:[1,0,1]
	v_pk_fma_f32 v[68:69], v[0:1], v[152:153], v[68:69] op_sel_hi:[1,0,1]
	v_pk_fma_f32 v[86:87], v[86:87], v[160:161], v[108:109] op_sel_hi:[1,0,1]
	v_pk_fma_f32 v[80:81], v[80:81], v[168:169], v[110:111] op_sel_hi:[1,0,1]
	v_pk_fma_f32 v[78:79], v[78:79], v[174:175], v[98:99] op_sel_hi:[1,0,1]
	v_pk_fma_f32 v[76:77], v[76:77], v[178:179], v[100:101] op_sel_hi:[1,0,1]
	v_pk_fma_f32 v[70:71], v[74:75], v[124:125], v[92:93] op_sel_hi:[1,0,1]
	ds_write_b64 v189, v[66:67] offset:57344
	ds_write_b64 v190, v[68:69]
	ds_write_b64 v191, v[82:83]
	ds_write_b64 v192, v[86:87]
	ds_write_b64 v105, v[88:89]
	ds_write_b64 v193, v[80:81]
	ds_write_b64 v194, v[78:79]
	ds_write_b64 v195, v[76:77]
	ds_write_b64 v196, v[70:71]
	s_cbranch_vccz .LBB0_359
	s_waitcnt lgkmcnt(0)
	s_barrier
	v_mov_b32 v0, 0
	s_mov_b32 s5, s14
	v_add_u32_e32 v74, v0, v170
	v_lshlrev_b32_e32 v0, 5, v74
	v_and_b32_e32 v71, 0xfffffc00, v0
	v_or_b32_e32 v75, 0x80, v71
	v_and_b32_e32 v70, 31, v74
	v_ashrrev_i32_e32 v75, 2, v75
	v_lshlrev_b32_e32 v78, 3, v71
	v_lshlrev_b32_e32 v79, 3, v70
	v_add_u32_e32 v75, 0, v75
	v_add3_u32 v111, v75, v78, v79
	v_or_b32_e32 v75, 0xa0, v71
	v_ashrrev_i32_e32 v75, 2, v75
	v_add_u32_e32 v75, 0, v75
	v_add3_u32 v110, v75, v78, v79
	v_or_b32_e32 v75, 0xc0, v71
	v_ashrrev_i32_e32 v75, 2, v75
	v_add_u32_e32 v75, 0, v75
	v_add3_u32 v109, v75, v78, v79
	v_or_b32_e32 v75, 0xe0, v71
	v_ashrrev_i32_e32 v75, 2, v75
	v_add_u32_e32 v75, 0, v75
	v_add3_u32 v108, v75, v78, v79
	v_or_b32_e32 v75, 0x100, v71
	v_ashrrev_i32_e32 v75, 2, v75
	v_add_u32_e32 v75, 0, v75
	v_add3_u32 v107, v75, v78, v79
	v_or_b32_e32 v75, 0x120, v71
	v_ashrrev_i32_e32 v75, 2, v75
	v_add_u32_e32 v75, 0, v75
	v_add3_u32 v106, v75, v78, v79
	v_or_b32_e32 v75, 0x140, v71
	v_ashrrev_i32_e32 v75, 2, v75
	v_add_u32_e32 v75, 0, v75
	v_add3_u32 v105, v75, v78, v79
	v_or_b32_e32 v75, 0x160, v71
	v_ashrrev_i32_e32 v75, 2, v75
	v_add_u32_e32 v75, 0, v75
	v_add3_u32 v103, v75, v78, v79
	v_or_b32_e32 v75, 0x180, v71
	v_ashrrev_i32_e32 v75, 2, v75
	v_add_u32_e32 v75, 0, v75
	v_add3_u32 v102, v75, v78, v79
	v_or_b32_e32 v75, 0x1a0, v71
	v_ashrrev_i32_e32 v75, 2, v75
	v_add_u32_e32 v75, 0, v75
	v_add3_u32 v101, v75, v78, v79
	v_or_b32_e32 v75, 0x1c0, v71
	v_ashrrev_i32_e32 v75, 2, v75
	v_add_u32_e32 v75, 0, v75
	v_add3_u32 v100, v75, v78, v79
	v_or_b32_e32 v75, 0x1e0, v71
	v_ashrrev_i32_e32 v75, 2, v75
	v_add_u32_e32 v75, 0, v75
	v_add3_u32 v99, v75, v78, v79
	v_or_b32_e32 v75, 0x200, v71
	v_ashrrev_i32_e32 v75, 2, v75
	v_add_u32_e32 v75, 0, v75
	v_add3_u32 v98, v75, v78, v79
	v_or_b32_e32 v75, 0x220, v71
	v_ashrrev_i32_e32 v75, 2, v75
	v_add_u32_e32 v75, 0, v75
	v_add3_u32 v97, v75, v78, v79
	v_or_b32_e32 v75, 0x240, v71
	v_ashrrev_i32_e32 v75, 2, v75
	v_add_u32_e32 v75, 0, v75
	v_add3_u32 v96, v75, v78, v79
	v_or_b32_e32 v75, 0x260, v71
	v_ashrrev_i32_e32 v75, 2, v75
	v_add_u32_e32 v75, 0, v75
	v_add3_u32 v95, v75, v78, v79
	v_or_b32_e32 v75, 0x280, v71
	v_or_b32_e32 v67, 32, v71
	v_ashrrev_i32_e32 v75, 2, v75
	v_ashrrev_i32_e32 v67, 2, v67
	v_add_u32_e32 v75, 0, v75
	v_add_u32_e32 v67, 0, v67
	v_add3_u32 v94, v75, v78, v79
	v_or_b32_e32 v75, 0x2a0, v71
	v_add3_u32 v114, v67, v78, v79
	v_or_b32_e32 v67, 64, v71
	v_ashrrev_i32_e32 v75, 2, v75
	v_ashrrev_i32_e32 v67, 2, v67
	v_add_u32_e32 v75, 0, v75
	v_add_u32_e32 v67, 0, v67
	v_add3_u32 v93, v75, v78, v79
	v_or_b32_e32 v75, 0x2c0, v71
	v_ashrrev_i32_e32 v66, 2, v71
	v_add3_u32 v113, v67, v78, v79
	v_or_b32_e32 v67, 0x60, v71
	v_ashrrev_i32_e32 v75, 2, v75
	v_add_u32_e32 v66, 0, v66
	v_ashrrev_i32_e32 v67, 2, v67
	v_add_u32_e32 v75, 0, v75
	v_add3_u32 v66, v66, v78, v79
	v_add_u32_e32 v67, 0, v67
	v_add3_u32 v92, v75, v78, v79
	v_or_b32_e32 v75, 0x2e0, v71
	v_add3_u32 v112, v67, v78, v79
	ds_read_b64 v[66:67], v66
	ds_read_b64 v[68:69], v114 offset:256
	ds_read_b64 v[72:73], v113 offset:512
	ds_read_b64 v[76:77], v112 offset:768
	ds_read_b64 v[80:81], v111 offset:1024
	ds_read_b64 v[82:83], v110 offset:1280
	ds_read_b64 v[116:117], v109 offset:1536
	ds_read_b64 v[118:119], v108 offset:1792
	ds_read_b64 v[120:121], v107 offset:2048
	ds_read_b64 v[122:123], v106 offset:2304
	ds_read_b64 v[124:125], v105 offset:2560
	ds_read_b64 v[126:127], v103 offset:2816
	ds_read_b64 v[128:129], v102 offset:3072
	ds_read_b64 v[130:131], v101 offset:3328
	ds_read_b64 v[132:133], v100 offset:3584
	ds_read_b64 v[134:135], v99 offset:3840
	ds_read_b64 v[136:137], v98 offset:4096
	ds_read_b64 v[138:139], v97 offset:4352
	ds_read_b64 v[140:141], v96 offset:4608
	ds_read_b64 v[142:143], v95 offset:4864
	v_ashrrev_i32_e32 v75, 2, v75
	v_add_u32_e32 v75, 0, v75
	v_add3_u32 v91, v75, v78, v79
	v_or_b32_e32 v75, 0x300, v71
	v_ashrrev_i32_e32 v75, 2, v75
	s_waitcnt lgkmcnt(3)
	v_pk_add_f32 v[168:169], v[66:67], v[136:137]
	v_pk_add_f32 v[66:67], v[66:67], v[136:137] neg_lo:[0,1] neg_hi:[0,1]
	s_waitcnt lgkmcnt(2)
	v_pk_add_f32 v[136:137], v[68:69], v[138:139]
	v_pk_add_f32 v[68:69], v[68:69], v[138:139] neg_lo:[0,1] neg_hi:[0,1]
	v_add_u32_e32 v75, 0, v75
	v_pk_mul_f32 v[138:139], v[68:69], s[18:19]
	v_add3_u32 v90, v75, v78, v79
	v_or_b32_e32 v75, 0x320, v71
	v_pk_fma_f32 v[68:69], v[68:69], s[20:21], v[138:139] op_sel:[0,0,1] op_sel_hi:[1,0,0]
	s_waitcnt lgkmcnt(1)
	v_pk_add_f32 v[138:139], v[72:73], v[140:141]
	v_pk_add_f32 v[72:73], v[72:73], v[140:141] neg_lo:[0,1] neg_hi:[0,1]
	v_ashrrev_i32_e32 v75, 2, v75
	v_pk_mul_f32 v[140:141], v[72:73], s[4:5]
	ds_read_b64 v[144:145], v94 offset:5120
	ds_read_b64 v[146:147], v93 offset:5376
	ds_read_b64 v[148:149], v92 offset:5632
	ds_read_b64 v[150:151], v91 offset:5888
	v_add_u32_e32 v75, 0, v75
	v_pk_fma_f32 v[72:73], v[72:73], s[6:7], v[140:141] op_sel:[0,0,1] op_sel_hi:[1,0,0]
	s_waitcnt lgkmcnt(4)
	v_pk_add_f32 v[140:141], v[76:77], v[142:143]
	v_pk_add_f32 v[76:77], v[76:77], v[142:143] neg_lo:[0,1] neg_hi:[0,1]
	v_add3_u32 v89, v75, v78, v79
	v_or_b32_e32 v75, 0x340, v71
	v_pk_mul_f32 v[142:143], v[76:77], s[22:23]
	v_ashrrev_i32_e32 v75, 2, v75
	v_pk_fma_f32 v[76:77], v[76:77], s[24:25], v[142:143] op_sel:[0,0,1] op_sel_hi:[1,0,0]
	s_waitcnt lgkmcnt(3)
	v_pk_add_f32 v[142:143], v[80:81], v[144:145]
	v_pk_add_f32 v[80:81], v[80:81], v[144:145] neg_lo:[0,1] neg_hi:[0,1]
	s_mov_b32 s9, s10
	v_add_u32_e32 v75, 0, v75
	v_pk_mul_f32 v[144:145], v[80:81], s[8:9]
	v_add3_u32 v88, v75, v78, v79
	v_or_b32_e32 v75, 0x360, v71
	v_pk_fma_f32 v[80:81], v[80:81], s[10:11], v[144:145] op_sel:[0,0,1] op_sel_hi:[1,0,0]
	s_waitcnt lgkmcnt(2)
	v_pk_add_f32 v[144:145], v[82:83], v[146:147]
	v_pk_add_f32 v[82:83], v[82:83], v[146:147] neg_lo:[0,1] neg_hi:[0,1]
	s_mov_b32 s27, s24
	v_ashrrev_i32_e32 v75, 2, v75
	v_pk_mul_f32 v[146:147], v[82:83], s[26:27]
	s_mov_b32 s0, s23
	v_add_u32_e32 v75, 0, v75
	v_pk_fma_f32 v[82:83], v[82:83], s[0:1], v[146:147] op_sel:[0,0,1] op_sel_hi:[1,0,0]
	s_waitcnt lgkmcnt(1)
	v_pk_add_f32 v[146:147], v[116:117], v[148:149]
	v_pk_add_f32 v[116:117], v[116:117], v[148:149] neg_lo:[0,1] neg_hi:[0,1]
	s_mov_b32 s13, s6
	v_add3_u32 v87, v75, v78, v79
	v_or_b32_e32 v75, 0x380, v71
	v_pk_mul_f32 v[148:149], v[116:117], s[12:13]
	ds_read_b64 v[152:153], v90 offset:6144
	ds_read_b64 v[154:155], v89 offset:6400
	ds_read_b64 v[156:157], v88 offset:6656
	ds_read_b64 v[158:159], v87 offset:6912
	v_ashrrev_i32_e32 v75, 2, v75
	v_pk_fma_f32 v[116:117], v[116:117], s[14:15], v[148:149] op_sel:[0,0,1] op_sel_hi:[1,0,0]
	s_waitcnt lgkmcnt(4)
	v_pk_add_f32 v[148:149], v[118:119], v[150:151]
	v_pk_add_f32 v[118:119], v[118:119], v[150:151] neg_lo:[0,1] neg_hi:[0,1]
	s_mov_b32 s35, s20
	v_add_u32_e32 v75, 0, v75
	v_pk_mul_f32 v[150:151], v[118:119], s[34:35]
	s_mov_b32 s44, s19
	v_add3_u32 v86, v75, v78, v79
	v_or_b32_e32 v75, 0x3a0, v71
	v_or_b32_e32 v71, 0x3c0, v71
	v_pk_fma_f32 v[118:119], v[118:119], s[44:45], v[150:151] op_sel:[0,0,1] op_sel_hi:[1,0,0]
	s_waitcnt lgkmcnt(3)
	v_pk_add_f32 v[150:151], v[120:121], v[152:153]
	v_pk_add_f32 v[152:153], v[120:121], v[152:153] op_sel:[1,1] op_sel_hi:[0,0] neg_lo:[0,1] neg_hi:[1,0]
	v_ashrrev_i32_e32 v71, 2, v71
	s_waitcnt lgkmcnt(2)
	v_pk_add_f32 v[120:121], v[122:123], v[154:155]
	v_pk_add_f32 v[122:123], v[122:123], v[154:155] neg_lo:[0,1] neg_hi:[0,1]
	v_add_u32_e32 v71, 0, v71
	v_or_b32_e32 v0, 0x3e0, v0
	v_pk_mul_f32 v[154:155], v[122:123], s[34:35]
	v_ashrrev_i32_e32 v75, 2, v75
	v_add3_u32 v84, v71, v78, v79
	v_ashrrev_i32_e32 v71, 2, v0
	v_pk_fma_f32 v[122:123], v[122:123], s[18:19], v[154:155] op_sel:[0,0,1] op_sel_hi:[1,0,0]
	s_waitcnt lgkmcnt(1)
	v_pk_add_f32 v[154:155], v[124:125], v[156:157]
	v_pk_add_f32 v[124:125], v[124:125], v[156:157] neg_lo:[0,1] neg_hi:[0,1]
	v_add_u32_e32 v75, 0, v75
	v_add_u32_e32 v71, 0, v71
	v_lshlrev_b32_e32 v0, 3, v0
	v_pk_mul_f32 v[156:157], v[124:125], s[12:13]
	v_add3_u32 v85, v75, v78, v79
	v_add3_u32 v0, v71, v0, v79
	ds_read_b64 v[160:161], v86 offset:7168
	ds_read_b64 v[162:163], v85 offset:7424
	ds_read_b64 v[164:165], v84 offset:7680
	ds_read_b64 v[166:167], v0
	v_pk_fma_f32 v[124:125], v[124:125], s[4:5], v[156:157] op_sel:[0,0,1] op_sel_hi:[1,0,0]
	s_waitcnt lgkmcnt(4)
	v_pk_add_f32 v[156:157], v[126:127], v[158:159]
	v_pk_add_f32 v[126:127], v[126:127], v[158:159] neg_lo:[0,1] neg_hi:[0,1]
	v_lshlrev_b32_e32 v70, 4, v70
	v_pk_mul_f32 v[158:159], v[126:127], s[26:27]
	v_cvt_f32_u32_e32 v75, v70
	v_pk_fma_f32 v[126:127], v[126:127], s[22:23], v[158:159] op_sel:[0,0,1] op_sel_hi:[1,0,0]
	s_waitcnt lgkmcnt(3)
	v_pk_add_f32 v[158:159], v[128:129], v[160:161]
	v_pk_add_f32 v[128:129], v[128:129], v[160:161] neg_lo:[0,1] neg_hi:[0,1]
	v_and_b32_e32 v74, 0x1fffffe0, v74
	v_pk_mul_f32 v[160:161], v[128:129], s[8:9]
	v_mul_f32_e32 v115, 0x38800000, v75
	v_pk_fma_f32 v[128:129], v[128:129], s[8:9], v[160:161] op_sel:[0,0,1] op_sel_hi:[1,0,0]
	s_waitcnt lgkmcnt(2)
	v_pk_add_f32 v[160:161], v[130:131], v[162:163]
	v_pk_add_f32 v[130:131], v[130:131], v[162:163] neg_lo:[0,1] neg_hi:[0,1]
	v_lshl_add_u32 v74, v74, 3, 0
	v_pk_mul_f32 v[162:163], v[130:131], s[22:23]
	v_sin_f32_e32 v75, v115
	v_pk_fma_f32 v[130:131], v[130:131], s[26:27], v[162:163] op_sel:[0,0,1] op_sel_hi:[1,0,0]
	s_waitcnt lgkmcnt(1)
	v_pk_add_f32 v[162:163], v[132:133], v[164:165]
	v_pk_add_f32 v[132:133], v[132:133], v[164:165] neg_lo:[0,1] neg_hi:[0,1]
	v_add3_u32 v74, v74, v78, v79
	v_pk_mul_f32 v[164:165], v[132:133], s[4:5]
	v_xor_b32_e32 v78, 0x80000000, v75
	v_pk_fma_f32 v[132:133], v[132:133], s[12:13], v[164:165] op_sel:[0,0,1] op_sel_hi:[1,0,0]
	s_waitcnt lgkmcnt(0)
	v_pk_add_f32 v[164:165], v[134:135], v[166:167]
	v_pk_add_f32 v[134:135], v[134:135], v[166:167] neg_lo:[0,1] neg_hi:[0,1]
	v_mov_b32_e32 v79, v75
	v_pk_mul_f32 v[166:167], v[134:135], s[18:19]
	s_add_u32 s41, s56, s42
	v_pk_fma_f32 v[134:135], v[134:135], s[34:35], v[166:167] op_sel:[0,0,1] op_sel_hi:[1,0,0]
	v_pk_add_f32 v[166:167], v[168:169], v[150:151]
	v_pk_add_f32 v[150:151], v[168:169], v[150:151] neg_lo:[0,1] neg_hi:[0,1]
	v_pk_add_f32 v[168:169], v[136:137], v[120:121]
	v_pk_add_f32 v[120:121], v[136:137], v[120:121] neg_lo:[0,1] neg_hi:[0,1]
	s_addc_u32 s61, s57, s43
	v_pk_mul_f32 v[136:137], v[120:121], s[4:5]
	s_nop 0
	v_pk_fma_f32 v[120:121], v[120:121], s[6:7], v[136:137] op_sel:[0,0,1] op_sel_hi:[1,0,0]
	v_pk_add_f32 v[136:137], v[138:139], v[154:155]
	v_pk_add_f32 v[138:139], v[138:139], v[154:155] neg_lo:[0,1] neg_hi:[0,1]
	s_nop 0
	v_pk_mul_f32 v[154:155], v[138:139], s[8:9]
	s_nop 0
	v_pk_fma_f32 v[138:139], v[138:139], s[10:11], v[154:155] op_sel:[0,0,1] op_sel_hi:[1,0,0]
	v_pk_add_f32 v[154:155], v[140:141], v[156:157]
	v_pk_add_f32 v[140:141], v[140:141], v[156:157] neg_lo:[0,1] neg_hi:[0,1]
	s_nop 0
	v_pk_mul_f32 v[156:157], v[140:141], s[12:13]
	s_nop 0
	v_pk_fma_f32 v[140:141], v[140:141], s[14:15], v[156:157] op_sel:[0,0,1] op_sel_hi:[1,0,0]
	v_pk_add_f32 v[156:157], v[142:143], v[158:159]
	v_pk_add_f32 v[158:159], v[142:143], v[158:159] op_sel:[1,1] op_sel_hi:[0,0] neg_lo:[0,1] neg_hi:[1,0]
	s_nop 0
	v_pk_add_f32 v[142:143], v[144:145], v[160:161]
	v_pk_add_f32 v[144:145], v[144:145], v[160:161] neg_lo:[0,1] neg_hi:[0,1]
	s_nop 0
	v_pk_mul_f32 v[160:161], v[144:145], s[12:13]
	s_nop 0
	v_pk_fma_f32 v[144:145], v[144:145], s[4:5], v[160:161] op_sel:[0,0,1] op_sel_hi:[1,0,0]
	v_pk_add_f32 v[160:161], v[146:147], v[162:163]
	v_pk_add_f32 v[146:147], v[146:147], v[162:163] neg_lo:[0,1] neg_hi:[0,1]
	s_nop 0
	v_pk_mul_f32 v[162:163], v[146:147], s[8:9]
	s_nop 0
	v_pk_fma_f32 v[146:147], v[146:147], s[8:9], v[162:163] op_sel:[0,0,1] op_sel_hi:[1,0,0]
	v_pk_add_f32 v[162:163], v[148:149], v[164:165]
	v_pk_add_f32 v[148:149], v[148:149], v[164:165] neg_lo:[0,1] neg_hi:[0,1]
	s_nop 0
	v_pk_mul_f32 v[164:165], v[148:149], s[4:5]
	s_nop 0
	v_pk_fma_f32 v[148:149], v[148:149], s[12:13], v[164:165] op_sel:[0,0,1] op_sel_hi:[1,0,0]
	v_pk_add_f32 v[164:165], v[66:67], v[152:153]
	v_pk_add_f32 v[66:67], v[66:67], v[152:153] neg_lo:[0,1] neg_hi:[0,1]
	v_pk_add_f32 v[152:153], v[68:69], v[122:123]
	v_pk_add_f32 v[68:69], v[68:69], v[122:123] neg_lo:[0,1] neg_hi:[0,1]
	s_nop 0
	v_pk_mul_f32 v[122:123], v[68:69], s[4:5]
	s_nop 0
	v_pk_fma_f32 v[68:69], v[68:69], s[6:7], v[122:123] op_sel:[0,0,1] op_sel_hi:[1,0,0]
	v_pk_add_f32 v[122:123], v[72:73], v[124:125]
	v_pk_add_f32 v[72:73], v[72:73], v[124:125] neg_lo:[0,1] neg_hi:[0,1]
	s_nop 0
	v_pk_mul_f32 v[124:125], v[72:73], s[8:9]
	s_nop 0
	v_pk_fma_f32 v[72:73], v[72:73], s[10:11], v[124:125] op_sel:[0,0,1] op_sel_hi:[1,0,0]
	v_pk_add_f32 v[124:125], v[76:77], v[126:127]
	v_pk_add_f32 v[76:77], v[76:77], v[126:127] neg_lo:[0,1] neg_hi:[0,1]
	s_nop 0
	v_pk_mul_f32 v[126:127], v[76:77], s[12:13]
	s_nop 0
	v_pk_fma_f32 v[76:77], v[76:77], s[14:15], v[126:127] op_sel:[0,0,1] op_sel_hi:[1,0,0]
	v_pk_add_f32 v[126:127], v[80:81], v[128:129]
	v_pk_add_f32 v[128:129], v[80:81], v[128:129] op_sel:[1,1] op_sel_hi:[0,0] neg_lo:[0,1] neg_hi:[1,0]
	s_nop 0
	v_pk_add_f32 v[80:81], v[82:83], v[130:131]
	v_pk_add_f32 v[82:83], v[82:83], v[130:131] neg_lo:[0,1] neg_hi:[0,1]
	s_nop 0
	v_pk_mul_f32 v[130:131], v[82:83], s[12:13]
	s_nop 0
	v_pk_fma_f32 v[82:83], v[82:83], s[4:5], v[130:131] op_sel:[0,0,1] op_sel_hi:[1,0,0]
	v_pk_add_f32 v[130:131], v[116:117], v[132:133]
	v_pk_add_f32 v[116:117], v[116:117], v[132:133] neg_lo:[0,1] neg_hi:[0,1]
	s_nop 0
	v_pk_mul_f32 v[132:133], v[116:117], s[8:9]
	s_nop 0
	v_pk_fma_f32 v[116:117], v[116:117], s[8:9], v[132:133] op_sel:[0,0,1] op_sel_hi:[1,0,0]
	v_pk_add_f32 v[132:133], v[118:119], v[134:135]
	v_pk_add_f32 v[118:119], v[118:119], v[134:135] neg_lo:[0,1] neg_hi:[0,1]
	s_nop 0
	v_pk_mul_f32 v[134:135], v[118:119], s[4:5]
	s_nop 0
	v_pk_fma_f32 v[118:119], v[118:119], s[12:13], v[134:135] op_sel:[0,0,1] op_sel_hi:[1,0,0]
	v_pk_add_f32 v[134:135], v[166:167], v[156:157]
	v_pk_add_f32 v[156:157], v[166:167], v[156:157] neg_lo:[0,1] neg_hi:[0,1]
	v_pk_add_f32 v[166:167], v[168:169], v[142:143]
	v_pk_add_f32 v[142:143], v[168:169], v[142:143] neg_lo:[0,1] neg_hi:[0,1]
	s_nop 0
	v_pk_mul_f32 v[168:169], v[142:143], s[8:9]
	s_nop 0
	v_pk_fma_f32 v[142:143], v[142:143], s[10:11], v[168:169] op_sel:[0,0,1] op_sel_hi:[1,0,0]
	v_pk_add_f32 v[168:169], v[136:137], v[160:161]
	v_pk_add_f32 v[160:161], v[136:137], v[160:161] op_sel:[1,1] op_sel_hi:[0,0] neg_lo:[0,1] neg_hi:[1,0]
	s_nop 0
	v_pk_add_f32 v[136:137], v[154:155], v[162:163]
	v_pk_add_f32 v[154:155], v[154:155], v[162:163] neg_lo:[0,1] neg_hi:[0,1]
	s_nop 0
	v_pk_mul_f32 v[162:163], v[154:155], s[8:9]
	s_nop 0
	v_pk_fma_f32 v[154:155], v[154:155], s[8:9], v[162:163] op_sel:[0,0,1] op_sel_hi:[1,0,0]
	v_pk_add_f32 v[162:163], v[150:151], v[158:159]
	v_pk_add_f32 v[150:151], v[150:151], v[158:159] neg_lo:[0,1] neg_hi:[0,1]
	v_pk_add_f32 v[158:159], v[120:121], v[144:145]
	v_pk_add_f32 v[120:121], v[120:121], v[144:145] neg_lo:[0,1] neg_hi:[0,1]
	s_nop 0
	v_pk_mul_f32 v[144:145], v[120:121], s[8:9]
	s_nop 0
	v_pk_fma_f32 v[120:121], v[120:121], s[10:11], v[144:145] op_sel:[0,0,1] op_sel_hi:[1,0,0]
	v_pk_add_f32 v[144:145], v[138:139], v[146:147]
	v_pk_add_f32 v[146:147], v[138:139], v[146:147] op_sel:[1,1] op_sel_hi:[0,0] neg_lo:[0,1] neg_hi:[1,0]
	s_nop 0
	v_pk_add_f32 v[138:139], v[140:141], v[148:149]
	v_pk_add_f32 v[140:141], v[140:141], v[148:149] neg_lo:[0,1] neg_hi:[0,1]
	s_nop 0
	v_pk_mul_f32 v[148:149], v[140:141], s[8:9]
	s_nop 0
	v_pk_fma_f32 v[140:141], v[140:141], s[8:9], v[148:149] op_sel:[0,0,1] op_sel_hi:[1,0,0]
	v_pk_add_f32 v[148:149], v[164:165], v[126:127]
	v_pk_add_f32 v[126:127], v[164:165], v[126:127] neg_lo:[0,1] neg_hi:[0,1]
	v_pk_add_f32 v[164:165], v[152:153], v[80:81]
	v_pk_add_f32 v[80:81], v[152:153], v[80:81] neg_lo:[0,1] neg_hi:[0,1]
	s_nop 0
	v_pk_mul_f32 v[152:153], v[80:81], s[8:9]
	s_nop 0
	v_pk_fma_f32 v[80:81], v[80:81], s[10:11], v[152:153] op_sel:[0,0,1] op_sel_hi:[1,0,0]
	v_pk_add_f32 v[152:153], v[122:123], v[130:131]
	v_pk_add_f32 v[130:131], v[122:123], v[130:131] op_sel:[1,1] op_sel_hi:[0,0] neg_lo:[0,1] neg_hi:[1,0]
	s_nop 0
	v_pk_add_f32 v[122:123], v[124:125], v[132:133]
	v_pk_add_f32 v[124:125], v[124:125], v[132:133] neg_lo:[0,1] neg_hi:[0,1]
	s_nop 0
	v_pk_mul_f32 v[132:133], v[124:125], s[8:9]
	s_nop 0
	v_pk_fma_f32 v[124:125], v[124:125], s[8:9], v[132:133] op_sel:[0,0,1] op_sel_hi:[1,0,0]
	v_pk_add_f32 v[132:133], v[66:67], v[128:129]
	v_pk_add_f32 v[66:67], v[66:67], v[128:129] neg_lo:[0,1] neg_hi:[0,1]
	v_pk_add_f32 v[128:129], v[68:69], v[82:83]
	v_pk_add_f32 v[68:69], v[68:69], v[82:83] neg_lo:[0,1] neg_hi:[0,1]
	s_nop 0
	v_pk_mul_f32 v[82:83], v[68:69], s[8:9]
	s_nop 0
	v_pk_fma_f32 v[68:69], v[68:69], s[10:11], v[82:83] op_sel:[0,0,1] op_sel_hi:[1,0,0]
	v_pk_add_f32 v[82:83], v[72:73], v[116:117]
	v_pk_add_f32 v[116:117], v[72:73], v[116:117] op_sel:[1,1] op_sel_hi:[0,0] neg_lo:[0,1] neg_hi:[1,0]
	s_nop 0
	v_pk_add_f32 v[72:73], v[76:77], v[118:119]
	v_pk_add_f32 v[76:77], v[76:77], v[118:119] neg_lo:[0,1] neg_hi:[0,1]
	v_pk_add_f32 v[174:175], v[66:67], v[116:117]
	v_pk_mul_f32 v[118:119], v[76:77], s[8:9]
	v_pk_add_f32 v[116:117], v[66:67], v[116:117] neg_lo:[0,1] neg_hi:[0,1]
	v_pk_fma_f32 v[76:77], v[76:77], s[8:9], v[118:119] op_sel:[0,0,1] op_sel_hi:[1,0,0]
	v_pk_add_f32 v[118:119], v[134:135], v[168:169]
	v_pk_add_f32 v[134:135], v[134:135], v[168:169] neg_lo:[0,1] neg_hi:[0,1]
	v_pk_add_f32 v[168:169], v[166:167], v[136:137]
	v_pk_add_f32 v[166:167], v[166:167], v[136:137] op_sel:[1,1] op_sel_hi:[0,0] neg_lo:[0,1] neg_hi:[1,0]
	v_pk_add_f32 v[180:181], v[118:119], v[168:169]
	v_pk_add_f32 v[136:137], v[156:157], v[160:161]
	v_pk_add_f32 v[156:157], v[156:157], v[160:161] neg_lo:[0,1] neg_hi:[0,1]
	v_pk_add_f32 v[160:161], v[142:143], v[154:155]
	v_pk_add_f32 v[154:155], v[142:143], v[154:155] op_sel:[1,1] op_sel_hi:[0,0] neg_lo:[0,1] neg_hi:[1,0]
	v_pk_add_f32 v[66:67], v[68:69], v[76:77] neg_lo:[0,1] neg_hi:[0,1]
	v_pk_add_f32 v[142:143], v[162:163], v[144:145]
	v_pk_add_f32 v[144:145], v[162:163], v[144:145] neg_lo:[0,1] neg_hi:[0,1]
	v_pk_add_f32 v[162:163], v[158:159], v[138:139]
	v_pk_add_f32 v[158:159], v[158:159], v[138:139] op_sel:[1,1] op_sel_hi:[0,0] neg_lo:[0,1] neg_hi:[1,0]
	ds_write_b64 v74, v[180:181]
	v_pk_add_f32 v[138:139], v[150:151], v[146:147]
	v_pk_add_f32 v[146:147], v[150:151], v[146:147] neg_lo:[0,1] neg_hi:[0,1]
	v_pk_add_f32 v[150:151], v[120:121], v[140:141]
	v_pk_add_f32 v[140:141], v[120:121], v[140:141] op_sel:[1,1] op_sel_hi:[0,0] neg_lo:[0,1] neg_hi:[1,0]
	v_cos_f32_e32 v74, v115
	v_pk_add_f32 v[120:121], v[148:149], v[152:153]
	v_pk_add_f32 v[148:149], v[148:149], v[152:153] neg_lo:[0,1] neg_hi:[0,1]
	v_pk_add_f32 v[152:153], v[164:165], v[122:123]
	v_pk_add_f32 v[164:165], v[164:165], v[122:123] op_sel:[1,1] op_sel_hi:[0,0] neg_lo:[0,1] neg_hi:[1,0]
	v_xor_b32_e32 v179, 0x80000000, v66
	v_pk_add_f32 v[122:123], v[126:127], v[130:131]
	v_pk_add_f32 v[126:127], v[126:127], v[130:131] neg_lo:[0,1] neg_hi:[0,1]
	v_pk_add_f32 v[130:131], v[80:81], v[124:125]
	v_pk_add_f32 v[124:125], v[80:81], v[124:125] op_sel:[1,1] op_sel_hi:[0,0] neg_lo:[0,1] neg_hi:[1,0]
	v_mov_b32_e32 v178, v67
	v_pk_add_f32 v[80:81], v[132:133], v[82:83]
	v_pk_add_f32 v[132:133], v[132:133], v[82:83] neg_lo:[0,1] neg_hi:[0,1]
	v_pk_add_f32 v[176:177], v[68:69], v[76:77]
	v_pk_add_f32 v[118:119], v[118:119], v[168:169] neg_lo:[0,1] neg_hi:[0,1]
	v_pk_add_f32 v[168:169], v[134:135], v[166:167]
	v_pk_add_f32 v[82:83], v[134:135], v[166:167] neg_lo:[0,1] neg_hi:[0,1]
	v_pk_add_f32 v[134:135], v[136:137], v[160:161]
	v_pk_add_f32 v[136:137], v[136:137], v[160:161] neg_lo:[0,1] neg_hi:[0,1]
	v_pk_add_f32 v[160:161], v[156:157], v[154:155]
	v_pk_add_f32 v[68:69], v[156:157], v[154:155] neg_lo:[0,1] neg_hi:[0,1]
	v_pk_add_f32 v[154:155], v[142:143], v[162:163]
	v_pk_add_f32 v[142:143], v[142:143], v[162:163] neg_lo:[0,1] neg_hi:[0,1]
	v_pk_add_f32 v[156:157], v[144:145], v[158:159]
	v_pk_add_f32 v[76:77], v[144:145], v[158:159] neg_lo:[0,1] neg_hi:[0,1]
	v_pk_add_f32 v[144:145], v[138:139], v[150:151]
	v_pk_add_f32 v[138:139], v[138:139], v[150:151] neg_lo:[0,1] neg_hi:[0,1]
	v_pk_add_f32 v[150:151], v[146:147], v[140:141]
	v_pk_add_f32 v[66:67], v[146:147], v[140:141] neg_lo:[0,1] neg_hi:[0,1]
	v_pk_add_f32 v[140:141], v[120:121], v[152:153]
	v_pk_add_f32 v[162:163], v[116:117], v[178:179]
	v_pk_add_f32 v[70:71], v[116:117], v[178:179] neg_lo:[0,1] neg_hi:[0,1]
	v_mov_b32_e32 v116, v75
	v_pk_mul_f32 v[116:117], v[116:117], v[140:141] op_sel:[0,1] op_sel_hi:[0,0] neg_hi:[1,0]
	v_pk_fma_f32 v[116:117], v[140:141], v[74:75], v[116:117] op_sel_hi:[1,0,1]
	ds_write_b64 v114, v[116:117] offset:256
	v_pk_mul_f32 v[114:115], v[78:79], v[74:75] op_sel:[0,1] op_sel_hi:[1,0]
	v_pk_add_f32 v[172:173], v[128:129], v[72:73]
	v_pk_fma_f32 v[114:115], v[74:75], v[74:75], v[114:115] op_sel_hi:[1,0,1]
	v_pk_add_f32 v[128:129], v[128:129], v[72:73] op_sel:[1,1] op_sel_hi:[0,0] neg_lo:[0,1] neg_hi:[1,0]
	v_pk_add_f32 v[116:117], v[114:115], 0 neg_lo:[1,1] neg_hi:[1,1]
	v_mov_b32_e32 v116, v115
	v_pk_mul_f32 v[116:117], v[116:117], v[154:155] op_sel:[0,1] op_sel_hi:[1,0]
	v_pk_fma_f32 v[116:117], v[154:155], v[114:115], v[116:117] op_sel_hi:[1,0,1]
	ds_write_b64 v113, v[116:117] offset:512
	v_pk_mul_f32 v[116:117], v[78:79], v[114:115] op_sel:[0,1] op_sel_hi:[1,0]
	v_pk_add_f32 v[120:121], v[120:121], v[152:153] neg_lo:[0,1] neg_hi:[0,1]
	v_pk_fma_f32 v[114:115], v[114:115], v[74:75], v[116:117] op_sel_hi:[1,0,1]
	v_pk_add_f32 v[152:153], v[122:123], v[130:131]
	v_pk_add_f32 v[116:117], v[114:115], 0 neg_lo:[1,1] neg_hi:[1,1]
	v_pk_add_f32 v[122:123], v[122:123], v[130:131] neg_lo:[0,1] neg_hi:[0,1]
	v_pk_add_f32 v[130:131], v[126:127], v[124:125]
	v_pk_add_f32 v[72:73], v[126:127], v[124:125] neg_lo:[0,1] neg_hi:[0,1]
	v_pk_add_f32 v[124:125], v[80:81], v[172:173]
	v_mov_b32_e32 v116, v115
	v_pk_mul_f32 v[116:117], v[116:117], v[124:125] op_sel:[0,1] op_sel_hi:[1,0]
	v_pk_add_f32 v[126:127], v[80:81], v[172:173] neg_lo:[0,1] neg_hi:[0,1]
	v_pk_fma_f32 v[116:117], v[124:125], v[114:115], v[116:117] op_sel_hi:[1,0,1]
	ds_write_b64 v112, v[116:117] offset:768
	v_pk_mul_f32 v[112:113], v[78:79], v[114:115] op_sel:[0,1] op_sel_hi:[1,0]
	v_pk_add_f32 v[158:159], v[132:133], v[128:129]
	v_pk_fma_f32 v[112:113], v[114:115], v[74:75], v[112:113] op_sel_hi:[1,0,1]
	v_pk_add_f32 v[80:81], v[132:133], v[128:129] neg_lo:[0,1] neg_hi:[0,1]
	v_pk_add_f32 v[114:115], v[112:113], 0 neg_lo:[1,1] neg_hi:[1,1]
	v_pk_add_f32 v[128:129], v[174:175], v[176:177]
	v_mov_b32_e32 v114, v113
	v_pk_mul_f32 v[114:115], v[114:115], v[134:135] op_sel:[0,1] op_sel_hi:[1,0]
	v_pk_add_f32 v[146:147], v[148:149], v[164:165]
	v_pk_fma_f32 v[114:115], v[134:135], v[112:113], v[114:115] op_sel_hi:[1,0,1]
	ds_write_b64 v111, v[114:115] offset:1024
	v_pk_mul_f32 v[114:115], v[78:79], v[112:113] op_sel:[0,1] op_sel_hi:[1,0]
	v_pk_add_f32 v[132:133], v[174:175], v[176:177] neg_lo:[0,1] neg_hi:[0,1]
	v_pk_fma_f32 v[112:113], v[112:113], v[74:75], v[114:115] op_sel_hi:[1,0,1]
	v_pk_add_f32 v[148:149], v[148:149], v[164:165] neg_lo:[0,1] neg_hi:[0,1]
	v_pk_add_f32 v[114:115], v[112:113], 0 neg_lo:[1,1] neg_hi:[1,1]
	s_nop 0
	v_mov_b32_e32 v114, v113
	v_pk_mul_f32 v[114:115], v[114:115], v[152:153] op_sel:[0,1] op_sel_hi:[1,0]
	s_nop 0
	v_pk_fma_f32 v[114:115], v[152:153], v[112:113], v[114:115] op_sel_hi:[1,0,1]
	ds_write_b64 v110, v[114:115] offset:1280
	v_pk_mul_f32 v[110:111], v[78:79], v[112:113] op_sel:[0,1] op_sel_hi:[1,0]
	s_nop 0
	v_pk_fma_f32 v[110:111], v[112:113], v[74:75], v[110:111] op_sel_hi:[1,0,1]
	s_nop 0
	v_pk_add_f32 v[112:113], v[110:111], 0 neg_lo:[1,1] neg_hi:[1,1]
	s_nop 0
	v_mov_b32_e32 v112, v111
	v_pk_mul_f32 v[112:113], v[112:113], v[144:145] op_sel:[0,1] op_sel_hi:[1,0]
	s_nop 0
	v_pk_fma_f32 v[112:113], v[144:145], v[110:111], v[112:113] op_sel_hi:[1,0,1]
	ds_write_b64 v109, v[112:113] offset:1536
	v_pk_mul_f32 v[112:113], v[78:79], v[110:111] op_sel:[0,1] op_sel_hi:[1,0]
	s_nop 0
	v_pk_fma_f32 v[110:111], v[110:111], v[74:75], v[112:113] op_sel_hi:[1,0,1]
	s_nop 0
	v_pk_add_f32 v[112:113], v[110:111], 0 neg_lo:[1,1] neg_hi:[1,1]
	s_nop 0
	v_mov_b32_e32 v112, v111
	v_pk_mul_f32 v[112:113], v[112:113], v[128:129] op_sel:[0,1] op_sel_hi:[1,0]
	s_nop 0
	v_pk_fma_f32 v[112:113], v[128:129], v[110:111], v[112:113] op_sel_hi:[1,0,1]
	ds_write_b64 v108, v[112:113] offset:1792
	v_pk_mul_f32 v[108:109], v[78:79], v[110:111] op_sel:[0,1] op_sel_hi:[1,0]
	s_nop 0
	v_pk_fma_f32 v[108:109], v[110:111], v[74:75], v[108:109] op_sel_hi:[1,0,1]
	s_nop 0
	v_pk_add_f32 v[110:111], v[108:109], 0 neg_lo:[1,1] neg_hi:[1,1]
	s_nop 0
	v_mov_b32_e32 v110, v109
	v_pk_mul_f32 v[110:111], v[110:111], v[168:169] op_sel:[0,1] op_sel_hi:[1,0]
	s_nop 0
	v_pk_fma_f32 v[110:111], v[168:169], v[108:109], v[110:111] op_sel_hi:[1,0,1]
	ds_write_b64 v107, v[110:111] offset:2048
	v_pk_mul_f32 v[110:111], v[78:79], v[108:109] op_sel:[0,1] op_sel_hi:[1,0]
	s_nop 0
	v_pk_fma_f32 v[108:109], v[108:109], v[74:75], v[110:111] op_sel_hi:[1,0,1]
	s_nop 0
	v_pk_add_f32 v[110:111], v[108:109], 0 neg_lo:[1,1] neg_hi:[1,1]
	s_nop 0
	v_mov_b32_e32 v110, v109
	v_pk_mul_f32 v[110:111], v[110:111], v[146:147] op_sel:[0,1] op_sel_hi:[1,0]
	s_nop 0
	v_pk_fma_f32 v[110:111], v[146:147], v[108:109], v[110:111] op_sel_hi:[1,0,1]
	ds_write_b64 v106, v[110:111] offset:2304
	v_pk_mul_f32 v[106:107], v[78:79], v[108:109] op_sel:[0,1] op_sel_hi:[1,0]
	s_nop 0
	v_pk_fma_f32 v[106:107], v[108:109], v[74:75], v[106:107] op_sel_hi:[1,0,1]
	s_nop 0
	v_pk_add_f32 v[108:109], v[106:107], 0 neg_lo:[1,1] neg_hi:[1,1]
	s_nop 0
	v_mov_b32_e32 v108, v107
	v_pk_mul_f32 v[108:109], v[108:109], v[156:157] op_sel:[0,1] op_sel_hi:[1,0]
	s_nop 0
	v_pk_fma_f32 v[108:109], v[156:157], v[106:107], v[108:109] op_sel_hi:[1,0,1]
	ds_write_b64 v105, v[108:109] offset:2560
	v_pk_mul_f32 v[108:109], v[78:79], v[106:107] op_sel:[0,1] op_sel_hi:[1,0]
	s_nop 0
	v_pk_fma_f32 v[106:107], v[106:107], v[74:75], v[108:109] op_sel_hi:[1,0,1]
	s_nop 0
	v_pk_add_f32 v[108:109], v[106:107], 0 neg_lo:[1,1] neg_hi:[1,1]
	s_nop 0
	v_mov_b32_e32 v108, v107
	v_pk_mul_f32 v[108:109], v[108:109], v[158:159] op_sel:[0,1] op_sel_hi:[1,0]
	s_nop 0
	v_pk_fma_f32 v[108:109], v[158:159], v[106:107], v[108:109] op_sel_hi:[1,0,1]
	ds_write_b64 v103, v[108:109] offset:2816
	v_pk_mul_f32 v[108:109], v[78:79], v[106:107] op_sel:[0,1] op_sel_hi:[1,0]
	s_nop 0
	v_pk_fma_f32 v[106:107], v[106:107], v[74:75], v[108:109] op_sel_hi:[1,0,1]
	s_nop 0
	v_pk_add_f32 v[108:109], v[106:107], 0 neg_lo:[1,1] neg_hi:[1,1]
	s_nop 0
	v_mov_b32_e32 v108, v107
	v_pk_mul_f32 v[108:109], v[108:109], v[160:161] op_sel:[0,1] op_sel_hi:[1,0]
	s_nop 0
	v_pk_fma_f32 v[108:109], v[160:161], v[106:107], v[108:109] op_sel_hi:[1,0,1]
	ds_write_b64 v102, v[108:109] offset:3072
	v_pk_mul_f32 v[102:103], v[78:79], v[106:107] op_sel:[0,1] op_sel_hi:[1,0]
	s_nop 0
	v_pk_fma_f32 v[102:103], v[106:107], v[74:75], v[102:103] op_sel_hi:[1,0,1]
	s_nop 0
	v_pk_add_f32 v[106:107], v[102:103], 0 neg_lo:[1,1] neg_hi:[1,1]
	s_nop 0
	v_mov_b32_e32 v106, v103
	v_pk_mul_f32 v[106:107], v[106:107], v[130:131] op_sel:[0,1] op_sel_hi:[1,0]
	s_nop 0
	v_pk_fma_f32 v[106:107], v[130:131], v[102:103], v[106:107] op_sel_hi:[1,0,1]
	ds_write_b64 v101, v[106:107] offset:3328
	v_pk_mul_f32 v[106:107], v[78:79], v[102:103] op_sel:[0,1] op_sel_hi:[1,0]
	s_nop 0
	v_pk_fma_f32 v[102:103], v[102:103], v[74:75], v[106:107] op_sel_hi:[1,0,1]
	s_nop 0
	v_pk_add_f32 v[106:107], v[102:103], 0 neg_lo:[1,1] neg_hi:[1,1]
	s_nop 0
	v_mov_b32_e32 v106, v103
	v_pk_mul_f32 v[106:107], v[150:151], v[106:107] op_sel:[1,0] op_sel_hi:[0,1]
	v_pk_fma_f32 v[106:107], v[150:151], v[102:103], v[106:107] op_sel_hi:[1,0,1]
	ds_write_b64 v100, v[106:107] offset:3584
	v_pk_mul_f32 v[100:101], v[78:79], v[102:103] op_sel:[0,1] op_sel_hi:[1,0]
	s_nop 0
	v_pk_fma_f32 v[100:101], v[102:103], v[74:75], v[100:101] op_sel_hi:[1,0,1]
	s_nop 0
	v_pk_add_f32 v[102:103], v[100:101], 0 neg_lo:[1,1] neg_hi:[1,1]
	s_nop 0
	v_mov_b32_e32 v102, v101
	v_pk_mul_f32 v[102:103], v[162:163], v[102:103] op_sel:[1,0] op_sel_hi:[0,1]
	v_pk_fma_f32 v[102:103], v[162:163], v[100:101], v[102:103] op_sel_hi:[1,0,1]
	ds_write_b64 v99, v[102:103] offset:3840
	v_pk_mul_f32 v[102:103], v[78:79], v[100:101] op_sel:[0,1] op_sel_hi:[1,0]
	s_nop 0
	v_pk_fma_f32 v[100:101], v[100:101], v[74:75], v[102:103] op_sel_hi:[1,0,1]
	s_nop 0
	v_pk_add_f32 v[102:103], v[100:101], 0 neg_lo:[1,1] neg_hi:[1,1]
	s_nop 0
	v_mov_b32_e32 v102, v101
	v_pk_mul_f32 v[102:103], v[118:119], v[102:103] op_sel:[1,0] op_sel_hi:[0,1]
	v_pk_fma_f32 v[102:103], v[118:119], v[100:101], v[102:103] op_sel_hi:[1,0,1]
	ds_write_b64 v98, v[102:103] offset:4096
	v_pk_mul_f32 v[98:99], v[78:79], v[100:101] op_sel:[0,1] op_sel_hi:[1,0]
	s_nop 0
	v_pk_fma_f32 v[98:99], v[100:101], v[74:75], v[98:99] op_sel_hi:[1,0,1]
	s_nop 0
	v_pk_add_f32 v[100:101], v[98:99], 0 neg_lo:[1,1] neg_hi:[1,1]
	s_nop 0
	v_mov_b32_e32 v100, v99
	v_pk_mul_f32 v[100:101], v[120:121], v[100:101] op_sel:[1,0] op_sel_hi:[0,1]
	v_pk_fma_f32 v[100:101], v[120:121], v[98:99], v[100:101] op_sel_hi:[1,0,1]
	ds_write_b64 v97, v[100:101] offset:4352
	v_pk_mul_f32 v[100:101], v[78:79], v[98:99] op_sel:[0,1] op_sel_hi:[1,0]
	s_nop 0
	v_pk_fma_f32 v[98:99], v[98:99], v[74:75], v[100:101] op_sel_hi:[1,0,1]
	s_nop 0
	v_pk_add_f32 v[100:101], v[98:99], 0 neg_lo:[1,1] neg_hi:[1,1]
	s_nop 0
	v_mov_b32_e32 v100, v99
	v_pk_mul_f32 v[100:101], v[142:143], v[100:101] op_sel:[1,0] op_sel_hi:[0,1]
	v_pk_fma_f32 v[100:101], v[142:143], v[98:99], v[100:101] op_sel_hi:[1,0,1]
	ds_write_b64 v96, v[100:101] offset:4608
	v_pk_mul_f32 v[96:97], v[78:79], v[98:99] op_sel:[0,1] op_sel_hi:[1,0]
	s_nop 0
	v_pk_fma_f32 v[96:97], v[98:99], v[74:75], v[96:97] op_sel_hi:[1,0,1]
	s_nop 0
	v_pk_add_f32 v[98:99], v[96:97], 0 neg_lo:[1,1] neg_hi:[1,1]
	s_nop 0
	v_mov_b32_e32 v98, v97
	v_pk_mul_f32 v[98:99], v[126:127], v[98:99] op_sel:[1,0] op_sel_hi:[0,1]
	v_pk_fma_f32 v[98:99], v[126:127], v[96:97], v[98:99] op_sel_hi:[1,0,1]
	ds_write_b64 v95, v[98:99] offset:4864
	v_pk_mul_f32 v[98:99], v[78:79], v[96:97] op_sel:[0,1] op_sel_hi:[1,0]
	s_nop 0
	v_pk_fma_f32 v[96:97], v[96:97], v[74:75], v[98:99] op_sel_hi:[1,0,1]
	s_nop 0
	v_pk_add_f32 v[98:99], v[96:97], 0 neg_lo:[1,1] neg_hi:[1,1]
	s_nop 0
	v_mov_b32_e32 v98, v97
	v_pk_mul_f32 v[98:99], v[136:137], v[98:99] op_sel:[1,0] op_sel_hi:[0,1]
	v_pk_fma_f32 v[98:99], v[136:137], v[96:97], v[98:99] op_sel_hi:[1,0,1]
	ds_write_b64 v94, v[98:99] offset:5120
	v_pk_mul_f32 v[94:95], v[78:79], v[96:97] op_sel:[0,1] op_sel_hi:[1,0]
	s_nop 0
	v_pk_fma_f32 v[94:95], v[96:97], v[74:75], v[94:95] op_sel_hi:[1,0,1]
	s_nop 0
	v_pk_add_f32 v[96:97], v[94:95], 0 neg_lo:[1,1] neg_hi:[1,1]
	s_nop 0
	v_mov_b32_e32 v96, v95
	v_pk_mul_f32 v[96:97], v[122:123], v[96:97] op_sel:[1,0] op_sel_hi:[0,1]
	v_pk_fma_f32 v[96:97], v[122:123], v[94:95], v[96:97] op_sel_hi:[1,0,1]
	ds_write_b64 v93, v[96:97] offset:5376
	v_pk_mul_f32 v[96:97], v[78:79], v[94:95] op_sel:[0,1] op_sel_hi:[1,0]
	s_nop 0
	v_pk_fma_f32 v[94:95], v[94:95], v[74:75], v[96:97] op_sel_hi:[1,0,1]
	s_nop 0
	v_pk_add_f32 v[96:97], v[94:95], 0 neg_lo:[1,1] neg_hi:[1,1]
	s_nop 0
	v_mov_b32_e32 v96, v95
	v_pk_mul_f32 v[96:97], v[138:139], v[96:97] op_sel:[1,0] op_sel_hi:[0,1]
	v_pk_fma_f32 v[96:97], v[138:139], v[94:95], v[96:97] op_sel_hi:[1,0,1]
	ds_write_b64 v92, v[96:97] offset:5632
	v_pk_mul_f32 v[92:93], v[78:79], v[94:95] op_sel:[0,1] op_sel_hi:[1,0]
	s_nop 0
	v_pk_fma_f32 v[92:93], v[94:95], v[74:75], v[92:93] op_sel_hi:[1,0,1]
	s_nop 0
	v_pk_add_f32 v[94:95], v[92:93], 0 neg_lo:[1,1] neg_hi:[1,1]
	s_nop 0
	v_mov_b32_e32 v94, v93
	v_pk_mul_f32 v[94:95], v[132:133], v[94:95] op_sel:[1,0] op_sel_hi:[0,1]
	v_pk_fma_f32 v[94:95], v[132:133], v[92:93], v[94:95] op_sel_hi:[1,0,1]
	ds_write_b64 v91, v[94:95] offset:5888
	v_pk_mul_f32 v[94:95], v[78:79], v[92:93] op_sel:[0,1] op_sel_hi:[1,0]
	s_nop 0
	v_pk_fma_f32 v[92:93], v[92:93], v[74:75], v[94:95] op_sel_hi:[1,0,1]
	s_nop 0
	v_pk_add_f32 v[94:95], v[92:93], 0 neg_lo:[1,1] neg_hi:[1,1]
	s_nop 0
	v_mov_b32_e32 v94, v93
	v_pk_mul_f32 v[94:95], v[82:83], v[94:95] op_sel:[1,0] op_sel_hi:[0,1]
	v_pk_fma_f32 v[82:83], v[82:83], v[92:93], v[94:95] op_sel_hi:[1,0,1]
	ds_write_b64 v90, v[82:83] offset:6144
	v_pk_mul_f32 v[82:83], v[78:79], v[92:93] op_sel:[0,1] op_sel_hi:[1,0]
	s_nop 0
	v_pk_fma_f32 v[82:83], v[92:93], v[74:75], v[82:83] op_sel_hi:[1,0,1]
	s_nop 0
	v_pk_add_f32 v[90:91], v[82:83], 0 neg_lo:[1,1] neg_hi:[1,1]
	s_nop 0
	v_mov_b32_e32 v90, v83
	v_pk_mul_f32 v[90:91], v[148:149], v[90:91] op_sel:[1,0] op_sel_hi:[0,1]
	v_pk_fma_f32 v[90:91], v[148:149], v[82:83], v[90:91] op_sel_hi:[1,0,1]
	ds_write_b64 v89, v[90:91] offset:6400
	v_pk_mul_f32 v[90:91], v[78:79], v[82:83] op_sel:[0,1] op_sel_hi:[1,0]
	s_nop 0
	v_pk_fma_f32 v[82:83], v[82:83], v[74:75], v[90:91] op_sel_hi:[1,0,1]
	s_nop 0
	v_pk_add_f32 v[90:91], v[82:83], 0 neg_lo:[1,1] neg_hi:[1,1]
	s_nop 0
	v_mov_b32_e32 v90, v83
	v_pk_mul_f32 v[90:91], v[76:77], v[90:91] op_sel:[1,0] op_sel_hi:[0,1]
	v_pk_fma_f32 v[76:77], v[76:77], v[82:83], v[90:91] op_sel_hi:[1,0,1]
	ds_write_b64 v88, v[76:77] offset:6656
	v_pk_mul_f32 v[76:77], v[78:79], v[82:83] op_sel:[0,1] op_sel_hi:[1,0]
	s_nop 0
	v_pk_fma_f32 v[76:77], v[82:83], v[74:75], v[76:77] op_sel_hi:[1,0,1]
	s_nop 0
	v_pk_add_f32 v[82:83], v[76:77], 0 neg_lo:[1,1] neg_hi:[1,1]
	s_nop 0
	v_mov_b32_e32 v82, v77
	v_pk_mul_f32 v[82:83], v[80:81], v[82:83] op_sel:[1,0] op_sel_hi:[0,1]
	v_pk_fma_f32 v[80:81], v[80:81], v[76:77], v[82:83] op_sel_hi:[1,0,1]
	ds_write_b64 v87, v[80:81] offset:6912
	v_pk_mul_f32 v[80:81], v[78:79], v[76:77] op_sel:[0,1] op_sel_hi:[1,0]
	s_nop 0
	v_pk_fma_f32 v[76:77], v[76:77], v[74:75], v[80:81] op_sel_hi:[1,0,1]
	s_nop 0
	v_pk_add_f32 v[80:81], v[76:77], 0 neg_lo:[1,1] neg_hi:[1,1]
	s_nop 0
	v_mov_b32_e32 v80, v77
	v_pk_mul_f32 v[80:81], v[68:69], v[80:81] op_sel:[1,0] op_sel_hi:[0,1]
	v_pk_fma_f32 v[68:69], v[68:69], v[76:77], v[80:81] op_sel_hi:[1,0,1]
	ds_write_b64 v86, v[68:69] offset:7168
	v_pk_mul_f32 v[68:69], v[78:79], v[76:77] op_sel:[0,1] op_sel_hi:[1,0]
	s_nop 0
	v_pk_fma_f32 v[68:69], v[76:77], v[74:75], v[68:69] op_sel_hi:[1,0,1]
	s_nop 0
	v_pk_add_f32 v[76:77], v[68:69], 0 neg_lo:[1,1] neg_hi:[1,1]
	s_nop 0
	v_mov_b32_e32 v76, v69
	v_pk_mul_f32 v[76:77], v[72:73], v[76:77] op_sel:[1,0] op_sel_hi:[0,1]
	v_pk_fma_f32 v[72:73], v[72:73], v[68:69], v[76:77] op_sel_hi:[1,0,1]
	ds_write_b64 v85, v[72:73] offset:7424
	v_pk_mul_f32 v[72:73], v[78:79], v[68:69] op_sel:[0,1] op_sel_hi:[1,0]
	s_nop 0
	v_pk_fma_f32 v[68:69], v[68:69], v[74:75], v[72:73] op_sel_hi:[1,0,1]
	s_nop 0
	v_pk_add_f32 v[72:73], v[68:69], 0 neg_lo:[1,1] neg_hi:[1,1]
	s_nop 0
	v_mov_b32_e32 v72, v69
	v_pk_mul_f32 v[72:73], v[66:67], v[72:73] op_sel:[1,0] op_sel_hi:[0,1]
	v_pk_fma_f32 v[66:67], v[66:67], v[68:69], v[72:73] op_sel_hi:[1,0,1]
	ds_write_b64 v84, v[66:67] offset:7680
	v_pk_mul_f32 v[66:67], v[78:79], v[68:69] op_sel:[0,1] op_sel_hi:[1,0]
	s_nop 0
	v_pk_fma_f32 v[66:67], v[68:69], v[74:75], v[66:67] op_sel_hi:[1,0,1]
	s_nop 0
	v_pk_add_f32 v[68:69], v[66:67], 0 neg_lo:[1,1] neg_hi:[1,1]
	s_nop 0
	v_mov_b32_e32 v68, v67
	v_pk_mul_f32 v[68:69], v[70:71], v[68:69] op_sel:[1,0] op_sel_hi:[0,1]
	v_pk_fma_f32 v[66:67], v[70:71], v[66:67], v[68:69] op_sel_hi:[1,0,1]
	ds_write_b64 v0, v[66:67]
	s_waitcnt lgkmcnt(0)
	s_barrier
	ds_read2_b64 v[66:69], v104 offset1:1
	ds_read2_b64 v[70:73], v104 offset0:2 offset1:3
	ds_read2_b64 v[74:77], v104 offset0:4 offset1:5
	ds_read2_b64 v[78:81], v104 offset0:6 offset1:7
	ds_read2_b64 v[82:85], v104 offset0:8 offset1:9
	ds_read2_b64 v[86:89], v104 offset0:10 offset1:11
	ds_read2_b64 v[90:93], v104 offset0:12 offset1:13
	ds_read2_b64 v[94:97], v104 offset0:14 offset1:15
	ds_read2_b64 v[98:101], v104 offset0:16 offset1:17
	ds_read2_b64 v[106:109], v104 offset0:18 offset1:19
	ds_read2_b64 v[110:113], v104 offset0:20 offset1:21
	ds_read2_b64 v[114:117], v104 offset0:22 offset1:23
	ds_read2_b64 v[118:121], v104 offset0:24 offset1:25
	ds_read2_b64 v[122:125], v104 offset0:26 offset1:27
	ds_read2_b64 v[126:129], v104 offset0:28 offset1:29
	ds_read2_b64 v[130:133], v104 offset0:30 offset1:31
	s_waitcnt lgkmcnt(7)
	v_pk_add_f32 v[102:103], v[66:67], v[98:99]
	v_pk_add_f32 v[66:67], v[66:67], v[98:99] neg_lo:[0,1] neg_hi:[0,1]
	v_pk_add_f32 v[98:99], v[68:69], v[100:101]
	v_pk_add_f32 v[68:69], v[68:69], v[100:101] neg_lo:[0,1] neg_hi:[0,1]
	s_nop 0
	v_pk_mul_f32 v[100:101], v[68:69], s[18:19]
	s_nop 0
	v_pk_fma_f32 v[68:69], v[68:69], s[20:21], v[100:101] op_sel:[0,0,1] op_sel_hi:[1,0,0]
	s_waitcnt lgkmcnt(6)
	v_pk_add_f32 v[100:101], v[70:71], v[106:107]
	v_pk_add_f32 v[70:71], v[70:71], v[106:107] neg_lo:[0,1] neg_hi:[0,1]
	s_nop 0
	v_pk_mul_f32 v[106:107], v[70:71], s[4:5]
	s_nop 0
	v_pk_fma_f32 v[70:71], v[70:71], s[6:7], v[106:107] op_sel:[0,0,1] op_sel_hi:[1,0,0]
	v_pk_add_f32 v[106:107], v[72:73], v[108:109]
	v_pk_add_f32 v[72:73], v[72:73], v[108:109] neg_lo:[0,1] neg_hi:[0,1]
	s_nop 0
	v_pk_mul_f32 v[108:109], v[72:73], s[22:23]
	s_nop 0
	v_pk_fma_f32 v[72:73], v[72:73], s[24:25], v[108:109] op_sel:[0,0,1] op_sel_hi:[1,0,0]
	s_waitcnt lgkmcnt(5)
	v_pk_add_f32 v[108:109], v[74:75], v[110:111]
	v_pk_add_f32 v[74:75], v[74:75], v[110:111] neg_lo:[0,1] neg_hi:[0,1]
	s_nop 0
	v_pk_mul_f32 v[110:111], v[74:75], s[8:9]
	s_nop 0
	v_pk_fma_f32 v[74:75], v[74:75], s[10:11], v[110:111] op_sel:[0,0,1] op_sel_hi:[1,0,0]
	v_pk_add_f32 v[110:111], v[76:77], v[112:113]
	v_pk_add_f32 v[76:77], v[76:77], v[112:113] neg_lo:[0,1] neg_hi:[0,1]
	s_nop 0
	v_pk_mul_f32 v[112:113], v[76:77], s[26:27]
	s_nop 0
	v_pk_fma_f32 v[76:77], v[76:77], s[0:1], v[112:113] op_sel:[0,0,1] op_sel_hi:[1,0,0]
	s_waitcnt lgkmcnt(4)
	v_pk_add_f32 v[112:113], v[78:79], v[114:115]
	v_pk_add_f32 v[78:79], v[78:79], v[114:115] neg_lo:[0,1] neg_hi:[0,1]
	s_mov_b64 s[0:1], 0
	v_pk_mul_f32 v[114:115], v[78:79], s[12:13]
	s_nop 0
	v_pk_fma_f32 v[78:79], v[78:79], s[14:15], v[114:115] op_sel:[0,0,1] op_sel_hi:[1,0,0]
	v_pk_add_f32 v[114:115], v[80:81], v[116:117]
	v_pk_add_f32 v[80:81], v[80:81], v[116:117] neg_lo:[0,1] neg_hi:[0,1]
	s_nop 0
	v_pk_mul_f32 v[116:117], v[80:81], s[34:35]
	s_nop 0
	v_pk_fma_f32 v[80:81], v[80:81], s[44:45], v[116:117] op_sel:[0,0,1] op_sel_hi:[1,0,0]
	s_waitcnt lgkmcnt(3)
	v_pk_add_f32 v[116:117], v[82:83], v[118:119]
	v_pk_add_f32 v[118:119], v[82:83], v[118:119] op_sel:[1,1] op_sel_hi:[0,0] neg_lo:[0,1] neg_hi:[1,0]
	s_mov_b64 s[44:45], -1
	v_pk_add_f32 v[82:83], v[84:85], v[120:121]
	v_pk_add_f32 v[84:85], v[84:85], v[120:121] neg_lo:[0,1] neg_hi:[0,1]
	s_nop 0
	v_pk_mul_f32 v[120:121], v[84:85], s[34:35]
	s_nop 0
	v_pk_fma_f32 v[84:85], v[84:85], s[18:19], v[120:121] op_sel:[0,0,1] op_sel_hi:[1,0,0]
	s_waitcnt lgkmcnt(2)
	v_pk_add_f32 v[120:121], v[86:87], v[122:123]
	v_pk_add_f32 v[86:87], v[86:87], v[122:123] neg_lo:[0,1] neg_hi:[0,1]
	s_nop 0
	v_pk_mul_f32 v[122:123], v[86:87], s[12:13]
	s_nop 0
	v_pk_fma_f32 v[86:87], v[86:87], s[4:5], v[122:123] op_sel:[0,0,1] op_sel_hi:[1,0,0]
	v_pk_add_f32 v[122:123], v[88:89], v[124:125]
	v_pk_add_f32 v[88:89], v[88:89], v[124:125] neg_lo:[0,1] neg_hi:[0,1]
	s_nop 0
	v_pk_mul_f32 v[124:125], v[88:89], s[26:27]
	s_nop 0
	v_pk_fma_f32 v[88:89], v[88:89], s[22:23], v[124:125] op_sel:[0,0,1] op_sel_hi:[1,0,0]
	s_waitcnt lgkmcnt(1)
	v_pk_add_f32 v[124:125], v[90:91], v[126:127]
	v_pk_add_f32 v[90:91], v[90:91], v[126:127] neg_lo:[0,1] neg_hi:[0,1]
	s_nop 0
	v_pk_mul_f32 v[126:127], v[90:91], s[8:9]
	s_nop 0
	v_pk_fma_f32 v[90:91], v[90:91], s[8:9], v[126:127] op_sel:[0,0,1] op_sel_hi:[1,0,0]
	v_pk_add_f32 v[126:127], v[92:93], v[128:129]
	v_pk_add_f32 v[92:93], v[92:93], v[128:129] neg_lo:[0,1] neg_hi:[0,1]
	s_nop 0
	v_pk_mul_f32 v[128:129], v[92:93], s[22:23]
	s_nop 0
	v_pk_fma_f32 v[92:93], v[92:93], s[26:27], v[128:129] op_sel:[0,0,1] op_sel_hi:[1,0,0]
	s_waitcnt lgkmcnt(0)
	v_pk_add_f32 v[128:129], v[94:95], v[130:131]
	v_pk_add_f32 v[94:95], v[94:95], v[130:131] neg_lo:[0,1] neg_hi:[0,1]
	s_nop 0
	v_pk_mul_f32 v[130:131], v[94:95], s[4:5]
	s_nop 0
	v_pk_fma_f32 v[94:95], v[94:95], s[12:13], v[130:131] op_sel:[0,0,1] op_sel_hi:[1,0,0]
	v_pk_add_f32 v[130:131], v[96:97], v[132:133]
	v_pk_add_f32 v[96:97], v[96:97], v[132:133] neg_lo:[0,1] neg_hi:[0,1]
	s_nop 0
	v_pk_mul_f32 v[132:133], v[96:97], s[18:19]
	s_nop 0
	v_pk_fma_f32 v[96:97], v[96:97], s[34:35], v[132:133] op_sel:[0,0,1] op_sel_hi:[1,0,0]
	v_pk_add_f32 v[132:133], v[102:103], v[116:117]
	v_pk_add_f32 v[102:103], v[102:103], v[116:117] neg_lo:[0,1] neg_hi:[0,1]
	v_pk_add_f32 v[116:117], v[98:99], v[82:83]
	v_pk_add_f32 v[82:83], v[98:99], v[82:83] neg_lo:[0,1] neg_hi:[0,1]
	s_nop 0
	v_pk_mul_f32 v[98:99], v[82:83], s[4:5]
	s_nop 0
	v_pk_fma_f32 v[82:83], v[82:83], s[6:7], v[98:99] op_sel:[0,0,1] op_sel_hi:[1,0,0]
	v_pk_add_f32 v[98:99], v[100:101], v[120:121]
	v_pk_add_f32 v[100:101], v[100:101], v[120:121] neg_lo:[0,1] neg_hi:[0,1]
	s_nop 0
	v_pk_mul_f32 v[120:121], v[100:101], s[8:9]
	s_nop 0
	v_pk_fma_f32 v[100:101], v[100:101], s[10:11], v[120:121] op_sel:[0,0,1] op_sel_hi:[1,0,0]
	v_pk_add_f32 v[120:121], v[106:107], v[122:123]
	v_pk_add_f32 v[106:107], v[106:107], v[122:123] neg_lo:[0,1] neg_hi:[0,1]
	s_nop 0
	v_pk_mul_f32 v[122:123], v[106:107], s[12:13]
	s_nop 0
	v_pk_fma_f32 v[106:107], v[106:107], s[14:15], v[122:123] op_sel:[0,0,1] op_sel_hi:[1,0,0]
	v_pk_add_f32 v[122:123], v[108:109], v[124:125]
	v_pk_add_f32 v[124:125], v[108:109], v[124:125] op_sel:[1,1] op_sel_hi:[0,0] neg_lo:[0,1] neg_hi:[1,0]
	s_nop 0
	v_pk_add_f32 v[108:109], v[110:111], v[126:127]
	v_pk_add_f32 v[110:111], v[110:111], v[126:127] neg_lo:[0,1] neg_hi:[0,1]
	s_nop 0
	v_pk_mul_f32 v[126:127], v[110:111], s[12:13]
	s_nop 0
	v_pk_fma_f32 v[110:111], v[110:111], s[4:5], v[126:127] op_sel:[0,0,1] op_sel_hi:[1,0,0]
	v_pk_add_f32 v[126:127], v[112:113], v[128:129]
	v_pk_add_f32 v[112:113], v[112:113], v[128:129] neg_lo:[0,1] neg_hi:[0,1]
	s_nop 0
	v_pk_mul_f32 v[128:129], v[112:113], s[8:9]
	s_nop 0
	v_pk_fma_f32 v[112:113], v[112:113], s[8:9], v[128:129] op_sel:[0,0,1] op_sel_hi:[1,0,0]
	v_pk_add_f32 v[128:129], v[114:115], v[130:131]
	v_pk_add_f32 v[114:115], v[114:115], v[130:131] neg_lo:[0,1] neg_hi:[0,1]
	s_nop 0
	v_pk_mul_f32 v[130:131], v[114:115], s[4:5]
	s_nop 0
	v_pk_fma_f32 v[114:115], v[114:115], s[12:13], v[130:131] op_sel:[0,0,1] op_sel_hi:[1,0,0]
	v_pk_add_f32 v[130:131], v[66:67], v[118:119]
	v_pk_add_f32 v[66:67], v[66:67], v[118:119] neg_lo:[0,1] neg_hi:[0,1]
	v_pk_add_f32 v[118:119], v[68:69], v[84:85]
	v_pk_add_f32 v[68:69], v[68:69], v[84:85] neg_lo:[0,1] neg_hi:[0,1]
	s_nop 0
	v_pk_mul_f32 v[84:85], v[68:69], s[4:5]
	s_nop 0
	v_pk_fma_f32 v[68:69], v[68:69], s[6:7], v[84:85] op_sel:[0,0,1] op_sel_hi:[1,0,0]
	v_pk_add_f32 v[84:85], v[70:71], v[86:87]
	v_pk_add_f32 v[70:71], v[70:71], v[86:87] neg_lo:[0,1] neg_hi:[0,1]
	s_nop 0
	v_pk_mul_f32 v[86:87], v[70:71], s[8:9]
	s_nop 0
	v_pk_fma_f32 v[70:71], v[70:71], s[10:11], v[86:87] op_sel:[0,0,1] op_sel_hi:[1,0,0]
	v_pk_add_f32 v[86:87], v[72:73], v[88:89]
	v_pk_add_f32 v[72:73], v[72:73], v[88:89] neg_lo:[0,1] neg_hi:[0,1]
	s_nop 0
	v_pk_mul_f32 v[88:89], v[72:73], s[12:13]
	s_nop 0
	v_pk_fma_f32 v[72:73], v[72:73], s[14:15], v[88:89] op_sel:[0,0,1] op_sel_hi:[1,0,0]
	v_pk_add_f32 v[88:89], v[74:75], v[90:91]
	v_pk_add_f32 v[90:91], v[74:75], v[90:91] op_sel:[1,1] op_sel_hi:[0,0] neg_lo:[0,1] neg_hi:[1,0]
	s_nop 0
	v_pk_add_f32 v[74:75], v[76:77], v[92:93]
	v_pk_add_f32 v[76:77], v[76:77], v[92:93] neg_lo:[0,1] neg_hi:[0,1]
	s_nop 0
	v_pk_mul_f32 v[92:93], v[76:77], s[12:13]
	s_nop 0
	v_pk_fma_f32 v[76:77], v[76:77], s[4:5], v[92:93] op_sel:[0,0,1] op_sel_hi:[1,0,0]
	v_pk_add_f32 v[92:93], v[78:79], v[94:95]
	v_pk_add_f32 v[78:79], v[78:79], v[94:95] neg_lo:[0,1] neg_hi:[0,1]
	s_nop 0
	v_pk_mul_f32 v[94:95], v[78:79], s[8:9]
	s_nop 0
	v_pk_fma_f32 v[78:79], v[78:79], s[8:9], v[94:95] op_sel:[0,0,1] op_sel_hi:[1,0,0]
	v_pk_add_f32 v[94:95], v[80:81], v[96:97]
	v_pk_add_f32 v[80:81], v[80:81], v[96:97] neg_lo:[0,1] neg_hi:[0,1]
	s_nop 0
	v_pk_mul_f32 v[96:97], v[80:81], s[4:5]
	s_nop 0
	v_pk_fma_f32 v[80:81], v[80:81], s[12:13], v[96:97] op_sel:[0,0,1] op_sel_hi:[1,0,0]
	v_pk_add_f32 v[96:97], v[132:133], v[122:123]
	v_pk_add_f32 v[122:123], v[132:133], v[122:123] neg_lo:[0,1] neg_hi:[0,1]
	v_pk_add_f32 v[132:133], v[116:117], v[108:109]
	v_pk_add_f32 v[108:109], v[116:117], v[108:109] neg_lo:[0,1] neg_hi:[0,1]
	s_nop 0
	v_pk_mul_f32 v[116:117], v[108:109], s[8:9]
	s_nop 0
	v_pk_fma_f32 v[108:109], v[108:109], s[10:11], v[116:117] op_sel:[0,0,1] op_sel_hi:[1,0,0]
	v_pk_add_f32 v[116:117], v[98:99], v[126:127]
	v_pk_add_f32 v[126:127], v[98:99], v[126:127] op_sel:[1,1] op_sel_hi:[0,0] neg_lo:[0,1] neg_hi:[1,0]
	s_nop 0
	v_pk_add_f32 v[98:99], v[120:121], v[128:129]
	v_pk_add_f32 v[120:121], v[120:121], v[128:129] neg_lo:[0,1] neg_hi:[0,1]
	s_nop 0
	v_pk_mul_f32 v[128:129], v[120:121], s[8:9]
	s_nop 0
	v_pk_fma_f32 v[120:121], v[120:121], s[8:9], v[128:129] op_sel:[0,0,1] op_sel_hi:[1,0,0]
	v_pk_add_f32 v[128:129], v[102:103], v[124:125]
	v_pk_add_f32 v[102:103], v[102:103], v[124:125] neg_lo:[0,1] neg_hi:[0,1]
	v_pk_add_f32 v[124:125], v[82:83], v[110:111]
	v_pk_add_f32 v[82:83], v[82:83], v[110:111] neg_lo:[0,1] neg_hi:[0,1]
	s_nop 0
	v_pk_mul_f32 v[110:111], v[82:83], s[8:9]
	s_nop 0
	v_pk_fma_f32 v[82:83], v[82:83], s[10:11], v[110:111] op_sel:[0,0,1] op_sel_hi:[1,0,0]
	v_pk_add_f32 v[110:111], v[100:101], v[112:113]
	v_pk_add_f32 v[112:113], v[100:101], v[112:113] op_sel:[1,1] op_sel_hi:[0,0] neg_lo:[0,1] neg_hi:[1,0]
	s_nop 0
	v_pk_add_f32 v[100:101], v[106:107], v[114:115]
	v_pk_add_f32 v[106:107], v[106:107], v[114:115] neg_lo:[0,1] neg_hi:[0,1]
	s_nop 0
	v_pk_mul_f32 v[114:115], v[106:107], s[8:9]
	s_nop 0
	v_pk_fma_f32 v[106:107], v[106:107], s[8:9], v[114:115] op_sel:[0,0,1] op_sel_hi:[1,0,0]
	v_pk_add_f32 v[114:115], v[130:131], v[88:89]
	v_pk_add_f32 v[88:89], v[130:131], v[88:89] neg_lo:[0,1] neg_hi:[0,1]
	v_pk_add_f32 v[130:131], v[118:119], v[74:75]
	v_pk_add_f32 v[74:75], v[118:119], v[74:75] neg_lo:[0,1] neg_hi:[0,1]
	s_nop 0
	v_pk_mul_f32 v[118:119], v[74:75], s[8:9]
	s_nop 0
	v_pk_fma_f32 v[74:75], v[74:75], s[10:11], v[118:119] op_sel:[0,0,1] op_sel_hi:[1,0,0]
	v_pk_add_f32 v[118:119], v[84:85], v[92:93]
	v_pk_add_f32 v[92:93], v[84:85], v[92:93] op_sel:[1,1] op_sel_hi:[0,0] neg_lo:[0,1] neg_hi:[1,0]
	s_nop 0
	v_pk_add_f32 v[84:85], v[86:87], v[94:95]
	v_pk_add_f32 v[86:87], v[86:87], v[94:95] neg_lo:[0,1] neg_hi:[0,1]
	s_nop 0
	v_pk_mul_f32 v[94:95], v[86:87], s[8:9]
	s_nop 0
	v_pk_fma_f32 v[86:87], v[86:87], s[8:9], v[94:95] op_sel:[0,0,1] op_sel_hi:[1,0,0]
	v_pk_add_f32 v[94:95], v[66:67], v[90:91]
	v_pk_add_f32 v[66:67], v[66:67], v[90:91] neg_lo:[0,1] neg_hi:[0,1]
	v_pk_add_f32 v[90:91], v[68:69], v[76:77]
	v_pk_add_f32 v[68:69], v[68:69], v[76:77] neg_lo:[0,1] neg_hi:[0,1]
	s_nop 0
	v_pk_mul_f32 v[76:77], v[68:69], s[8:9]
	s_nop 0
	v_pk_fma_f32 v[68:69], v[68:69], s[10:11], v[76:77] op_sel:[0,0,1] op_sel_hi:[1,0,0]
	v_pk_add_f32 v[76:77], v[70:71], v[78:79]
	v_pk_add_f32 v[78:79], v[70:71], v[78:79] op_sel:[1,1] op_sel_hi:[0,0] neg_lo:[0,1] neg_hi:[1,0]
	s_nop 0
	v_pk_add_f32 v[70:71], v[72:73], v[80:81]
	v_pk_add_f32 v[72:73], v[72:73], v[80:81] neg_lo:[0,1] neg_hi:[0,1]
	s_nop 0
	v_pk_mul_f32 v[80:81], v[72:73], s[8:9]
	s_nop 0
	v_pk_fma_f32 v[72:73], v[72:73], s[8:9], v[80:81] op_sel:[0,0,1] op_sel_hi:[1,0,0]
	v_pk_add_f32 v[80:81], v[96:97], v[116:117]
	v_pk_add_f32 v[96:97], v[96:97], v[116:117] neg_lo:[0,1] neg_hi:[0,1]
	v_pk_add_f32 v[116:117], v[132:133], v[98:99]
	v_pk_add_f32 v[132:133], v[132:133], v[98:99] op_sel:[1,1] op_sel_hi:[0,0] neg_lo:[0,1] neg_hi:[1,0]
	s_nop 0
	v_pk_add_f32 v[98:99], v[122:123], v[126:127]
	v_pk_add_f32 v[122:123], v[122:123], v[126:127] neg_lo:[0,1] neg_hi:[0,1]
	v_pk_add_f32 v[126:127], v[108:109], v[120:121]
	v_pk_add_f32 v[120:121], v[108:109], v[120:121] op_sel:[1,1] op_sel_hi:[0,0] neg_lo:[0,1] neg_hi:[1,0]
	s_nop 0
	v_pk_add_f32 v[108:109], v[128:129], v[110:111]
	v_pk_add_f32 v[110:111], v[128:129], v[110:111] neg_lo:[0,1] neg_hi:[0,1]
	v_pk_add_f32 v[128:129], v[124:125], v[100:101]
	v_pk_add_f32 v[124:125], v[124:125], v[100:101] op_sel:[1,1] op_sel_hi:[0,0] neg_lo:[0,1] neg_hi:[1,0]
	s_nop 0
	v_pk_add_f32 v[100:101], v[102:103], v[112:113]
	v_pk_add_f32 v[102:103], v[102:103], v[112:113] neg_lo:[0,1] neg_hi:[0,1]
	v_pk_add_f32 v[112:113], v[82:83], v[106:107]
	v_pk_add_f32 v[106:107], v[82:83], v[106:107] op_sel:[1,1] op_sel_hi:[0,0] neg_lo:[0,1] neg_hi:[1,0]
	s_nop 0
	v_pk_add_f32 v[82:83], v[114:115], v[118:119]
	v_pk_add_f32 v[114:115], v[114:115], v[118:119] neg_lo:[0,1] neg_hi:[0,1]
	v_pk_add_f32 v[118:119], v[130:131], v[84:85]
	v_pk_add_f32 v[130:131], v[130:131], v[84:85] op_sel:[1,1] op_sel_hi:[0,0] neg_lo:[0,1] neg_hi:[1,0]
	s_nop 0
	v_pk_add_f32 v[84:85], v[88:89], v[92:93]
	v_pk_add_f32 v[88:89], v[88:89], v[92:93] neg_lo:[0,1] neg_hi:[0,1]
	v_pk_add_f32 v[92:93], v[74:75], v[86:87]
	v_pk_add_f32 v[86:87], v[74:75], v[86:87] op_sel:[1,1] op_sel_hi:[0,0] neg_lo:[0,1] neg_hi:[1,0]
	s_nop 0
	v_pk_add_f32 v[74:75], v[94:95], v[76:77]
	v_pk_add_f32 v[76:77], v[94:95], v[76:77] neg_lo:[0,1] neg_hi:[0,1]
	v_pk_add_f32 v[94:95], v[90:91], v[70:71]
	v_pk_add_f32 v[90:91], v[90:91], v[70:71] op_sel:[1,1] op_sel_hi:[0,0] neg_lo:[0,1] neg_hi:[1,0]
	s_nop 0
	v_pk_add_f32 v[70:71], v[66:67], v[78:79]
	v_pk_add_f32 v[66:67], v[66:67], v[78:79] neg_lo:[0,1] neg_hi:[0,1]
	v_pk_add_f32 v[78:79], v[68:69], v[72:73]
	v_pk_add_f32 v[72:73], v[68:69], v[72:73] op_sel:[1,1] op_sel_hi:[0,0] neg_lo:[0,1] neg_hi:[1,0]
	s_nop 0
	v_pk_add_f32 v[68:69], v[80:81], v[116:117]
	v_pk_add_f32 v[80:81], v[80:81], v[116:117] neg_lo:[0,1] neg_hi:[0,1]
	v_pk_add_f32 v[116:117], v[96:97], v[132:133]
	v_pk_add_f32 v[96:97], v[96:97], v[132:133] neg_lo:[0,1] neg_hi:[0,1]
	v_pk_add_f32 v[132:133], v[98:99], v[126:127]
	v_pk_add_f32 v[98:99], v[98:99], v[126:127] neg_lo:[0,1] neg_hi:[0,1]
	v_pk_add_f32 v[126:127], v[122:123], v[120:121]
	v_pk_add_f32 v[120:121], v[122:123], v[120:121] neg_lo:[0,1] neg_hi:[0,1]
	v_pk_add_f32 v[122:123], v[108:109], v[128:129]
	v_pk_add_f32 v[108:109], v[108:109], v[128:129] neg_lo:[0,1] neg_hi:[0,1]
	v_pk_add_f32 v[128:129], v[110:111], v[124:125]
	v_pk_add_f32 v[110:111], v[110:111], v[124:125] neg_lo:[0,1] neg_hi:[0,1]
	v_pk_add_f32 v[124:125], v[100:101], v[112:113]
	v_pk_add_f32 v[100:101], v[100:101], v[112:113] neg_lo:[0,1] neg_hi:[0,1]
	v_pk_add_f32 v[112:113], v[102:103], v[106:107]
	v_pk_add_f32 v[102:103], v[102:103], v[106:107] neg_lo:[0,1] neg_hi:[0,1]
	v_pk_add_f32 v[106:107], v[82:83], v[118:119]
	v_pk_mul_f32 v[68:69], v[68:69], s[2:3] op_sel_hi:[1,0]
	global_store_dwordx2 v[2:3], v[68:69], off
	v_pk_mul_f32 v[68:69], v[106:107], s[2:3] op_sel_hi:[1,0]
	v_pk_add_f32 v[82:83], v[82:83], v[118:119] neg_lo:[0,1] neg_hi:[0,1]
	v_pk_add_f32 v[118:119], v[114:115], v[130:131]
	v_pk_add_f32 v[114:115], v[114:115], v[130:131] neg_lo:[0,1] neg_hi:[0,1]
	v_pk_add_f32 v[130:131], v[84:85], v[92:93]
	v_pk_add_f32 v[84:85], v[84:85], v[92:93] neg_lo:[0,1] neg_hi:[0,1]
	v_pk_add_f32 v[92:93], v[88:89], v[86:87]
	v_pk_add_f32 v[86:87], v[88:89], v[86:87] neg_lo:[0,1] neg_hi:[0,1]
	v_pk_add_f32 v[88:89], v[74:75], v[94:95]
	global_store_dwordx2 v[4:5], v[68:69], off
	v_pk_mul_f32 v[68:69], v[122:123], s[2:3] op_sel_hi:[1,0]
	global_store_dwordx2 v[6:7], v[68:69], off
	v_pk_mul_f32 v[68:69], v[88:89], s[2:3] op_sel_hi:[1,0]
	global_store_dwordx2 v[8:9], v[68:69], off
	v_pk_mul_f32 v[68:69], v[132:133], s[2:3] op_sel_hi:[1,0]
	global_store_dwordx2 v[10:11], v[68:69], off
	v_pk_mul_f32 v[68:69], v[130:131], s[2:3] op_sel_hi:[1,0]
	v_pk_add_f32 v[74:75], v[74:75], v[94:95] neg_lo:[0,1] neg_hi:[0,1]
	v_pk_add_f32 v[94:95], v[76:77], v[90:91]
	v_pk_add_f32 v[76:77], v[76:77], v[90:91] neg_lo:[0,1] neg_hi:[0,1]
	v_pk_add_f32 v[90:91], v[70:71], v[78:79]
	global_store_dwordx2 v[12:13], v[68:69], off
	v_pk_mul_f32 v[68:69], v[124:125], s[2:3] op_sel_hi:[1,0]
	global_store_dwordx2 v[14:15], v[68:69], off
	v_pk_mul_f32 v[68:69], v[90:91], s[2:3] op_sel_hi:[1,0]
	global_store_dwordx2 v[16:17], v[68:69], off
	v_pk_mul_f32 v[68:69], v[116:117], s[2:3] op_sel_hi:[1,0]
	global_store_dwordx2 v[18:19], v[68:69], off
	v_pk_mul_f32 v[68:69], v[118:119], s[2:3] op_sel_hi:[1,0]
	global_store_dwordx2 v[20:21], v[68:69], off
	v_pk_mul_f32 v[68:69], v[128:129], s[2:3] op_sel_hi:[1,0]
	global_store_dwordx2 v[22:23], v[68:69], off
	v_pk_mul_f32 v[68:69], v[94:95], s[2:3] op_sel_hi:[1,0]
	global_store_dwordx2 v[24:25], v[68:69], off
	v_pk_mul_f32 v[68:69], v[126:127], s[2:3] op_sel_hi:[1,0]
	global_store_dwordx2 v[26:27], v[68:69], off
	v_pk_mul_f32 v[68:69], v[92:93], s[2:3] op_sel_hi:[1,0]
	v_pk_add_f32 v[70:71], v[70:71], v[78:79] neg_lo:[0,1] neg_hi:[0,1]
	v_pk_add_f32 v[78:79], v[66:67], v[72:73]
	global_store_dwordx2 v[28:29], v[68:69], off
	v_pk_mul_f32 v[68:69], v[112:113], s[2:3] op_sel_hi:[1,0]
	global_store_dwordx2 v[30:31], v[68:69], off
	v_pk_mul_f32 v[68:69], v[78:79], s[2:3] op_sel_hi:[1,0]
	global_store_dwordx2 v[32:33], v[68:69], off
	v_pk_mul_f32 v[68:69], v[80:81], s[2:3] op_sel_hi:[1,0]
	global_store_dwordx2 v[34:35], v[68:69], off
	v_pk_mul_f32 v[68:69], v[82:83], s[2:3] op_sel_hi:[1,0]
	global_store_dwordx2 v[36:37], v[68:69], off
	v_pk_mul_f32 v[68:69], v[108:109], s[2:3] op_sel_hi:[1,0]
	global_store_dwordx2 v[38:39], v[68:69], off
	v_pk_mul_f32 v[68:69], v[74:75], s[2:3] op_sel_hi:[1,0]
	global_store_dwordx2 v[40:41], v[68:69], off
	v_pk_mul_f32 v[68:69], v[98:99], s[2:3] op_sel_hi:[1,0]
	global_store_dwordx2 v[42:43], v[68:69], off
	v_pk_mul_f32 v[68:69], v[84:85], s[2:3] op_sel_hi:[1,0]
	global_store_dwordx2 v[44:45], v[68:69], off
	v_pk_mul_f32 v[68:69], v[100:101], s[2:3] op_sel_hi:[1,0]
	global_store_dwordx2 v[46:47], v[68:69], off
	v_pk_mul_f32 v[68:69], v[70:71], s[2:3] op_sel_hi:[1,0]
	global_store_dwordx2 v[48:49], v[68:69], off
	v_pk_mul_f32 v[68:69], v[96:97], s[2:3] op_sel_hi:[1,0]
	global_store_dwordx2 v[50:51], v[68:69], off
	v_pk_mul_f32 v[68:69], v[114:115], s[2:3] op_sel_hi:[1,0]
	global_store_dwordx2 v[52:53], v[68:69], off
	v_pk_mul_f32 v[68:69], v[110:111], s[2:3] op_sel_hi:[1,0]
	global_store_dwordx2 v[54:55], v[68:69], off
	v_pk_mul_f32 v[68:69], v[76:77], s[2:3] op_sel_hi:[1,0]
	global_store_dwordx2 v[56:57], v[68:69], off
	v_pk_mul_f32 v[68:69], v[120:121], s[2:3] op_sel_hi:[1,0]
	v_pk_add_f32 v[66:67], v[66:67], v[72:73] neg_lo:[0,1] neg_hi:[0,1]
	global_store_dwordx2 v[58:59], v[68:69], off
	v_pk_mul_f32 v[68:69], v[86:87], s[2:3] op_sel_hi:[1,0]
	global_store_dwordx2 v[60:61], v[68:69], off
	v_pk_mul_f32 v[68:69], v[102:103], s[2:3] op_sel_hi:[1,0]
	v_pk_mul_f32 v[66:67], v[66:67], s[2:3] op_sel_hi:[1,0]
	global_store_dwordx2 v[62:63], v[68:69], off
	global_store_dwordx2 v[64:65], v[66:67], off
	s_barrier

.Lmy_fft_hj:
	v_mov_b32 v66, 0
	s_movk_i32 s5, 0x200
	v_add_u32_e32 v0, v66, v0
	v_cvt_f32_i32_e32 v68, v0
	v_ashrrev_i32_e32 v66, 5, v0
	v_lshlrev_b32_e32 v67, 3, v0
	v_add_u32_e32 v69, 0x400, v0
	v_add_u32_e32 v70, 0x800, v0
	v_add_u32_e32 v71, 0xc00, v0
	v_add_u32_e32 v72, 0x1000, v0
	v_add_u32_e32 v73, 0x1400, v0
	v_add_u32_e32 v74, 0x1800, v0
	v_add_u32_e32 v75, 0x1c00, v0
	v_add_u32_e32 v76, 0x2000, v0
	v_add_u32_e32 v77, 0x2400, v0
	v_add_u32_e32 v78, 0x2800, v0
	v_add_u32_e32 v79, 0x2c00, v0
	v_add_u32_e32 v80, 0x3000, v0
	v_add_u32_e32 v81, 0x3400, v0
	v_add_u32_e32 v82, 0x3800, v0
	v_add_u32_e32 v0, 0x3c00, v0
	v_lshlrev_b32_e32 v66, 3, v66
	v_ashrrev_i32_e32 v69, 5, v69
	v_ashrrev_i32_e32 v70, 5, v70
	v_ashrrev_i32_e32 v71, 5, v71
	v_ashrrev_i32_e32 v72, 5, v72
	v_ashrrev_i32_e32 v73, 5, v73
	v_ashrrev_i32_e32 v74, 5, v74
	v_ashrrev_i32_e32 v75, 5, v75
	v_ashrrev_i32_e32 v83, 5, v76
	v_ashrrev_i32_e32 v84, 5, v77
	v_ashrrev_i32_e32 v85, 5, v78
	v_ashrrev_i32_e32 v86, 5, v79
	v_ashrrev_i32_e32 v87, 5, v80
	v_ashrrev_i32_e32 v88, 5, v81
	v_ashrrev_i32_e32 v89, 5, v82
	v_ashrrev_i32_e32 v90, 5, v0
	v_lshlrev_b32_e32 v0, 3, v0
	v_add3_u32 v171, 0, v66, v67
	v_lshlrev_b32_e32 v66, 3, v69
	v_lshlrev_b32_e32 v69, 3, v70
	v_lshlrev_b32_e32 v70, 3, v71
	v_lshlrev_b32_e32 v71, 3, v72
	v_lshlrev_b32_e32 v72, 3, v73
	v_lshlrev_b32_e32 v73, 3, v74
	v_lshlrev_b32_e32 v74, 3, v75
	v_lshlrev_b32_e32 v75, 3, v83
	v_lshlrev_b32_e32 v83, 3, v84
	v_lshlrev_b32_e32 v84, 3, v85
	v_lshlrev_b32_e32 v85, 3, v86
	v_lshlrev_b32_e32 v86, 3, v87
	v_lshlrev_b32_e32 v87, 3, v88
	v_lshlrev_b32_e32 v88, 3, v89
	v_lshlrev_b32_e32 v89, 3, v90
	v_add3_u32 v186, 0, v89, v0
	v_mul_f32_e32 v0, 0x38800000, v68
	v_add3_u32 v172, 0, v66, v67
	v_add3_u32 v173, 0, v69, v67
	v_add3_u32 v174, 0, v70, v67
	v_add3_u32 v175, 0, v71, v67
	v_add3_u32 v176, 0, v72, v67
	v_add3_u32 v177, 0, v73, v67
	v_add3_u32 v178, 0, v74, v67
	v_sin_f32_e32 v67, v0
	v_cos_f32_e32 v66, v0
	v_lshlrev_b32_e32 v76, 3, v76
	v_add3_u32 v179, 0, v75, v76
	v_xor_b32_e32 v68, 0x80000000, v67
	v_mov_b32_e32 v69, v67
	v_pk_mul_f32 v[70:71], v[68:69], v[66:67] op_sel:[0,1] op_sel_hi:[1,0]
	v_lshlrev_b32_e32 v78, 3, v78
	v_pk_fma_f32 v[70:71], v[66:67], v[66:67], v[70:71] op_sel_hi:[1,0,1]
	v_lshlrev_b32_e32 v79, 3, v79
	v_pk_mul_f32 v[74:75], v[68:69], v[70:71] op_sel:[0,1] op_sel_hi:[1,0]
	v_add3_u32 v181, 0, v84, v78
	v_pk_fma_f32 v[74:75], v[70:71], v[66:67], v[74:75] op_sel_hi:[1,0,1]
	v_add3_u32 v182, 0, v85, v79
	v_pk_mul_f32 v[78:79], v[68:69], v[74:75] op_sel:[0,1] op_sel_hi:[1,0]
	v_lshlrev_b32_e32 v77, 3, v77
	v_lshlrev_b32_e32 v82, 3, v82
	v_pk_fma_f32 v[78:79], v[74:75], v[66:67], v[78:79] op_sel_hi:[1,0,1]
	v_add3_u32 v180, 0, v83, v77
	v_add3_u32 v185, 0, v88, v82
	v_pk_mul_f32 v[82:83], v[68:69], v[78:79] op_sel:[0,1] op_sel_hi:[1,0]
	v_lshlrev_b32_e32 v80, 3, v80
	v_lshlrev_b32_e32 v81, 3, v81
	v_pk_fma_f32 v[82:83], v[78:79], v[66:67], v[82:83] op_sel_hi:[1,0,1]
	v_add3_u32 v183, 0, v86, v80
	v_add3_u32 v184, 0, v87, v81
	v_pk_mul_f32 v[86:87], v[68:69], v[82:83] op_sel:[0,1] op_sel_hi:[1,0]
	s_waitcnt vmcnt(31)
	v_lshlrev_b32_e32 v126, 16, v105
	v_pk_fma_f32 v[86:87], v[82:83], v[66:67], v[86:87] op_sel_hi:[1,0,1]
	s_waitcnt vmcnt(30)
	v_lshlrev_b32_e32 v127, 16, v127
	v_pk_mul_f32 v[90:91], v[68:69], v[86:87] op_sel:[0,1] op_sel_hi:[1,0]
	s_waitcnt vmcnt(29)
	v_lshlrev_b32_e32 v129, 16, v128
	v_pk_fma_f32 v[90:91], v[86:87], v[66:67], v[90:91] op_sel_hi:[1,0,1]
	s_waitcnt vmcnt(24)
	v_lshlrev_b32_e32 v128, 16, v134
	v_pk_mul_f32 v[94:95], v[68:69], v[90:91] op_sel:[0,1] op_sel_hi:[1,0]
	v_lshlrev_b32_e32 v130, 16, v130
	v_pk_fma_f32 v[94:95], v[90:91], v[66:67], v[94:95] op_sel_hi:[1,0,1]
	v_lshlrev_b32_e32 v131, 16, v131
	v_pk_mul_f32 v[98:99], v[68:69], v[94:95] op_sel:[0,1] op_sel_hi:[1,0]
	v_lshlrev_b32_e32 v132, 16, v132
	v_pk_fma_f32 v[98:99], v[94:95], v[66:67], v[98:99] op_sel_hi:[1,0,1]
	v_lshlrev_b32_e32 v133, 16, v133
	v_pk_mul_f32 v[102:103], v[68:69], v[98:99] op_sel:[0,1] op_sel_hi:[1,0]
	s_waitcnt vmcnt(22)
	v_lshlrev_b32_e32 v135, 16, v135
	v_pk_fma_f32 v[102:103], v[98:99], v[66:67], v[102:103] op_sel_hi:[1,0,1]
	v_lshlrev_b32_e32 v134, 16, v136
	v_pk_mul_f32 v[108:109], v[68:69], v[102:103] op_sel:[0,1] op_sel_hi:[1,0]
	s_waitcnt vmcnt(21)
	v_lshlrev_b32_e32 v136, 16, v137
	v_pk_fma_f32 v[108:109], v[102:103], v[66:67], v[108:109] op_sel_hi:[1,0,1]
	s_waitcnt vmcnt(20)
	v_lshlrev_b32_e32 v137, 16, v138
	v_pk_mul_f32 v[112:113], v[68:69], v[108:109] op_sel:[0,1] op_sel_hi:[1,0]
	s_waitcnt vmcnt(19)
	v_lshlrev_b32_e32 v138, 16, v139
	s_waitcnt vmcnt(18)
	v_lshlrev_b32_e32 v139, 16, v140
	s_waitcnt vmcnt(17)
	v_lshlrev_b32_e32 v140, 16, v141
	s_waitcnt vmcnt(16)
	v_lshlrev_b32_e32 v141, 16, v142
	v_pk_fma_f32 v[112:113], v[108:109], v[66:67], v[112:113] op_sel_hi:[1,0,1]
	v_pk_add_f32 v[142:143], v[126:127], 0 op_sel_hi:[1,0]
	v_pk_add_f32 v[144:145], v[128:129], 0 op_sel_hi:[1,0]
	v_pk_mul_f32 v[146:147], v[128:129], s[36:37]
	v_pk_add_f32 v[148:149], v[130:131], 0 op_sel_hi:[1,0]
	v_pk_mul_f32 v[150:151], v[130:131], s[16:17]
	v_pk_add_f32 v[152:153], v[132:133], 0 op_sel_hi:[1,0]
	v_pk_mul_f32 v[154:155], v[132:133], s[38:39]
	v_pk_add_f32 v[156:157], v[134:135], 0 op_sel_hi:[1,0]
	v_xor_b32_e32 v159, 0x80000000, v134
	v_mov_b32_e32 v158, v135
	v_pk_add_f32 v[134:135], v[136:137], 0 op_sel_hi:[1,0]
	v_pk_mul_f32 v[160:161], v[136:137], s[38:39]
	v_pk_add_f32 v[162:163], v[138:139], 0 op_sel_hi:[1,0]
	v_pk_mul_f32 v[164:165], v[138:139], s[16:17]
	v_pk_add_f32 v[166:167], v[140:141], 0 op_sel_hi:[1,0]
	v_pk_mul_f32 v[168:169], v[140:141], s[36:37]
	v_pk_mul_f32 v[116:117], v[68:69], v[112:113] op_sel:[0,1] op_sel_hi:[1,0]
	v_pk_fma_f32 v[128:129], v[128:129], s[6:7], v[146:147] op_sel:[0,0,1] op_sel_hi:[1,0,0]
	v_pk_fma_f32 v[130:131], v[130:131], s[10:11], v[150:151] op_sel:[0,0,1] op_sel_hi:[1,0,0]
	v_pk_fma_f32 v[132:133], v[132:133], s[14:15], v[154:155] op_sel:[0,0,1] op_sel_hi:[1,0,0]
	v_pk_fma_f32 v[136:137], v[136:137], s[4:5], v[160:161] op_sel:[0,0,1] op_sel_hi:[1,0,0]
	v_pk_fma_f32 v[138:139], v[138:139], s[8:9], v[164:165] op_sel:[0,0,1] op_sel_hi:[1,0,0]
	v_pk_fma_f32 v[140:141], v[140:141], s[12:13], v[168:169] op_sel:[0,0,1] op_sel_hi:[1,0,0]
	v_pk_add_f32 v[146:147], v[142:143], v[156:157]
	v_pk_add_f32 v[150:151], v[144:145], v[134:135]
	v_pk_add_f32 v[134:135], v[144:145], v[134:135] neg_lo:[0,1] neg_hi:[0,1]
	v_pk_add_f32 v[144:145], v[148:149], v[162:163]
	v_pk_add_f32 v[160:161], v[148:149], v[162:163] op_sel:[1,1] op_sel_hi:[0,0] neg_lo:[0,1] neg_hi:[1,0]
	v_pk_add_f32 v[154:155], v[152:153], v[166:167]
	v_pk_add_f32 v[152:153], v[152:153], v[166:167] neg_lo:[0,1] neg_hi:[0,1]
	v_pk_fma_f32 v[116:117], v[112:113], v[66:67], v[116:117] op_sel_hi:[1,0,1]
	v_pk_add_f32 v[142:143], v[142:143], v[156:157] neg_lo:[0,1] neg_hi:[0,1]
	v_pk_add_f32 v[156:157], v[158:159], v[126:127]
	v_pk_add_f32 v[126:127], v[126:127], v[158:159] neg_lo:[0,1] neg_hi:[0,1]
	v_pk_mul_f32 v[158:159], v[134:135], s[16:17]
	v_pk_mul_f32 v[148:149], v[152:153], s[16:17]
	v_pk_add_f32 v[162:163], v[128:129], v[136:137]
	v_pk_add_f32 v[128:129], v[128:129], v[136:137] neg_lo:[0,1] neg_hi:[0,1]
	v_pk_add_f32 v[136:137], v[130:131], v[138:139]
	v_pk_add_f32 v[130:131], v[130:131], v[138:139] neg_lo:[0,1] neg_hi:[0,1]
	v_pk_add_f32 v[138:139], v[132:133], v[140:141]
	v_pk_add_f32 v[132:133], v[132:133], v[140:141] neg_lo:[0,1] neg_hi:[0,1]
	v_pk_add_f32 v[140:141], v[146:147], v[144:145]
	v_pk_add_f32 v[144:145], v[146:147], v[144:145] neg_lo:[0,1] neg_hi:[0,1]
	v_pk_add_f32 v[146:147], v[150:151], v[154:155]
	v_pk_add_f32 v[150:151], v[150:151], v[154:155] neg_lo:[0,1] neg_hi:[0,1]
	v_pk_add_f32 v[96:97], v[94:95], 0 neg_lo:[1,1] neg_hi:[1,1]
	v_pk_mul_f32 v[120:121], v[68:69], v[116:117] op_sel:[0,1] op_sel_hi:[1,0]
	v_pk_fma_f32 v[134:135], v[134:135], s[10:11], v[158:159] op_sel:[0,0,1] op_sel_hi:[1,0,0]
	v_pk_fma_f32 v[148:149], v[152:153], s[8:9], v[148:149] op_sel:[0,0,1] op_sel_hi:[1,0,0]
	v_pk_mul_f32 v[152:153], v[128:129], s[16:17]
	v_xor_b32_e32 v155, 0x80000000, v130
	v_mov_b32_e32 v154, v131
	v_pk_mul_f32 v[130:131], v[132:133], s[16:17]
	v_xor_b32_e32 v159, 0x80000000, v150
	v_mov_b32_e32 v158, v151
	v_pk_add_f32 v[150:151], v[142:143], v[160:161]
	v_pk_add_f32 v[142:143], v[142:143], v[160:161] neg_lo:[0,1] neg_hi:[0,1]
	v_pk_add_f32 v[160:161], v[156:157], v[136:137]
	v_pk_add_f32 v[136:137], v[156:157], v[136:137] neg_lo:[0,1] neg_hi:[0,1]
	v_pk_add_f32 v[156:157], v[162:163], v[138:139]
	v_pk_add_f32 v[138:139], v[162:163], v[138:139] neg_lo:[0,1] neg_hi:[0,1]
	v_mov_b32_e32 v0, v67
	v_pk_add_f32 v[72:73], v[70:71], 0 neg_lo:[1,1] neg_hi:[1,1]
	v_pk_add_f32 v[80:81], v[78:79], 0 neg_lo:[1,1] neg_hi:[1,1]
	v_mov_b32_e32 v96, v95
	v_pk_add_f32 v[100:101], v[98:99], 0 neg_lo:[1,1] neg_hi:[1,1]
	v_pk_add_f32 v[114:115], v[112:113], 0 neg_lo:[1,1] neg_hi:[1,1]
	v_pk_fma_f32 v[120:121], v[116:117], v[66:67], v[120:121] op_sel_hi:[1,0,1]
	v_pk_add_f32 v[162:163], v[140:141], v[146:147]
	v_pk_add_f32 v[140:141], v[140:141], v[146:147] neg_lo:[0,1] neg_hi:[0,1]
	v_pk_fma_f32 v[128:129], v[128:129], s[10:11], v[152:153] op_sel:[0,0,1] op_sel_hi:[1,0,0]
	v_pk_fma_f32 v[130:131], v[132:133], s[8:9], v[130:131] op_sel:[0,0,1] op_sel_hi:[1,0,0]
	v_pk_add_f32 v[132:133], v[134:135], v[148:149]
	v_pk_add_f32 v[134:135], v[134:135], v[148:149] neg_lo:[0,1] neg_hi:[0,1]
	v_xor_b32_e32 v147, 0x80000000, v138
	v_mov_b32_e32 v146, v139
	v_pk_add_f32 v[152:153], v[160:161], v[156:157]
	v_mov_b32_e32 v72, v71
	v_pk_add_f32 v[76:77], v[74:75], 0 neg_lo:[1,1] neg_hi:[1,1]
	v_mov_b32_e32 v80, v79
	v_pk_add_f32 v[84:85], v[82:83], 0 neg_lo:[1,1] neg_hi:[1,1]
	v_mov_b32_e32 v100, v99
	v_pk_add_f32 v[106:107], v[102:103], 0 neg_lo:[1,1] neg_hi:[1,1]
	v_mov_b32_e32 v114, v113
	v_pk_mul_f32 v[68:69], v[68:69], v[120:121] op_sel:[0,1] op_sel_hi:[1,0]
	v_pk_add_f32 v[138:139], v[126:127], v[154:155]
	v_pk_add_f32 v[126:127], v[126:127], v[154:155] neg_lo:[0,1] neg_hi:[0,1]
	v_pk_add_f32 v[148:149], v[144:145], v[158:159]
	v_pk_add_f32 v[144:145], v[144:145], v[158:159] neg_lo:[0,1] neg_hi:[0,1]
	v_pk_add_f32 v[154:155], v[160:161], v[156:157] neg_lo:[0,1] neg_hi:[0,1]
	v_pk_mul_f32 v[96:97], v[140:141], v[96:97] op_sel:[1,0] op_sel_hi:[0,1]
	v_xor_b32_e32 v157, 0x80000000, v134
	v_mov_b32_e32 v156, v135
	v_pk_add_f32 v[134:135], v[128:129], v[130:131]
	v_pk_add_f32 v[128:129], v[128:129], v[130:131] neg_lo:[0,1] neg_hi:[0,1]
	v_pk_add_f32 v[130:131], v[150:151], v[132:133]
	v_pk_add_f32 v[132:133], v[150:151], v[132:133] neg_lo:[0,1] neg_hi:[0,1]
	v_pk_add_f32 v[150:151], v[136:137], v[146:147]
	v_pk_add_f32 v[136:137], v[136:137], v[146:147] neg_lo:[0,1] neg_hi:[0,1]
	v_pk_mul_f32 v[146:147], v[0:1], v[152:153] op_sel:[0,1] op_sel_hi:[0,0] neg_hi:[1,0]
	v_mov_b32_e32 v76, v75
	v_mov_b32_e32 v84, v83
	v_pk_add_f32 v[88:89], v[86:87], 0 neg_lo:[1,1] neg_hi:[1,1]
	v_pk_add_f32 v[92:93], v[90:91], 0 neg_lo:[1,1] neg_hi:[1,1]
	v_mov_b32_e32 v106, v103
	v_pk_fma_f32 v[68:69], v[120:121], v[66:67], v[68:69] op_sel_hi:[1,0,1]
	v_pk_mul_f32 v[80:81], v[148:149], v[80:81] op_sel:[1,0] op_sel_hi:[0,1]
	v_pk_fma_f32 v[94:95], v[140:141], v[94:95], v[96:97] op_sel_hi:[1,0,1]
	v_pk_mul_f32 v[96:97], v[154:155], v[100:101] op_sel:[1,0] op_sel_hi:[0,1]
	v_pk_mul_f32 v[100:101], v[144:145], v[114:115] op_sel:[1,0] op_sel_hi:[0,1]
	v_xor_b32_e32 v115, 0x80000000, v128
	v_mov_b32_e32 v114, v129
	v_pk_add_f32 v[128:129], v[142:143], v[156:157]
	v_pk_add_f32 v[140:141], v[142:143], v[156:157] neg_lo:[0,1] neg_hi:[0,1]
	v_pk_add_f32 v[142:143], v[138:139], v[134:135]
	v_pk_fma_f32 v[66:67], v[152:153], v[66:67], v[146:147] op_sel_hi:[1,0,1]
	v_pk_mul_f32 v[72:73], v[130:131], v[72:73] op_sel:[1,0] op_sel_hi:[0,1]
	v_mov_b32_e32 v88, v87
	v_mov_b32_e32 v92, v91
	v_pk_add_f32 v[110:111], v[108:109], 0 neg_lo:[1,1] neg_hi:[1,1]
	v_pk_add_f32 v[118:119], v[116:117], 0 neg_lo:[1,1] neg_hi:[1,1]
	v_pk_add_f32 v[122:123], v[120:121], 0 neg_lo:[1,1] neg_hi:[1,1]
	v_pk_add_f32 v[124:125], v[68:69], 0 neg_lo:[1,1] neg_hi:[1,1]
	ds_write_b64 v171, v[162:163]
	v_pk_fma_f32 v[78:79], v[148:149], v[78:79], v[80:81] op_sel_hi:[1,0,1]
	v_pk_mul_f32 v[80:81], v[150:151], v[84:85] op_sel:[1,0] op_sel_hi:[0,1]
	v_pk_fma_f32 v[84:85], v[154:155], v[98:99], v[96:97] op_sel_hi:[1,0,1]
	v_pk_mul_f32 v[96:97], v[132:133], v[106:107] op_sel:[1,0] op_sel_hi:[0,1]
	v_pk_add_f32 v[106:107], v[126:127], v[114:115]
	ds_write_b64 v172, v[66:67] offset:8192
	v_pk_fma_f32 v[66:67], v[130:131], v[70:71], v[72:73] op_sel_hi:[1,0,1]
	v_pk_mul_f32 v[70:71], v[142:143], v[76:77] op_sel:[1,0] op_sel_hi:[0,1]
	v_mov_b32_e32 v110, v109
	v_mov_b32_e32 v118, v117
	v_mov_b32_e32 v122, v121
	v_mov_b32_e32 v124, v69
	v_pk_add_f32 v[134:135], v[138:139], v[134:135] neg_lo:[0,1] neg_hi:[0,1]
	v_pk_fma_f32 v[98:99], v[144:145], v[112:113], v[100:101] op_sel_hi:[1,0,1]
	v_pk_add_f32 v[112:113], v[126:127], v[114:115] neg_lo:[0,1] neg_hi:[0,1]
	v_pk_mul_f32 v[76:77], v[128:129], v[88:89] op_sel:[1,0] op_sel_hi:[0,1]
	ds_write_b64 v173, v[66:67] offset:16384
	v_pk_fma_f32 v[66:67], v[142:143], v[74:75], v[70:71] op_sel_hi:[1,0,1]
	v_pk_mul_f32 v[74:75], v[106:107], v[92:93] op_sel:[1,0] op_sel_hi:[0,1]
	s_mov_b64 s[48:49], 0
	s_and_b64 vcc, exec, vcc
	v_pk_mul_f32 v[100:101], v[136:137], v[118:119] op_sel:[1,0] op_sel_hi:[0,1]
	v_pk_fma_f32 v[72:73], v[150:151], v[82:83], v[80:81] op_sel_hi:[1,0,1]
	v_pk_fma_f32 v[80:81], v[132:133], v[102:103], v[96:97] op_sel_hi:[1,0,1]
	v_pk_mul_f32 v[82:83], v[134:135], v[110:111] op_sel:[1,0] op_sel_hi:[0,1]
	v_pk_mul_f32 v[96:97], v[140:141], v[122:123] op_sel:[1,0] op_sel_hi:[0,1]
	v_pk_fma_f32 v[70:71], v[128:129], v[86:87], v[76:77] op_sel_hi:[1,0,1]
	v_pk_mul_f32 v[86:87], v[112:113], v[124:125] op_sel:[1,0] op_sel_hi:[0,1]
	ds_write_b64 v174, v[66:67] offset:24576
	ds_write_b64 v175, v[78:79] offset:32768
	ds_write_b64 v176, v[72:73] offset:40960
	ds_write_b64 v177, v[70:71] offset:49152
	v_pk_fma_f32 v[66:67], v[106:107], v[90:91], v[74:75] op_sel_hi:[1,0,1]
	v_pk_fma_f32 v[88:89], v[136:137], v[116:117], v[100:101] op_sel_hi:[1,0,1]
	v_pk_fma_f32 v[76:77], v[134:135], v[108:109], v[82:83] op_sel_hi:[1,0,1]
	v_pk_fma_f32 v[82:83], v[140:141], v[120:121], v[96:97] op_sel_hi:[1,0,1]
	v_pk_fma_f32 v[68:69], v[112:113], v[68:69], v[86:87] op_sel_hi:[1,0,1]
	ds_write_b64 v178, v[66:67] offset:57344
	ds_write_b64 v179, v[94:95]
	ds_write_b64 v180, v[84:85]
	ds_write_b64 v181, v[80:81]
	ds_write_b64 v182, v[76:77]
	ds_write_b64 v183, v[98:99]
	ds_write_b64 v184, v[88:89]
	ds_write_b64 v185, v[82:83]
	ds_write_b64 v186, v[68:69]
	s_cbranch_vccz .LBB0_362
	s_waitcnt lgkmcnt(0)
	s_barrier
	v_mov_b32 v0, 0
	s_mov_b32 s5, s14
	v_add_u32_e32 v74, v0, v170
	v_lshlrev_b32_e32 v0, 5, v74
	v_and_b32_e32 v71, 0xfffffc00, v0
	v_or_b32_e32 v75, 0x80, v71
	v_and_b32_e32 v70, 31, v74
	v_ashrrev_i32_e32 v75, 2, v75
	v_lshlrev_b32_e32 v78, 3, v71
	v_lshlrev_b32_e32 v79, 3, v70
	v_add_u32_e32 v75, 0, v75
	v_add3_u32 v111, v75, v78, v79
	v_or_b32_e32 v75, 0xa0, v71
	v_ashrrev_i32_e32 v75, 2, v75
	v_add_u32_e32 v75, 0, v75
	v_add3_u32 v110, v75, v78, v79
	v_or_b32_e32 v75, 0xc0, v71
	v_ashrrev_i32_e32 v75, 2, v75
	v_add_u32_e32 v75, 0, v75
	v_add3_u32 v109, v75, v78, v79
	v_or_b32_e32 v75, 0xe0, v71
	v_ashrrev_i32_e32 v75, 2, v75
	v_add_u32_e32 v75, 0, v75
	v_add3_u32 v108, v75, v78, v79
	v_or_b32_e32 v75, 0x100, v71
	v_ashrrev_i32_e32 v75, 2, v75
	v_add_u32_e32 v75, 0, v75
	v_add3_u32 v107, v75, v78, v79
	v_or_b32_e32 v75, 0x120, v71
	v_ashrrev_i32_e32 v75, 2, v75
	v_add_u32_e32 v75, 0, v75
	v_add3_u32 v106, v75, v78, v79
	v_or_b32_e32 v75, 0x140, v71
	v_ashrrev_i32_e32 v75, 2, v75
	v_add_u32_e32 v75, 0, v75
	v_add3_u32 v105, v75, v78, v79
	v_or_b32_e32 v75, 0x160, v71
	v_ashrrev_i32_e32 v75, 2, v75
	v_add_u32_e32 v75, 0, v75
	v_add3_u32 v103, v75, v78, v79
	v_or_b32_e32 v75, 0x180, v71
	v_ashrrev_i32_e32 v75, 2, v75
	v_add_u32_e32 v75, 0, v75
	v_add3_u32 v102, v75, v78, v79
	v_or_b32_e32 v75, 0x1a0, v71
	v_ashrrev_i32_e32 v75, 2, v75
	v_add_u32_e32 v75, 0, v75
	v_add3_u32 v101, v75, v78, v79
	v_or_b32_e32 v75, 0x1c0, v71
	v_ashrrev_i32_e32 v75, 2, v75
	v_add_u32_e32 v75, 0, v75
	v_add3_u32 v100, v75, v78, v79
	v_or_b32_e32 v75, 0x1e0, v71
	v_ashrrev_i32_e32 v75, 2, v75
	v_add_u32_e32 v75, 0, v75
	v_add3_u32 v99, v75, v78, v79
	v_or_b32_e32 v75, 0x200, v71
	v_ashrrev_i32_e32 v75, 2, v75
	v_add_u32_e32 v75, 0, v75
	v_add3_u32 v98, v75, v78, v79
	v_or_b32_e32 v75, 0x220, v71
	v_ashrrev_i32_e32 v75, 2, v75
	v_add_u32_e32 v75, 0, v75
	v_add3_u32 v97, v75, v78, v79
	v_or_b32_e32 v75, 0x240, v71
	v_ashrrev_i32_e32 v75, 2, v75
	v_add_u32_e32 v75, 0, v75
	v_add3_u32 v96, v75, v78, v79
	v_or_b32_e32 v75, 0x260, v71
	v_ashrrev_i32_e32 v75, 2, v75
	v_add_u32_e32 v75, 0, v75
	v_add3_u32 v95, v75, v78, v79
	v_or_b32_e32 v75, 0x280, v71
	v_or_b32_e32 v67, 32, v71
	v_ashrrev_i32_e32 v75, 2, v75
	v_ashrrev_i32_e32 v67, 2, v67
	v_add_u32_e32 v75, 0, v75
	v_add_u32_e32 v67, 0, v67
	v_add3_u32 v94, v75, v78, v79
	v_or_b32_e32 v75, 0x2a0, v71
	v_add3_u32 v114, v67, v78, v79
	v_or_b32_e32 v67, 64, v71
	v_ashrrev_i32_e32 v75, 2, v75
	v_ashrrev_i32_e32 v67, 2, v67
	v_add_u32_e32 v75, 0, v75
	v_add_u32_e32 v67, 0, v67
	v_add3_u32 v93, v75, v78, v79
	v_or_b32_e32 v75, 0x2c0, v71
	v_ashrrev_i32_e32 v66, 2, v71
	v_add3_u32 v113, v67, v78, v79
	v_or_b32_e32 v67, 0x60, v71
	v_ashrrev_i32_e32 v75, 2, v75
	v_add_u32_e32 v66, 0, v66
	v_ashrrev_i32_e32 v67, 2, v67
	v_add_u32_e32 v75, 0, v75
	v_add3_u32 v66, v66, v78, v79
	v_add_u32_e32 v67, 0, v67
	v_add3_u32 v92, v75, v78, v79
	v_or_b32_e32 v75, 0x2e0, v71
	v_add3_u32 v112, v67, v78, v79
	ds_read_b64 v[66:67], v66
	ds_read_b64 v[68:69], v114 offset:256
	ds_read_b64 v[72:73], v113 offset:512
	ds_read_b64 v[76:77], v112 offset:768
	ds_read_b64 v[80:81], v111 offset:1024
	ds_read_b64 v[82:83], v110 offset:1280
	ds_read_b64 v[116:117], v109 offset:1536
	ds_read_b64 v[118:119], v108 offset:1792
	ds_read_b64 v[120:121], v107 offset:2048
	ds_read_b64 v[122:123], v106 offset:2304
	ds_read_b64 v[124:125], v105 offset:2560
	ds_read_b64 v[126:127], v103 offset:2816
	ds_read_b64 v[128:129], v102 offset:3072
	ds_read_b64 v[130:131], v101 offset:3328
	ds_read_b64 v[132:133], v100 offset:3584
	ds_read_b64 v[134:135], v99 offset:3840
	ds_read_b64 v[136:137], v98 offset:4096
	ds_read_b64 v[138:139], v97 offset:4352
	ds_read_b64 v[140:141], v96 offset:4608
	ds_read_b64 v[142:143], v95 offset:4864
	v_ashrrev_i32_e32 v75, 2, v75
	v_add_u32_e32 v75, 0, v75
	v_add3_u32 v91, v75, v78, v79
	v_or_b32_e32 v75, 0x300, v71
	v_ashrrev_i32_e32 v75, 2, v75
	s_waitcnt lgkmcnt(3)
	v_pk_add_f32 v[168:169], v[66:67], v[136:137]
	v_pk_add_f32 v[66:67], v[66:67], v[136:137] neg_lo:[0,1] neg_hi:[0,1]
	s_waitcnt lgkmcnt(2)
	v_pk_add_f32 v[136:137], v[68:69], v[138:139]
	v_pk_add_f32 v[68:69], v[68:69], v[138:139] neg_lo:[0,1] neg_hi:[0,1]
	v_add_u32_e32 v75, 0, v75
	v_pk_mul_f32 v[138:139], v[68:69], s[18:19]
	v_add3_u32 v90, v75, v78, v79
	v_or_b32_e32 v75, 0x320, v71
	v_pk_fma_f32 v[68:69], v[68:69], s[20:21], v[138:139] op_sel:[0,0,1] op_sel_hi:[1,0,0]
	s_waitcnt lgkmcnt(1)
	v_pk_add_f32 v[138:139], v[72:73], v[140:141]
	v_pk_add_f32 v[72:73], v[72:73], v[140:141] neg_lo:[0,1] neg_hi:[0,1]
	v_ashrrev_i32_e32 v75, 2, v75
	v_pk_mul_f32 v[140:141], v[72:73], s[4:5]
	ds_read_b64 v[144:145], v94 offset:5120
	ds_read_b64 v[146:147], v93 offset:5376
	ds_read_b64 v[148:149], v92 offset:5632
	ds_read_b64 v[150:151], v91 offset:5888
	v_add_u32_e32 v75, 0, v75
	v_pk_fma_f32 v[72:73], v[72:73], s[6:7], v[140:141] op_sel:[0,0,1] op_sel_hi:[1,0,0]
	s_waitcnt lgkmcnt(4)
	v_pk_add_f32 v[140:141], v[76:77], v[142:143]
	v_pk_add_f32 v[76:77], v[76:77], v[142:143] neg_lo:[0,1] neg_hi:[0,1]
	v_add3_u32 v89, v75, v78, v79
	v_or_b32_e32 v75, 0x340, v71
	v_pk_mul_f32 v[142:143], v[76:77], s[22:23]
	v_ashrrev_i32_e32 v75, 2, v75
	v_pk_fma_f32 v[76:77], v[76:77], s[24:25], v[142:143] op_sel:[0,0,1] op_sel_hi:[1,0,0]
	s_waitcnt lgkmcnt(3)
	v_pk_add_f32 v[142:143], v[80:81], v[144:145]
	v_pk_add_f32 v[80:81], v[80:81], v[144:145] neg_lo:[0,1] neg_hi:[0,1]
	s_mov_b32 s9, s10
	v_add_u32_e32 v75, 0, v75
	v_pk_mul_f32 v[144:145], v[80:81], s[8:9]
	v_add3_u32 v88, v75, v78, v79
	v_or_b32_e32 v75, 0x360, v71
	v_pk_fma_f32 v[80:81], v[80:81], s[10:11], v[144:145] op_sel:[0,0,1] op_sel_hi:[1,0,0]
	s_waitcnt lgkmcnt(2)
	v_pk_add_f32 v[144:145], v[82:83], v[146:147]
	v_pk_add_f32 v[82:83], v[82:83], v[146:147] neg_lo:[0,1] neg_hi:[0,1]
	s_mov_b32 s27, s24
	v_ashrrev_i32_e32 v75, 2, v75
	v_pk_mul_f32 v[146:147], v[82:83], s[26:27]
	s_mov_b32 s0, s23
	v_add_u32_e32 v75, 0, v75
	v_pk_fma_f32 v[82:83], v[82:83], s[0:1], v[146:147] op_sel:[0,0,1] op_sel_hi:[1,0,0]
	s_waitcnt lgkmcnt(1)
	v_pk_add_f32 v[146:147], v[116:117], v[148:149]
	v_pk_add_f32 v[116:117], v[116:117], v[148:149] neg_lo:[0,1] neg_hi:[0,1]
	s_mov_b32 s13, s6
	v_add3_u32 v87, v75, v78, v79
	v_or_b32_e32 v75, 0x380, v71
	v_pk_mul_f32 v[148:149], v[116:117], s[12:13]
	ds_read_b64 v[152:153], v90 offset:6144
	ds_read_b64 v[154:155], v89 offset:6400
	ds_read_b64 v[156:157], v88 offset:6656
	ds_read_b64 v[158:159], v87 offset:6912
	v_ashrrev_i32_e32 v75, 2, v75
	v_pk_fma_f32 v[116:117], v[116:117], s[14:15], v[148:149] op_sel:[0,0,1] op_sel_hi:[1,0,0]
	s_waitcnt lgkmcnt(4)
	v_pk_add_f32 v[148:149], v[118:119], v[150:151]
	v_pk_add_f32 v[118:119], v[118:119], v[150:151] neg_lo:[0,1] neg_hi:[0,1]
	s_mov_b32 s35, s20
	v_add_u32_e32 v75, 0, v75
	v_pk_mul_f32 v[150:151], v[118:119], s[34:35]
	s_mov_b32 s48, s19
	v_add3_u32 v86, v75, v78, v79
	v_or_b32_e32 v75, 0x3a0, v71
	v_or_b32_e32 v71, 0x3c0, v71
	v_pk_fma_f32 v[118:119], v[118:119], s[48:49], v[150:151] op_sel:[0,0,1] op_sel_hi:[1,0,0]
	s_waitcnt lgkmcnt(3)
	v_pk_add_f32 v[150:151], v[120:121], v[152:153]
	v_pk_add_f32 v[152:153], v[120:121], v[152:153] op_sel:[1,1] op_sel_hi:[0,0] neg_lo:[0,1] neg_hi:[1,0]
	v_ashrrev_i32_e32 v71, 2, v71
	s_waitcnt lgkmcnt(2)
	v_pk_add_f32 v[120:121], v[122:123], v[154:155]
	v_pk_add_f32 v[122:123], v[122:123], v[154:155] neg_lo:[0,1] neg_hi:[0,1]
	v_add_u32_e32 v71, 0, v71
	v_or_b32_e32 v0, 0x3e0, v0
	v_pk_mul_f32 v[154:155], v[122:123], s[34:35]
	v_ashrrev_i32_e32 v75, 2, v75
	v_add3_u32 v84, v71, v78, v79
	v_ashrrev_i32_e32 v71, 2, v0
	v_pk_fma_f32 v[122:123], v[122:123], s[18:19], v[154:155] op_sel:[0,0,1] op_sel_hi:[1,0,0]
	s_waitcnt lgkmcnt(1)
	v_pk_add_f32 v[154:155], v[124:125], v[156:157]
	v_pk_add_f32 v[124:125], v[124:125], v[156:157] neg_lo:[0,1] neg_hi:[0,1]
	v_add_u32_e32 v75, 0, v75
	v_add_u32_e32 v71, 0, v71
	v_lshlrev_b32_e32 v0, 3, v0
	v_pk_mul_f32 v[156:157], v[124:125], s[12:13]
	v_add3_u32 v85, v75, v78, v79
	v_add3_u32 v0, v71, v0, v79
	ds_read_b64 v[160:161], v86 offset:7168
	ds_read_b64 v[162:163], v85 offset:7424
	ds_read_b64 v[164:165], v84 offset:7680
	ds_read_b64 v[166:167], v0
	v_pk_fma_f32 v[124:125], v[124:125], s[4:5], v[156:157] op_sel:[0,0,1] op_sel_hi:[1,0,0]
	s_waitcnt lgkmcnt(4)
	v_pk_add_f32 v[156:157], v[126:127], v[158:159]
	v_pk_add_f32 v[126:127], v[126:127], v[158:159] neg_lo:[0,1] neg_hi:[0,1]
	v_lshlrev_b32_e32 v70, 4, v70
	v_pk_mul_f32 v[158:159], v[126:127], s[26:27]
	v_cvt_f32_u32_e32 v75, v70
	v_pk_fma_f32 v[126:127], v[126:127], s[22:23], v[158:159] op_sel:[0,0,1] op_sel_hi:[1,0,0]
	s_waitcnt lgkmcnt(3)
	v_pk_add_f32 v[158:159], v[128:129], v[160:161]
	v_pk_add_f32 v[128:129], v[128:129], v[160:161] neg_lo:[0,1] neg_hi:[0,1]
	v_and_b32_e32 v74, 0x1fffffe0, v74
	v_pk_mul_f32 v[160:161], v[128:129], s[8:9]
	v_mul_f32_e32 v115, 0x38800000, v75
	v_pk_fma_f32 v[128:129], v[128:129], s[8:9], v[160:161] op_sel:[0,0,1] op_sel_hi:[1,0,0]
	s_waitcnt lgkmcnt(2)
	v_pk_add_f32 v[160:161], v[130:131], v[162:163]
	v_pk_add_f32 v[130:131], v[130:131], v[162:163] neg_lo:[0,1] neg_hi:[0,1]
	v_lshl_add_u32 v74, v74, 3, 0
	v_pk_mul_f32 v[162:163], v[130:131], s[22:23]
	v_sin_f32_e32 v75, v115
	v_pk_fma_f32 v[130:131], v[130:131], s[26:27], v[162:163] op_sel:[0,0,1] op_sel_hi:[1,0,0]
	s_waitcnt lgkmcnt(1)
	v_pk_add_f32 v[162:163], v[132:133], v[164:165]
	v_pk_add_f32 v[132:133], v[132:133], v[164:165] neg_lo:[0,1] neg_hi:[0,1]
	v_add3_u32 v74, v74, v78, v79
	v_pk_mul_f32 v[164:165], v[132:133], s[4:5]
	v_xor_b32_e32 v78, 0x80000000, v75
	v_pk_fma_f32 v[132:133], v[132:133], s[12:13], v[164:165] op_sel:[0,0,1] op_sel_hi:[1,0,0]
	s_waitcnt lgkmcnt(0)
	v_pk_add_f32 v[164:165], v[134:135], v[166:167]
	v_pk_add_f32 v[134:135], v[134:135], v[166:167] neg_lo:[0,1] neg_hi:[0,1]
	v_mov_b32_e32 v79, v75
	v_pk_mul_f32 v[166:167], v[134:135], s[18:19]
	s_mov_b32 s50, s19
	v_pk_fma_f32 v[134:135], v[134:135], s[34:35], v[166:167] op_sel:[0,0,1] op_sel_hi:[1,0,0]
	v_pk_add_f32 v[166:167], v[168:169], v[150:151]
	v_pk_add_f32 v[150:151], v[168:169], v[150:151] neg_lo:[0,1] neg_hi:[0,1]
	v_pk_add_f32 v[168:169], v[136:137], v[120:121]
	v_pk_add_f32 v[120:121], v[136:137], v[120:121] neg_lo:[0,1] neg_hi:[0,1]
	s_mov_b32 s51, s18
	v_pk_mul_f32 v[136:137], v[120:121], s[4:5]
	s_mov_b32 s52, s23
	v_pk_fma_f32 v[120:121], v[120:121], s[6:7], v[136:137] op_sel:[0,0,1] op_sel_hi:[1,0,0]
	v_pk_add_f32 v[136:137], v[138:139], v[154:155]
	v_pk_add_f32 v[138:139], v[138:139], v[154:155] neg_lo:[0,1] neg_hi:[0,1]
	s_mov_b32 s53, s22
	v_pk_mul_f32 v[154:155], v[138:139], s[8:9]
	s_nop 0
	v_pk_fma_f32 v[138:139], v[138:139], s[10:11], v[154:155] op_sel:[0,0,1] op_sel_hi:[1,0,0]
	v_pk_add_f32 v[154:155], v[140:141], v[156:157]
	v_pk_add_f32 v[140:141], v[140:141], v[156:157] neg_lo:[0,1] neg_hi:[0,1]
	s_nop 0
	v_pk_mul_f32 v[156:157], v[140:141], s[12:13]
	s_nop 0
	v_pk_fma_f32 v[140:141], v[140:141], s[14:15], v[156:157] op_sel:[0,0,1] op_sel_hi:[1,0,0]
	v_pk_add_f32 v[156:157], v[142:143], v[158:159]
	v_pk_add_f32 v[158:159], v[142:143], v[158:159] op_sel:[1,1] op_sel_hi:[0,0] neg_lo:[0,1] neg_hi:[1,0]
	s_nop 0
	v_pk_add_f32 v[142:143], v[144:145], v[160:161]
	v_pk_add_f32 v[144:145], v[144:145], v[160:161] neg_lo:[0,1] neg_hi:[0,1]
	s_nop 0
	v_pk_mul_f32 v[160:161], v[144:145], s[12:13]
	s_nop 0
	v_pk_fma_f32 v[144:145], v[144:145], s[4:5], v[160:161] op_sel:[0,0,1] op_sel_hi:[1,0,0]
	v_pk_add_f32 v[160:161], v[146:147], v[162:163]
	v_pk_add_f32 v[146:147], v[146:147], v[162:163] neg_lo:[0,1] neg_hi:[0,1]
	s_nop 0
	v_pk_mul_f32 v[162:163], v[146:147], s[8:9]
	s_nop 0
	v_pk_fma_f32 v[146:147], v[146:147], s[8:9], v[162:163] op_sel:[0,0,1] op_sel_hi:[1,0,0]
	v_pk_add_f32 v[162:163], v[148:149], v[164:165]
	v_pk_add_f32 v[148:149], v[148:149], v[164:165] neg_lo:[0,1] neg_hi:[0,1]
	s_nop 0
	v_pk_mul_f32 v[164:165], v[148:149], s[4:5]
	s_nop 0
	v_pk_fma_f32 v[148:149], v[148:149], s[12:13], v[164:165] op_sel:[0,0,1] op_sel_hi:[1,0,0]
	v_pk_add_f32 v[164:165], v[66:67], v[152:153]
	v_pk_add_f32 v[66:67], v[66:67], v[152:153] neg_lo:[0,1] neg_hi:[0,1]
	v_pk_add_f32 v[152:153], v[68:69], v[122:123]
	v_pk_add_f32 v[68:69], v[68:69], v[122:123] neg_lo:[0,1] neg_hi:[0,1]
	s_nop 0
	v_pk_mul_f32 v[122:123], v[68:69], s[4:5]
	s_nop 0
	v_pk_fma_f32 v[68:69], v[68:69], s[6:7], v[122:123] op_sel:[0,0,1] op_sel_hi:[1,0,0]
	v_pk_add_f32 v[122:123], v[72:73], v[124:125]
	v_pk_add_f32 v[72:73], v[72:73], v[124:125] neg_lo:[0,1] neg_hi:[0,1]
	s_nop 0
	v_pk_mul_f32 v[124:125], v[72:73], s[8:9]
	s_nop 0
	v_pk_fma_f32 v[72:73], v[72:73], s[10:11], v[124:125] op_sel:[0,0,1] op_sel_hi:[1,0,0]
	v_pk_add_f32 v[124:125], v[76:77], v[126:127]
	v_pk_add_f32 v[76:77], v[76:77], v[126:127] neg_lo:[0,1] neg_hi:[0,1]
	s_nop 0
	v_pk_mul_f32 v[126:127], v[76:77], s[12:13]
	s_nop 0
	v_pk_fma_f32 v[76:77], v[76:77], s[14:15], v[126:127] op_sel:[0,0,1] op_sel_hi:[1,0,0]
	v_pk_add_f32 v[126:127], v[80:81], v[128:129]
	v_pk_add_f32 v[128:129], v[80:81], v[128:129] op_sel:[1,1] op_sel_hi:[0,0] neg_lo:[0,1] neg_hi:[1,0]
	s_nop 0
	v_pk_add_f32 v[80:81], v[82:83], v[130:131]
	v_pk_add_f32 v[82:83], v[82:83], v[130:131] neg_lo:[0,1] neg_hi:[0,1]
	s_nop 0
	v_pk_mul_f32 v[130:131], v[82:83], s[12:13]
	s_nop 0
	v_pk_fma_f32 v[82:83], v[82:83], s[4:5], v[130:131] op_sel:[0,0,1] op_sel_hi:[1,0,0]
	v_pk_add_f32 v[130:131], v[116:117], v[132:133]
	v_pk_add_f32 v[116:117], v[116:117], v[132:133] neg_lo:[0,1] neg_hi:[0,1]
	s_nop 0
	v_pk_mul_f32 v[132:133], v[116:117], s[8:9]
	s_nop 0
	v_pk_fma_f32 v[116:117], v[116:117], s[8:9], v[132:133] op_sel:[0,0,1] op_sel_hi:[1,0,0]
	v_pk_add_f32 v[132:133], v[118:119], v[134:135]
	v_pk_add_f32 v[118:119], v[118:119], v[134:135] neg_lo:[0,1] neg_hi:[0,1]
	s_nop 0
	v_pk_mul_f32 v[134:135], v[118:119], s[4:5]
	s_nop 0
	v_pk_fma_f32 v[118:119], v[118:119], s[12:13], v[134:135] op_sel:[0,0,1] op_sel_hi:[1,0,0]
	v_pk_add_f32 v[134:135], v[166:167], v[156:157]
	v_pk_add_f32 v[156:157], v[166:167], v[156:157] neg_lo:[0,1] neg_hi:[0,1]
	v_pk_add_f32 v[166:167], v[168:169], v[142:143]
	v_pk_add_f32 v[142:143], v[168:169], v[142:143] neg_lo:[0,1] neg_hi:[0,1]
	s_nop 0
	v_pk_mul_f32 v[168:169], v[142:143], s[8:9]
	s_nop 0
	v_pk_fma_f32 v[142:143], v[142:143], s[10:11], v[168:169] op_sel:[0,0,1] op_sel_hi:[1,0,0]
	v_pk_add_f32 v[168:169], v[136:137], v[160:161]
	v_pk_add_f32 v[160:161], v[136:137], v[160:161] op_sel:[1,1] op_sel_hi:[0,0] neg_lo:[0,1] neg_hi:[1,0]
	s_nop 0
	v_pk_add_f32 v[136:137], v[154:155], v[162:163]
	v_pk_add_f32 v[154:155], v[154:155], v[162:163] neg_lo:[0,1] neg_hi:[0,1]
	s_nop 0
	v_pk_mul_f32 v[162:163], v[154:155], s[8:9]
	s_nop 0
	v_pk_fma_f32 v[154:155], v[154:155], s[8:9], v[162:163] op_sel:[0,0,1] op_sel_hi:[1,0,0]
	v_pk_add_f32 v[162:163], v[150:151], v[158:159]
	v_pk_add_f32 v[150:151], v[150:151], v[158:159] neg_lo:[0,1] neg_hi:[0,1]
	v_pk_add_f32 v[158:159], v[120:121], v[144:145]
	v_pk_add_f32 v[120:121], v[120:121], v[144:145] neg_lo:[0,1] neg_hi:[0,1]
	s_nop 0
	v_pk_mul_f32 v[144:145], v[120:121], s[8:9]
	s_nop 0
	v_pk_fma_f32 v[120:121], v[120:121], s[10:11], v[144:145] op_sel:[0,0,1] op_sel_hi:[1,0,0]
	v_pk_add_f32 v[144:145], v[138:139], v[146:147]
	v_pk_add_f32 v[146:147], v[138:139], v[146:147] op_sel:[1,1] op_sel_hi:[0,0] neg_lo:[0,1] neg_hi:[1,0]
	s_nop 0
	v_pk_add_f32 v[138:139], v[140:141], v[148:149]
	v_pk_add_f32 v[140:141], v[140:141], v[148:149] neg_lo:[0,1] neg_hi:[0,1]
	s_nop 0
	v_pk_mul_f32 v[148:149], v[140:141], s[8:9]
	s_nop 0
	v_pk_fma_f32 v[140:141], v[140:141], s[8:9], v[148:149] op_sel:[0,0,1] op_sel_hi:[1,0,0]
	v_pk_add_f32 v[148:149], v[164:165], v[126:127]
	v_pk_add_f32 v[126:127], v[164:165], v[126:127] neg_lo:[0,1] neg_hi:[0,1]
	v_pk_add_f32 v[164:165], v[152:153], v[80:81]
	v_pk_add_f32 v[80:81], v[152:153], v[80:81] neg_lo:[0,1] neg_hi:[0,1]
	s_nop 0
	v_pk_mul_f32 v[152:153], v[80:81], s[8:9]
	s_nop 0
	v_pk_fma_f32 v[80:81], v[80:81], s[10:11], v[152:153] op_sel:[0,0,1] op_sel_hi:[1,0,0]
	v_pk_add_f32 v[152:153], v[122:123], v[130:131]
	v_pk_add_f32 v[130:131], v[122:123], v[130:131] op_sel:[1,1] op_sel_hi:[0,0] neg_lo:[0,1] neg_hi:[1,0]
	s_nop 0
	v_pk_add_f32 v[122:123], v[124:125], v[132:133]
	v_pk_add_f32 v[124:125], v[124:125], v[132:133] neg_lo:[0,1] neg_hi:[0,1]
	s_nop 0
	v_pk_mul_f32 v[132:133], v[124:125], s[8:9]
	s_nop 0
	v_pk_fma_f32 v[124:125], v[124:125], s[8:9], v[132:133] op_sel:[0,0,1] op_sel_hi:[1,0,0]
	v_pk_add_f32 v[132:133], v[66:67], v[128:129]
	v_pk_add_f32 v[66:67], v[66:67], v[128:129] neg_lo:[0,1] neg_hi:[0,1]
	v_pk_add_f32 v[128:129], v[68:69], v[82:83]
	v_pk_add_f32 v[68:69], v[68:69], v[82:83] neg_lo:[0,1] neg_hi:[0,1]
	s_nop 0
	v_pk_mul_f32 v[82:83], v[68:69], s[8:9]
	s_nop 0
	v_pk_fma_f32 v[68:69], v[68:69], s[10:11], v[82:83] op_sel:[0,0,1] op_sel_hi:[1,0,0]
	v_pk_add_f32 v[82:83], v[72:73], v[116:117]
	v_pk_add_f32 v[116:117], v[72:73], v[116:117] op_sel:[1,1] op_sel_hi:[0,0] neg_lo:[0,1] neg_hi:[1,0]
	s_nop 0
	v_pk_add_f32 v[72:73], v[76:77], v[118:119]
	v_pk_add_f32 v[76:77], v[76:77], v[118:119] neg_lo:[0,1] neg_hi:[0,1]
	v_pk_add_f32 v[174:175], v[66:67], v[116:117]
	v_pk_mul_f32 v[118:119], v[76:77], s[8:9]
	v_pk_add_f32 v[116:117], v[66:67], v[116:117] neg_lo:[0,1] neg_hi:[0,1]
	v_pk_fma_f32 v[76:77], v[76:77], s[8:9], v[118:119] op_sel:[0,0,1] op_sel_hi:[1,0,0]
	v_pk_add_f32 v[118:119], v[134:135], v[168:169]
	v_pk_add_f32 v[134:135], v[134:135], v[168:169] neg_lo:[0,1] neg_hi:[0,1]
	v_pk_add_f32 v[168:169], v[166:167], v[136:137]
	v_pk_add_f32 v[166:167], v[166:167], v[136:137] op_sel:[1,1] op_sel_hi:[0,0] neg_lo:[0,1] neg_hi:[1,0]
	v_pk_add_f32 v[180:181], v[118:119], v[168:169]
	v_pk_add_f32 v[136:137], v[156:157], v[160:161]
	v_pk_add_f32 v[156:157], v[156:157], v[160:161] neg_lo:[0,1] neg_hi:[0,1]
	v_pk_add_f32 v[160:161], v[142:143], v[154:155]
	v_pk_add_f32 v[154:155], v[142:143], v[154:155] op_sel:[1,1] op_sel_hi:[0,0] neg_lo:[0,1] neg_hi:[1,0]
	v_pk_add_f32 v[66:67], v[68:69], v[76:77] neg_lo:[0,1] neg_hi:[0,1]
	v_pk_add_f32 v[142:143], v[162:163], v[144:145]
	v_pk_add_f32 v[144:145], v[162:163], v[144:145] neg_lo:[0,1] neg_hi:[0,1]
	v_pk_add_f32 v[162:163], v[158:159], v[138:139]
	v_pk_add_f32 v[158:159], v[158:159], v[138:139] op_sel:[1,1] op_sel_hi:[0,0] neg_lo:[0,1] neg_hi:[1,0]
	ds_write_b64 v74, v[180:181]
	v_pk_add_f32 v[138:139], v[150:151], v[146:147]
	v_pk_add_f32 v[146:147], v[150:151], v[146:147] neg_lo:[0,1] neg_hi:[0,1]
	v_pk_add_f32 v[150:151], v[120:121], v[140:141]
	v_pk_add_f32 v[140:141], v[120:121], v[140:141] op_sel:[1,1] op_sel_hi:[0,0] neg_lo:[0,1] neg_hi:[1,0]
	v_cos_f32_e32 v74, v115
	v_pk_add_f32 v[120:121], v[148:149], v[152:153]
	v_pk_add_f32 v[148:149], v[148:149], v[152:153] neg_lo:[0,1] neg_hi:[0,1]
	v_pk_add_f32 v[152:153], v[164:165], v[122:123]
	v_pk_add_f32 v[164:165], v[164:165], v[122:123] op_sel:[1,1] op_sel_hi:[0,0] neg_lo:[0,1] neg_hi:[1,0]
	v_xor_b32_e32 v179, 0x80000000, v66
	v_pk_add_f32 v[122:123], v[126:127], v[130:131]
	v_pk_add_f32 v[126:127], v[126:127], v[130:131] neg_lo:[0,1] neg_hi:[0,1]
	v_pk_add_f32 v[130:131], v[80:81], v[124:125]
	v_pk_add_f32 v[124:125], v[80:81], v[124:125] op_sel:[1,1] op_sel_hi:[0,0] neg_lo:[0,1] neg_hi:[1,0]
	v_mov_b32_e32 v178, v67
	v_pk_add_f32 v[80:81], v[132:133], v[82:83]
	v_pk_add_f32 v[132:133], v[132:133], v[82:83] neg_lo:[0,1] neg_hi:[0,1]
	v_pk_add_f32 v[176:177], v[68:69], v[76:77]
	v_pk_add_f32 v[118:119], v[118:119], v[168:169] neg_lo:[0,1] neg_hi:[0,1]
	v_pk_add_f32 v[168:169], v[134:135], v[166:167]
	v_pk_add_f32 v[82:83], v[134:135], v[166:167] neg_lo:[0,1] neg_hi:[0,1]
	v_pk_add_f32 v[134:135], v[136:137], v[160:161]
	v_pk_add_f32 v[136:137], v[136:137], v[160:161] neg_lo:[0,1] neg_hi:[0,1]
	v_pk_add_f32 v[160:161], v[156:157], v[154:155]
	v_pk_add_f32 v[68:69], v[156:157], v[154:155] neg_lo:[0,1] neg_hi:[0,1]
	v_pk_add_f32 v[154:155], v[142:143], v[162:163]
	v_pk_add_f32 v[142:143], v[142:143], v[162:163] neg_lo:[0,1] neg_hi:[0,1]
	v_pk_add_f32 v[156:157], v[144:145], v[158:159]
	v_pk_add_f32 v[76:77], v[144:145], v[158:159] neg_lo:[0,1] neg_hi:[0,1]
	v_pk_add_f32 v[144:145], v[138:139], v[150:151]
	v_pk_add_f32 v[138:139], v[138:139], v[150:151] neg_lo:[0,1] neg_hi:[0,1]
	v_pk_add_f32 v[150:151], v[146:147], v[140:141]
	v_pk_add_f32 v[66:67], v[146:147], v[140:141] neg_lo:[0,1] neg_hi:[0,1]
	v_pk_add_f32 v[140:141], v[120:121], v[152:153]
	v_pk_add_f32 v[162:163], v[116:117], v[178:179]
	v_pk_add_f32 v[70:71], v[116:117], v[178:179] neg_lo:[0,1] neg_hi:[0,1]
	v_mov_b32_e32 v116, v75
	v_pk_mul_f32 v[116:117], v[116:117], v[140:141] op_sel:[0,1] op_sel_hi:[0,0] neg_hi:[1,0]
	v_pk_fma_f32 v[116:117], v[140:141], v[74:75], v[116:117] op_sel_hi:[1,0,1]
	ds_write_b64 v114, v[116:117] offset:256
	v_pk_mul_f32 v[114:115], v[78:79], v[74:75] op_sel:[0,1] op_sel_hi:[1,0]
	v_pk_add_f32 v[172:173], v[128:129], v[72:73]
	v_pk_fma_f32 v[114:115], v[74:75], v[74:75], v[114:115] op_sel_hi:[1,0,1]
	v_pk_add_f32 v[128:129], v[128:129], v[72:73] op_sel:[1,1] op_sel_hi:[0,0] neg_lo:[0,1] neg_hi:[1,0]
	v_pk_add_f32 v[116:117], v[114:115], 0 neg_lo:[1,1] neg_hi:[1,1]
	v_mov_b32_e32 v116, v115
	v_pk_mul_f32 v[116:117], v[116:117], v[154:155] op_sel:[0,1] op_sel_hi:[1,0]
	v_pk_fma_f32 v[116:117], v[154:155], v[114:115], v[116:117] op_sel_hi:[1,0,1]
	ds_write_b64 v113, v[116:117] offset:512
	v_pk_mul_f32 v[116:117], v[78:79], v[114:115] op_sel:[0,1] op_sel_hi:[1,0]
	v_pk_add_f32 v[120:121], v[120:121], v[152:153] neg_lo:[0,1] neg_hi:[0,1]
	v_pk_fma_f32 v[114:115], v[114:115], v[74:75], v[116:117] op_sel_hi:[1,0,1]
	v_pk_add_f32 v[152:153], v[122:123], v[130:131]
	v_pk_add_f32 v[116:117], v[114:115], 0 neg_lo:[1,1] neg_hi:[1,1]
	v_pk_add_f32 v[122:123], v[122:123], v[130:131] neg_lo:[0,1] neg_hi:[0,1]
	v_pk_add_f32 v[130:131], v[126:127], v[124:125]
	v_pk_add_f32 v[72:73], v[126:127], v[124:125] neg_lo:[0,1] neg_hi:[0,1]
	v_pk_add_f32 v[124:125], v[80:81], v[172:173]
	v_mov_b32_e32 v116, v115
	v_pk_mul_f32 v[116:117], v[116:117], v[124:125] op_sel:[0,1] op_sel_hi:[1,0]
	v_pk_add_f32 v[126:127], v[80:81], v[172:173] neg_lo:[0,1] neg_hi:[0,1]
	v_pk_fma_f32 v[116:117], v[124:125], v[114:115], v[116:117] op_sel_hi:[1,0,1]
	ds_write_b64 v112, v[116:117] offset:768
	v_pk_mul_f32 v[112:113], v[78:79], v[114:115] op_sel:[0,1] op_sel_hi:[1,0]
	v_pk_add_f32 v[158:159], v[132:133], v[128:129]
	v_pk_fma_f32 v[112:113], v[114:115], v[74:75], v[112:113] op_sel_hi:[1,0,1]
	v_pk_add_f32 v[80:81], v[132:133], v[128:129] neg_lo:[0,1] neg_hi:[0,1]
	v_pk_add_f32 v[114:115], v[112:113], 0 neg_lo:[1,1] neg_hi:[1,1]
	v_pk_add_f32 v[128:129], v[174:175], v[176:177]
	v_mov_b32_e32 v114, v113
	v_pk_mul_f32 v[114:115], v[114:115], v[134:135] op_sel:[0,1] op_sel_hi:[1,0]
	v_pk_add_f32 v[146:147], v[148:149], v[164:165]
	v_pk_fma_f32 v[114:115], v[134:135], v[112:113], v[114:115] op_sel_hi:[1,0,1]
	ds_write_b64 v111, v[114:115] offset:1024
	v_pk_mul_f32 v[114:115], v[78:79], v[112:113] op_sel:[0,1] op_sel_hi:[1,0]
	v_pk_add_f32 v[132:133], v[174:175], v[176:177] neg_lo:[0,1] neg_hi:[0,1]
	v_pk_fma_f32 v[112:113], v[112:113], v[74:75], v[114:115] op_sel_hi:[1,0,1]
	v_pk_add_f32 v[148:149], v[148:149], v[164:165] neg_lo:[0,1] neg_hi:[0,1]
	v_pk_add_f32 v[114:115], v[112:113], 0 neg_lo:[1,1] neg_hi:[1,1]
	s_nop 0
	v_mov_b32_e32 v114, v113
	v_pk_mul_f32 v[114:115], v[114:115], v[152:153] op_sel:[0,1] op_sel_hi:[1,0]
	s_nop 0
	v_pk_fma_f32 v[114:115], v[152:153], v[112:113], v[114:115] op_sel_hi:[1,0,1]
	ds_write_b64 v110, v[114:115] offset:1280
	v_pk_mul_f32 v[110:111], v[78:79], v[112:113] op_sel:[0,1] op_sel_hi:[1,0]
	s_nop 0
	v_pk_fma_f32 v[110:111], v[112:113], v[74:75], v[110:111] op_sel_hi:[1,0,1]
	s_nop 0
	v_pk_add_f32 v[112:113], v[110:111], 0 neg_lo:[1,1] neg_hi:[1,1]
	s_nop 0
	v_mov_b32_e32 v112, v111
	v_pk_mul_f32 v[112:113], v[112:113], v[144:145] op_sel:[0,1] op_sel_hi:[1,0]
	s_nop 0
	v_pk_fma_f32 v[112:113], v[144:145], v[110:111], v[112:113] op_sel_hi:[1,0,1]
	ds_write_b64 v109, v[112:113] offset:1536
	v_pk_mul_f32 v[112:113], v[78:79], v[110:111] op_sel:[0,1] op_sel_hi:[1,0]
	s_nop 0
	v_pk_fma_f32 v[110:111], v[110:111], v[74:75], v[112:113] op_sel_hi:[1,0,1]
	s_nop 0
	v_pk_add_f32 v[112:113], v[110:111], 0 neg_lo:[1,1] neg_hi:[1,1]
	s_nop 0
	v_mov_b32_e32 v112, v111
	v_pk_mul_f32 v[112:113], v[112:113], v[128:129] op_sel:[0,1] op_sel_hi:[1,0]
	s_nop 0
	v_pk_fma_f32 v[112:113], v[128:129], v[110:111], v[112:113] op_sel_hi:[1,0,1]
	ds_write_b64 v108, v[112:113] offset:1792
	v_pk_mul_f32 v[108:109], v[78:79], v[110:111] op_sel:[0,1] op_sel_hi:[1,0]
	s_nop 0
	v_pk_fma_f32 v[108:109], v[110:111], v[74:75], v[108:109] op_sel_hi:[1,0,1]
	s_nop 0
	v_pk_add_f32 v[110:111], v[108:109], 0 neg_lo:[1,1] neg_hi:[1,1]
	s_nop 0
	v_mov_b32_e32 v110, v109
	v_pk_mul_f32 v[110:111], v[110:111], v[168:169] op_sel:[0,1] op_sel_hi:[1,0]
	s_nop 0
	v_pk_fma_f32 v[110:111], v[168:169], v[108:109], v[110:111] op_sel_hi:[1,0,1]
	ds_write_b64 v107, v[110:111] offset:2048
	v_pk_mul_f32 v[110:111], v[78:79], v[108:109] op_sel:[0,1] op_sel_hi:[1,0]
	s_nop 0
	v_pk_fma_f32 v[108:109], v[108:109], v[74:75], v[110:111] op_sel_hi:[1,0,1]
	s_nop 0
	v_pk_add_f32 v[110:111], v[108:109], 0 neg_lo:[1,1] neg_hi:[1,1]
	s_nop 0
	v_mov_b32_e32 v110, v109
	v_pk_mul_f32 v[110:111], v[110:111], v[146:147] op_sel:[0,1] op_sel_hi:[1,0]
	s_nop 0
	v_pk_fma_f32 v[110:111], v[146:147], v[108:109], v[110:111] op_sel_hi:[1,0,1]
	ds_write_b64 v106, v[110:111] offset:2304
	v_pk_mul_f32 v[106:107], v[78:79], v[108:109] op_sel:[0,1] op_sel_hi:[1,0]
	s_nop 0
	v_pk_fma_f32 v[106:107], v[108:109], v[74:75], v[106:107] op_sel_hi:[1,0,1]
	s_nop 0
	v_pk_add_f32 v[108:109], v[106:107], 0 neg_lo:[1,1] neg_hi:[1,1]
	s_nop 0
	v_mov_b32_e32 v108, v107
	v_pk_mul_f32 v[108:109], v[108:109], v[156:157] op_sel:[0,1] op_sel_hi:[1,0]
	s_nop 0
	v_pk_fma_f32 v[108:109], v[156:157], v[106:107], v[108:109] op_sel_hi:[1,0,1]
	ds_write_b64 v105, v[108:109] offset:2560
	v_pk_mul_f32 v[108:109], v[78:79], v[106:107] op_sel:[0,1] op_sel_hi:[1,0]
	s_nop 0
	v_pk_fma_f32 v[106:107], v[106:107], v[74:75], v[108:109] op_sel_hi:[1,0,1]
	s_nop 0
	v_pk_add_f32 v[108:109], v[106:107], 0 neg_lo:[1,1] neg_hi:[1,1]
	s_nop 0
	v_mov_b32_e32 v108, v107
	v_pk_mul_f32 v[108:109], v[108:109], v[158:159] op_sel:[0,1] op_sel_hi:[1,0]
	s_nop 0
	v_pk_fma_f32 v[108:109], v[158:159], v[106:107], v[108:109] op_sel_hi:[1,0,1]
	ds_write_b64 v103, v[108:109] offset:2816
	v_pk_mul_f32 v[108:109], v[78:79], v[106:107] op_sel:[0,1] op_sel_hi:[1,0]
	s_nop 0
	v_pk_fma_f32 v[106:107], v[106:107], v[74:75], v[108:109] op_sel_hi:[1,0,1]
	s_nop 0
	v_pk_add_f32 v[108:109], v[106:107], 0 neg_lo:[1,1] neg_hi:[1,1]
	s_nop 0
	v_mov_b32_e32 v108, v107
	v_pk_mul_f32 v[108:109], v[108:109], v[160:161] op_sel:[0,1] op_sel_hi:[1,0]
	s_nop 0
	v_pk_fma_f32 v[108:109], v[160:161], v[106:107], v[108:109] op_sel_hi:[1,0,1]
	ds_write_b64 v102, v[108:109] offset:3072
	v_pk_mul_f32 v[102:103], v[78:79], v[106:107] op_sel:[0,1] op_sel_hi:[1,0]
	s_nop 0
	v_pk_fma_f32 v[102:103], v[106:107], v[74:75], v[102:103] op_sel_hi:[1,0,1]
	s_nop 0
	v_pk_add_f32 v[106:107], v[102:103], 0 neg_lo:[1,1] neg_hi:[1,1]
	s_nop 0
	v_mov_b32_e32 v106, v103
	v_pk_mul_f32 v[106:107], v[106:107], v[130:131] op_sel:[0,1] op_sel_hi:[1,0]
	s_nop 0
	v_pk_fma_f32 v[106:107], v[130:131], v[102:103], v[106:107] op_sel_hi:[1,0,1]
	ds_write_b64 v101, v[106:107] offset:3328
	v_pk_mul_f32 v[106:107], v[78:79], v[102:103] op_sel:[0,1] op_sel_hi:[1,0]
	s_nop 0
	v_pk_fma_f32 v[102:103], v[102:103], v[74:75], v[106:107] op_sel_hi:[1,0,1]
	s_nop 0
	v_pk_add_f32 v[106:107], v[102:103], 0 neg_lo:[1,1] neg_hi:[1,1]
	s_nop 0
	v_mov_b32_e32 v106, v103
	v_pk_mul_f32 v[106:107], v[150:151], v[106:107] op_sel:[1,0] op_sel_hi:[0,1]
	v_pk_fma_f32 v[106:107], v[150:151], v[102:103], v[106:107] op_sel_hi:[1,0,1]
	ds_write_b64 v100, v[106:107] offset:3584
	v_pk_mul_f32 v[100:101], v[78:79], v[102:103] op_sel:[0,1] op_sel_hi:[1,0]
	s_nop 0
	v_pk_fma_f32 v[100:101], v[102:103], v[74:75], v[100:101] op_sel_hi:[1,0,1]
	s_nop 0
	v_pk_add_f32 v[102:103], v[100:101], 0 neg_lo:[1,1] neg_hi:[1,1]
	s_nop 0
	v_mov_b32_e32 v102, v101
	v_pk_mul_f32 v[102:103], v[162:163], v[102:103] op_sel:[1,0] op_sel_hi:[0,1]
	v_pk_fma_f32 v[102:103], v[162:163], v[100:101], v[102:103] op_sel_hi:[1,0,1]
	ds_write_b64 v99, v[102:103] offset:3840
	v_pk_mul_f32 v[102:103], v[78:79], v[100:101] op_sel:[0,1] op_sel_hi:[1,0]
	s_nop 0
	v_pk_fma_f32 v[100:101], v[100:101], v[74:75], v[102:103] op_sel_hi:[1,0,1]
	s_nop 0
	v_pk_add_f32 v[102:103], v[100:101], 0 neg_lo:[1,1] neg_hi:[1,1]
	s_nop 0
	v_mov_b32_e32 v102, v101
	v_pk_mul_f32 v[102:103], v[118:119], v[102:103] op_sel:[1,0] op_sel_hi:[0,1]
	v_pk_fma_f32 v[102:103], v[118:119], v[100:101], v[102:103] op_sel_hi:[1,0,1]
	ds_write_b64 v98, v[102:103] offset:4096
	v_pk_mul_f32 v[98:99], v[78:79], v[100:101] op_sel:[0,1] op_sel_hi:[1,0]
	s_nop 0
	v_pk_fma_f32 v[98:99], v[100:101], v[74:75], v[98:99] op_sel_hi:[1,0,1]
	s_nop 0
	v_pk_add_f32 v[100:101], v[98:99], 0 neg_lo:[1,1] neg_hi:[1,1]
	s_nop 0
	v_mov_b32_e32 v100, v99
	v_pk_mul_f32 v[100:101], v[120:121], v[100:101] op_sel:[1,0] op_sel_hi:[0,1]
	v_pk_fma_f32 v[100:101], v[120:121], v[98:99], v[100:101] op_sel_hi:[1,0,1]
	ds_write_b64 v97, v[100:101] offset:4352
	v_pk_mul_f32 v[100:101], v[78:79], v[98:99] op_sel:[0,1] op_sel_hi:[1,0]
	s_nop 0
	v_pk_fma_f32 v[98:99], v[98:99], v[74:75], v[100:101] op_sel_hi:[1,0,1]
	s_nop 0
	v_pk_add_f32 v[100:101], v[98:99], 0 neg_lo:[1,1] neg_hi:[1,1]
	s_nop 0
	v_mov_b32_e32 v100, v99
	v_pk_mul_f32 v[100:101], v[142:143], v[100:101] op_sel:[1,0] op_sel_hi:[0,1]
	v_pk_fma_f32 v[100:101], v[142:143], v[98:99], v[100:101] op_sel_hi:[1,0,1]
	ds_write_b64 v96, v[100:101] offset:4608
	v_pk_mul_f32 v[96:97], v[78:79], v[98:99] op_sel:[0,1] op_sel_hi:[1,0]
	s_nop 0
	v_pk_fma_f32 v[96:97], v[98:99], v[74:75], v[96:97] op_sel_hi:[1,0,1]
	s_nop 0
	v_pk_add_f32 v[98:99], v[96:97], 0 neg_lo:[1,1] neg_hi:[1,1]
	s_nop 0
	v_mov_b32_e32 v98, v97
	v_pk_mul_f32 v[98:99], v[126:127], v[98:99] op_sel:[1,0] op_sel_hi:[0,1]
	v_pk_fma_f32 v[98:99], v[126:127], v[96:97], v[98:99] op_sel_hi:[1,0,1]
	ds_write_b64 v95, v[98:99] offset:4864
	v_pk_mul_f32 v[98:99], v[78:79], v[96:97] op_sel:[0,1] op_sel_hi:[1,0]
	s_nop 0
	v_pk_fma_f32 v[96:97], v[96:97], v[74:75], v[98:99] op_sel_hi:[1,0,1]
	s_nop 0
	v_pk_add_f32 v[98:99], v[96:97], 0 neg_lo:[1,1] neg_hi:[1,1]
	s_nop 0
	v_mov_b32_e32 v98, v97
	v_pk_mul_f32 v[98:99], v[136:137], v[98:99] op_sel:[1,0] op_sel_hi:[0,1]
	v_pk_fma_f32 v[98:99], v[136:137], v[96:97], v[98:99] op_sel_hi:[1,0,1]
	ds_write_b64 v94, v[98:99] offset:5120
	v_pk_mul_f32 v[94:95], v[78:79], v[96:97] op_sel:[0,1] op_sel_hi:[1,0]
	s_nop 0
	v_pk_fma_f32 v[94:95], v[96:97], v[74:75], v[94:95] op_sel_hi:[1,0,1]
	s_nop 0
	v_pk_add_f32 v[96:97], v[94:95], 0 neg_lo:[1,1] neg_hi:[1,1]
	s_nop 0
	v_mov_b32_e32 v96, v95
	v_pk_mul_f32 v[96:97], v[122:123], v[96:97] op_sel:[1,0] op_sel_hi:[0,1]
	v_pk_fma_f32 v[96:97], v[122:123], v[94:95], v[96:97] op_sel_hi:[1,0,1]
	ds_write_b64 v93, v[96:97] offset:5376
	v_pk_mul_f32 v[96:97], v[78:79], v[94:95] op_sel:[0,1] op_sel_hi:[1,0]
	s_nop 0
	v_pk_fma_f32 v[94:95], v[94:95], v[74:75], v[96:97] op_sel_hi:[1,0,1]
	s_nop 0
	v_pk_add_f32 v[96:97], v[94:95], 0 neg_lo:[1,1] neg_hi:[1,1]
	s_nop 0
	v_mov_b32_e32 v96, v95
	v_pk_mul_f32 v[96:97], v[138:139], v[96:97] op_sel:[1,0] op_sel_hi:[0,1]
	v_pk_fma_f32 v[96:97], v[138:139], v[94:95], v[96:97] op_sel_hi:[1,0,1]
	ds_write_b64 v92, v[96:97] offset:5632
	v_pk_mul_f32 v[92:93], v[78:79], v[94:95] op_sel:[0,1] op_sel_hi:[1,0]
	s_nop 0
	v_pk_fma_f32 v[92:93], v[94:95], v[74:75], v[92:93] op_sel_hi:[1,0,1]
	s_nop 0
	v_pk_add_f32 v[94:95], v[92:93], 0 neg_lo:[1,1] neg_hi:[1,1]
	s_nop 0
	v_mov_b32_e32 v94, v93
	v_pk_mul_f32 v[94:95], v[132:133], v[94:95] op_sel:[1,0] op_sel_hi:[0,1]
	v_pk_fma_f32 v[94:95], v[132:133], v[92:93], v[94:95] op_sel_hi:[1,0,1]
	ds_write_b64 v91, v[94:95] offset:5888
	v_pk_mul_f32 v[94:95], v[78:79], v[92:93] op_sel:[0,1] op_sel_hi:[1,0]
	s_nop 0
	v_pk_fma_f32 v[92:93], v[92:93], v[74:75], v[94:95] op_sel_hi:[1,0,1]
	s_nop 0
	v_pk_add_f32 v[94:95], v[92:93], 0 neg_lo:[1,1] neg_hi:[1,1]
	s_nop 0
	v_mov_b32_e32 v94, v93
	v_pk_mul_f32 v[94:95], v[82:83], v[94:95] op_sel:[1,0] op_sel_hi:[0,1]
	v_pk_fma_f32 v[82:83], v[82:83], v[92:93], v[94:95] op_sel_hi:[1,0,1]
	ds_write_b64 v90, v[82:83] offset:6144
	v_pk_mul_f32 v[82:83], v[78:79], v[92:93] op_sel:[0,1] op_sel_hi:[1,0]
	s_nop 0
	v_pk_fma_f32 v[82:83], v[92:93], v[74:75], v[82:83] op_sel_hi:[1,0,1]
	s_nop 0
	v_pk_add_f32 v[90:91], v[82:83], 0 neg_lo:[1,1] neg_hi:[1,1]
	s_nop 0
	v_mov_b32_e32 v90, v83
	v_pk_mul_f32 v[90:91], v[148:149], v[90:91] op_sel:[1,0] op_sel_hi:[0,1]
	v_pk_fma_f32 v[90:91], v[148:149], v[82:83], v[90:91] op_sel_hi:[1,0,1]
	ds_write_b64 v89, v[90:91] offset:6400
	v_pk_mul_f32 v[90:91], v[78:79], v[82:83] op_sel:[0,1] op_sel_hi:[1,0]
	s_nop 0
	v_pk_fma_f32 v[82:83], v[82:83], v[74:75], v[90:91] op_sel_hi:[1,0,1]
	s_nop 0
	v_pk_add_f32 v[90:91], v[82:83], 0 neg_lo:[1,1] neg_hi:[1,1]
	s_nop 0
	v_mov_b32_e32 v90, v83
	v_pk_mul_f32 v[90:91], v[76:77], v[90:91] op_sel:[1,0] op_sel_hi:[0,1]
	v_pk_fma_f32 v[76:77], v[76:77], v[82:83], v[90:91] op_sel_hi:[1,0,1]
	ds_write_b64 v88, v[76:77] offset:6656
	v_pk_mul_f32 v[76:77], v[78:79], v[82:83] op_sel:[0,1] op_sel_hi:[1,0]
	s_nop 0
	v_pk_fma_f32 v[76:77], v[82:83], v[74:75], v[76:77] op_sel_hi:[1,0,1]
	s_nop 0
	v_pk_add_f32 v[82:83], v[76:77], 0 neg_lo:[1,1] neg_hi:[1,1]
	s_nop 0
	v_mov_b32_e32 v82, v77
	v_pk_mul_f32 v[82:83], v[80:81], v[82:83] op_sel:[1,0] op_sel_hi:[0,1]
	v_pk_fma_f32 v[80:81], v[80:81], v[76:77], v[82:83] op_sel_hi:[1,0,1]
	ds_write_b64 v87, v[80:81] offset:6912
	v_pk_mul_f32 v[80:81], v[78:79], v[76:77] op_sel:[0,1] op_sel_hi:[1,0]
	s_nop 0
	v_pk_fma_f32 v[76:77], v[76:77], v[74:75], v[80:81] op_sel_hi:[1,0,1]
	s_nop 0
	v_pk_add_f32 v[80:81], v[76:77], 0 neg_lo:[1,1] neg_hi:[1,1]
	s_nop 0
	v_mov_b32_e32 v80, v77
	v_pk_mul_f32 v[80:81], v[68:69], v[80:81] op_sel:[1,0] op_sel_hi:[0,1]
	v_pk_fma_f32 v[68:69], v[68:69], v[76:77], v[80:81] op_sel_hi:[1,0,1]
	ds_write_b64 v86, v[68:69] offset:7168
	v_pk_mul_f32 v[68:69], v[78:79], v[76:77] op_sel:[0,1] op_sel_hi:[1,0]
	s_nop 0
	v_pk_fma_f32 v[68:69], v[76:77], v[74:75], v[68:69] op_sel_hi:[1,0,1]
	s_nop 0
	v_pk_add_f32 v[76:77], v[68:69], 0 neg_lo:[1,1] neg_hi:[1,1]
	s_nop 0
	v_mov_b32_e32 v76, v69
	v_pk_mul_f32 v[76:77], v[72:73], v[76:77] op_sel:[1,0] op_sel_hi:[0,1]
	v_pk_fma_f32 v[72:73], v[72:73], v[68:69], v[76:77] op_sel_hi:[1,0,1]
	ds_write_b64 v85, v[72:73] offset:7424
	v_pk_mul_f32 v[72:73], v[78:79], v[68:69] op_sel:[0,1] op_sel_hi:[1,0]
	s_nop 0
	v_pk_fma_f32 v[68:69], v[68:69], v[74:75], v[72:73] op_sel_hi:[1,0,1]
	s_nop 0
	v_pk_add_f32 v[72:73], v[68:69], 0 neg_lo:[1,1] neg_hi:[1,1]
	s_nop 0
	v_mov_b32_e32 v72, v69
	v_pk_mul_f32 v[72:73], v[66:67], v[72:73] op_sel:[1,0] op_sel_hi:[0,1]
	v_pk_fma_f32 v[66:67], v[66:67], v[68:69], v[72:73] op_sel_hi:[1,0,1]
	ds_write_b64 v84, v[66:67] offset:7680
	v_pk_mul_f32 v[66:67], v[78:79], v[68:69] op_sel:[0,1] op_sel_hi:[1,0]
	s_nop 0
	v_pk_fma_f32 v[66:67], v[68:69], v[74:75], v[66:67] op_sel_hi:[1,0,1]
	s_nop 0
	v_pk_add_f32 v[68:69], v[66:67], 0 neg_lo:[1,1] neg_hi:[1,1]
	s_nop 0
	v_mov_b32_e32 v68, v67
	v_pk_mul_f32 v[68:69], v[70:71], v[68:69] op_sel:[1,0] op_sel_hi:[0,1]
	v_pk_fma_f32 v[66:67], v[70:71], v[66:67], v[68:69] op_sel_hi:[1,0,1]
	ds_write_b64 v0, v[66:67]
	s_waitcnt lgkmcnt(0)
	s_barrier
	ds_read2_b64 v[66:69], v104 offset1:1
	ds_read2_b64 v[70:73], v104 offset0:2 offset1:3
	ds_read2_b64 v[74:77], v104 offset0:4 offset1:5
	ds_read2_b64 v[78:81], v104 offset0:6 offset1:7
	ds_read2_b64 v[82:85], v104 offset0:8 offset1:9
	ds_read2_b64 v[86:89], v104 offset0:10 offset1:11
	ds_read2_b64 v[90:93], v104 offset0:12 offset1:13
	ds_read2_b64 v[94:97], v104 offset0:14 offset1:15
	ds_read2_b64 v[98:101], v104 offset0:16 offset1:17
	ds_read2_b64 v[106:109], v104 offset0:18 offset1:19
	ds_read2_b64 v[110:113], v104 offset0:20 offset1:21
	ds_read2_b64 v[114:117], v104 offset0:22 offset1:23
	ds_read2_b64 v[118:121], v104 offset0:24 offset1:25
	ds_read2_b64 v[122:125], v104 offset0:26 offset1:27
	ds_read2_b64 v[126:129], v104 offset0:28 offset1:29
	ds_read2_b64 v[130:133], v104 offset0:30 offset1:31
	s_waitcnt lgkmcnt(7)
	v_pk_add_f32 v[102:103], v[66:67], v[98:99]
	v_pk_add_f32 v[66:67], v[66:67], v[98:99] neg_lo:[0,1] neg_hi:[0,1]
	v_pk_add_f32 v[98:99], v[68:69], v[100:101]
	v_pk_add_f32 v[68:69], v[68:69], v[100:101] neg_lo:[0,1] neg_hi:[0,1]
	global_load_dwordx2 v[134:135], v[2:3], off
	global_load_dwordx2 v[136:137], v[4:5], off
	global_load_dwordx2 v[138:139], v[6:7], off
	v_pk_mul_f32 v[100:101], v[68:69], s[18:19]
	global_load_dwordx2 v[148:149], v[14:15], off
	global_load_dwordx2 v[154:155], v[16:17], off
	v_pk_fma_f32 v[68:69], v[68:69], s[20:21], v[100:101] op_sel:[0,0,1] op_sel_hi:[1,0,0]
	s_waitcnt lgkmcnt(6)
	v_pk_add_f32 v[100:101], v[70:71], v[106:107]
	v_pk_add_f32 v[70:71], v[70:71], v[106:107] neg_lo:[0,1] neg_hi:[0,1]
	global_load_dwordx2 v[158:159], v[18:19], off
	v_pk_mul_f32 v[106:107], v[70:71], s[4:5]
	global_load_dwordx2 v[160:161], v[28:29], off
	global_load_dwordx2 v[164:165], v[32:33], off
	v_pk_fma_f32 v[70:71], v[70:71], s[6:7], v[106:107] op_sel:[0,0,1] op_sel_hi:[1,0,0]
	v_pk_add_f32 v[106:107], v[72:73], v[108:109]
	v_pk_add_f32 v[72:73], v[72:73], v[108:109] neg_lo:[0,1] neg_hi:[0,1]
	global_load_dwordx2 v[168:169], v[36:37], off
	v_pk_mul_f32 v[108:109], v[72:73], s[22:23]
	global_load_dwordx2 v[172:173], v[44:45], off
	v_pk_fma_f32 v[72:73], v[72:73], s[24:25], v[108:109] op_sel:[0,0,1] op_sel_hi:[1,0,0]
	s_waitcnt lgkmcnt(5)
	v_pk_add_f32 v[108:109], v[74:75], v[110:111]
	v_pk_add_f32 v[74:75], v[74:75], v[110:111] neg_lo:[0,1] neg_hi:[0,1]
	global_load_dwordx2 v[174:175], v[52:53], off
	v_pk_mul_f32 v[110:111], v[74:75], s[8:9]
	global_load_dwordx2 v[176:177], v[60:61], off
	v_pk_fma_f32 v[74:75], v[74:75], s[10:11], v[110:111] op_sel:[0,0,1] op_sel_hi:[1,0,0]
	v_pk_add_f32 v[110:111], v[76:77], v[112:113]
	v_pk_add_f32 v[76:77], v[76:77], v[112:113] neg_lo:[0,1] neg_hi:[0,1]
	s_nop 0
	v_pk_mul_f32 v[112:113], v[76:77], s[26:27]
	s_nop 0
	v_pk_fma_f32 v[76:77], v[76:77], s[0:1], v[112:113] op_sel:[0,0,1] op_sel_hi:[1,0,0]
	s_waitcnt lgkmcnt(4)
	v_pk_add_f32 v[112:113], v[78:79], v[114:115]
	v_pk_add_f32 v[78:79], v[78:79], v[114:115] neg_lo:[0,1] neg_hi:[0,1]
	s_nop 0
	v_pk_mul_f32 v[114:115], v[78:79], s[12:13]
	s_nop 0
	v_pk_fma_f32 v[78:79], v[78:79], s[14:15], v[114:115] op_sel:[0,0,1] op_sel_hi:[1,0,0]
	v_pk_add_f32 v[114:115], v[80:81], v[116:117]
	v_pk_add_f32 v[80:81], v[80:81], v[116:117] neg_lo:[0,1] neg_hi:[0,1]
	s_nop 0
	v_pk_mul_f32 v[116:117], v[80:81], s[34:35]
	s_nop 0
	v_pk_fma_f32 v[80:81], v[80:81], s[48:49], v[116:117] op_sel:[0,0,1] op_sel_hi:[1,0,0]
	s_waitcnt lgkmcnt(3)
	v_pk_add_f32 v[116:117], v[82:83], v[118:119]
	v_pk_add_f32 v[118:119], v[82:83], v[118:119] op_sel:[1,1] op_sel_hi:[0,0] neg_lo:[0,1] neg_hi:[1,0]
	s_nop 0
	v_pk_add_f32 v[82:83], v[84:85], v[120:121]
	v_pk_add_f32 v[84:85], v[84:85], v[120:121] neg_lo:[0,1] neg_hi:[0,1]
	s_nop 0
	v_pk_mul_f32 v[120:121], v[84:85], s[34:35]
	s_nop 0
	v_pk_fma_f32 v[84:85], v[84:85], s[18:19], v[120:121] op_sel:[0,0,1] op_sel_hi:[1,0,0]
	s_waitcnt lgkmcnt(2)
	v_pk_add_f32 v[120:121], v[86:87], v[122:123]
	v_pk_add_f32 v[86:87], v[86:87], v[122:123] neg_lo:[0,1] neg_hi:[0,1]
	s_nop 0
	v_pk_mul_f32 v[122:123], v[86:87], s[12:13]
	s_nop 0
	v_pk_fma_f32 v[86:87], v[86:87], s[4:5], v[122:123] op_sel:[0,0,1] op_sel_hi:[1,0,0]
	v_pk_add_f32 v[122:123], v[88:89], v[124:125]
	v_pk_add_f32 v[88:89], v[88:89], v[124:125] neg_lo:[0,1] neg_hi:[0,1]
	s_nop 0
	v_pk_mul_f32 v[124:125], v[88:89], s[26:27]
	s_nop 0
	v_pk_fma_f32 v[88:89], v[88:89], s[22:23], v[124:125] op_sel:[0,0,1] op_sel_hi:[1,0,0]
	s_waitcnt lgkmcnt(1)
	v_pk_add_f32 v[124:125], v[90:91], v[126:127]
	v_pk_add_f32 v[90:91], v[90:91], v[126:127] neg_lo:[0,1] neg_hi:[0,1]
	s_nop 0
	v_pk_mul_f32 v[126:127], v[90:91], s[8:9]
	s_nop 0
	v_pk_fma_f32 v[90:91], v[90:91], s[8:9], v[126:127] op_sel:[0,0,1] op_sel_hi:[1,0,0]
	v_pk_add_f32 v[126:127], v[92:93], v[128:129]
	v_pk_add_f32 v[92:93], v[92:93], v[128:129] neg_lo:[0,1] neg_hi:[0,1]
	s_nop 0
	v_pk_mul_f32 v[128:129], v[92:93], s[22:23]
	s_nop 0
	v_pk_fma_f32 v[92:93], v[92:93], s[26:27], v[128:129] op_sel:[0,0,1] op_sel_hi:[1,0,0]
	s_waitcnt lgkmcnt(0)
	v_pk_add_f32 v[128:129], v[94:95], v[130:131]
	v_pk_add_f32 v[94:95], v[94:95], v[130:131] neg_lo:[0,1] neg_hi:[0,1]
	s_nop 0
	v_pk_mul_f32 v[130:131], v[94:95], s[4:5]
	s_nop 0
	v_pk_fma_f32 v[94:95], v[94:95], s[12:13], v[130:131] op_sel:[0,0,1] op_sel_hi:[1,0,0]
	v_pk_add_f32 v[130:131], v[96:97], v[132:133]
	v_pk_add_f32 v[96:97], v[96:97], v[132:133] neg_lo:[0,1] neg_hi:[0,1]
	s_nop 0
	v_pk_mul_f32 v[132:133], v[96:97], s[18:19]
	s_nop 0
	v_pk_fma_f32 v[96:97], v[96:97], s[34:35], v[132:133] op_sel:[0,0,1] op_sel_hi:[1,0,0]
	v_pk_add_f32 v[132:133], v[102:103], v[116:117]
	v_pk_add_f32 v[102:103], v[102:103], v[116:117] neg_lo:[0,1] neg_hi:[0,1]
	v_pk_add_f32 v[116:117], v[98:99], v[82:83]
	v_pk_add_f32 v[82:83], v[98:99], v[82:83] neg_lo:[0,1] neg_hi:[0,1]
	s_nop 0
	v_pk_mul_f32 v[98:99], v[82:83], s[4:5]
	s_nop 0
	v_pk_fma_f32 v[82:83], v[82:83], s[6:7], v[98:99] op_sel:[0,0,1] op_sel_hi:[1,0,0]
	v_pk_add_f32 v[98:99], v[100:101], v[120:121]
	v_pk_add_f32 v[100:101], v[100:101], v[120:121] neg_lo:[0,1] neg_hi:[0,1]
	s_nop 0
	v_pk_mul_f32 v[120:121], v[100:101], s[8:9]
	s_nop 0
	v_pk_fma_f32 v[100:101], v[100:101], s[10:11], v[120:121] op_sel:[0,0,1] op_sel_hi:[1,0,0]
	v_pk_add_f32 v[120:121], v[106:107], v[122:123]
	v_pk_add_f32 v[106:107], v[106:107], v[122:123] neg_lo:[0,1] neg_hi:[0,1]
	s_nop 0
	v_pk_mul_f32 v[122:123], v[106:107], s[12:13]
	s_nop 0
	v_pk_fma_f32 v[106:107], v[106:107], s[14:15], v[122:123] op_sel:[0,0,1] op_sel_hi:[1,0,0]
	v_pk_add_f32 v[122:123], v[108:109], v[124:125]
	v_pk_add_f32 v[124:125], v[108:109], v[124:125] op_sel:[1,1] op_sel_hi:[0,0] neg_lo:[0,1] neg_hi:[1,0]
	s_nop 0
	v_pk_add_f32 v[108:109], v[110:111], v[126:127]
	v_pk_add_f32 v[110:111], v[110:111], v[126:127] neg_lo:[0,1] neg_hi:[0,1]
	s_nop 0
	v_pk_mul_f32 v[126:127], v[110:111], s[12:13]
	s_nop 0
	v_pk_fma_f32 v[110:111], v[110:111], s[4:5], v[126:127] op_sel:[0,0,1] op_sel_hi:[1,0,0]
	v_pk_add_f32 v[126:127], v[112:113], v[128:129]
	v_pk_add_f32 v[112:113], v[112:113], v[128:129] neg_lo:[0,1] neg_hi:[0,1]
	s_nop 0
	v_pk_mul_f32 v[128:129], v[112:113], s[8:9]
	s_nop 0
	v_pk_fma_f32 v[112:113], v[112:113], s[8:9], v[128:129] op_sel:[0,0,1] op_sel_hi:[1,0,0]
	v_pk_add_f32 v[128:129], v[114:115], v[130:131]
	v_pk_add_f32 v[114:115], v[114:115], v[130:131] neg_lo:[0,1] neg_hi:[0,1]
	s_nop 0
	v_pk_mul_f32 v[130:131], v[114:115], s[4:5]
	s_nop 0
	v_pk_fma_f32 v[114:115], v[114:115], s[12:13], v[130:131] op_sel:[0,0,1] op_sel_hi:[1,0,0]
	v_pk_add_f32 v[130:131], v[66:67], v[118:119]
	v_pk_add_f32 v[66:67], v[66:67], v[118:119] neg_lo:[0,1] neg_hi:[0,1]
	v_pk_add_f32 v[118:119], v[68:69], v[84:85]
	v_pk_add_f32 v[68:69], v[68:69], v[84:85] neg_lo:[0,1] neg_hi:[0,1]
	s_nop 0
	v_pk_mul_f32 v[84:85], v[68:69], s[4:5]
	s_nop 0
	v_pk_fma_f32 v[68:69], v[68:69], s[6:7], v[84:85] op_sel:[0,0,1] op_sel_hi:[1,0,0]
	v_pk_add_f32 v[84:85], v[70:71], v[86:87]
	v_pk_add_f32 v[70:71], v[70:71], v[86:87] neg_lo:[0,1] neg_hi:[0,1]
	s_nop 0
	v_pk_mul_f32 v[86:87], v[70:71], s[8:9]
	s_nop 0
	v_pk_fma_f32 v[70:71], v[70:71], s[10:11], v[86:87] op_sel:[0,0,1] op_sel_hi:[1,0,0]
	v_pk_add_f32 v[86:87], v[72:73], v[88:89]
	v_pk_add_f32 v[72:73], v[72:73], v[88:89] neg_lo:[0,1] neg_hi:[0,1]
	s_nop 0
	v_pk_mul_f32 v[88:89], v[72:73], s[12:13]
	s_nop 0
	v_pk_fma_f32 v[72:73], v[72:73], s[14:15], v[88:89] op_sel:[0,0,1] op_sel_hi:[1,0,0]
	v_pk_add_f32 v[88:89], v[74:75], v[90:91]
	v_pk_add_f32 v[90:91], v[74:75], v[90:91] op_sel:[1,1] op_sel_hi:[0,0] neg_lo:[0,1] neg_hi:[1,0]
	s_mov_b32 s15, s4
	v_pk_add_f32 v[74:75], v[76:77], v[92:93]
	v_pk_add_f32 v[76:77], v[76:77], v[92:93] neg_lo:[0,1] neg_hi:[0,1]
	s_nop 0
	v_pk_mul_f32 v[92:93], v[76:77], s[12:13]
	s_nop 0
	v_pk_fma_f32 v[76:77], v[76:77], s[4:5], v[92:93] op_sel:[0,0,1] op_sel_hi:[1,0,0]
	v_pk_add_f32 v[92:93], v[78:79], v[94:95]
	v_pk_add_f32 v[78:79], v[78:79], v[94:95] neg_lo:[0,1] neg_hi:[0,1]
	s_nop 0
	v_pk_mul_f32 v[94:95], v[78:79], s[8:9]
	s_nop 0
	v_pk_fma_f32 v[78:79], v[78:79], s[8:9], v[94:95] op_sel:[0,0,1] op_sel_hi:[1,0,0]
	v_pk_add_f32 v[94:95], v[80:81], v[96:97]
	v_pk_add_f32 v[80:81], v[80:81], v[96:97] neg_lo:[0,1] neg_hi:[0,1]
	s_nop 0
	v_pk_mul_f32 v[96:97], v[80:81], s[4:5]
	s_nop 0
	v_pk_fma_f32 v[80:81], v[80:81], s[12:13], v[96:97] op_sel:[0,0,1] op_sel_hi:[1,0,0]
	v_pk_add_f32 v[96:97], v[132:133], v[122:123]
	v_pk_add_f32 v[122:123], v[132:133], v[122:123] neg_lo:[0,1] neg_hi:[0,1]
	v_pk_add_f32 v[132:133], v[116:117], v[108:109]
	v_pk_add_f32 v[108:109], v[116:117], v[108:109] neg_lo:[0,1] neg_hi:[0,1]
	s_nop 0
	v_pk_mul_f32 v[116:117], v[108:109], s[8:9]
	s_nop 0
	v_pk_fma_f32 v[108:109], v[108:109], s[10:11], v[116:117] op_sel:[0,0,1] op_sel_hi:[1,0,0]
	v_pk_add_f32 v[116:117], v[98:99], v[126:127]
	v_pk_add_f32 v[126:127], v[98:99], v[126:127] op_sel:[1,1] op_sel_hi:[0,0] neg_lo:[0,1] neg_hi:[1,0]
	s_nop 0
	v_pk_add_f32 v[98:99], v[120:121], v[128:129]
	v_pk_add_f32 v[120:121], v[120:121], v[128:129] neg_lo:[0,1] neg_hi:[0,1]
	s_nop 0
	v_pk_mul_f32 v[128:129], v[120:121], s[8:9]
	s_nop 0
	v_pk_fma_f32 v[120:121], v[120:121], s[8:9], v[128:129] op_sel:[0,0,1] op_sel_hi:[1,0,0]
	v_pk_add_f32 v[128:129], v[102:103], v[124:125]
	v_pk_add_f32 v[102:103], v[102:103], v[124:125] neg_lo:[0,1] neg_hi:[0,1]
	v_pk_add_f32 v[124:125], v[82:83], v[110:111]
	v_pk_add_f32 v[82:83], v[82:83], v[110:111] neg_lo:[0,1] neg_hi:[0,1]
	s_nop 0
	v_pk_mul_f32 v[110:111], v[82:83], s[8:9]
	s_nop 0
	v_pk_fma_f32 v[82:83], v[82:83], s[10:11], v[110:111] op_sel:[0,0,1] op_sel_hi:[1,0,0]
	v_pk_add_f32 v[110:111], v[100:101], v[112:113]
	v_pk_add_f32 v[112:113], v[100:101], v[112:113] op_sel:[1,1] op_sel_hi:[0,0] neg_lo:[0,1] neg_hi:[1,0]
	s_nop 0
	v_pk_add_f32 v[100:101], v[106:107], v[114:115]
	v_pk_add_f32 v[106:107], v[106:107], v[114:115] neg_lo:[0,1] neg_hi:[0,1]
	s_nop 0
	v_pk_mul_f32 v[114:115], v[106:107], s[8:9]
	s_nop 0
	v_pk_fma_f32 v[106:107], v[106:107], s[8:9], v[114:115] op_sel:[0,0,1] op_sel_hi:[1,0,0]
	v_pk_add_f32 v[114:115], v[130:131], v[88:89]
	v_pk_add_f32 v[88:89], v[130:131], v[88:89] neg_lo:[0,1] neg_hi:[0,1]
	v_pk_add_f32 v[130:131], v[118:119], v[74:75]
	v_pk_add_f32 v[74:75], v[118:119], v[74:75] neg_lo:[0,1] neg_hi:[0,1]
	s_nop 0
	v_pk_mul_f32 v[118:119], v[74:75], s[8:9]
	s_nop 0
	v_pk_fma_f32 v[74:75], v[74:75], s[10:11], v[118:119] op_sel:[0,0,1] op_sel_hi:[1,0,0]
	v_pk_add_f32 v[118:119], v[84:85], v[92:93]
	v_pk_add_f32 v[92:93], v[84:85], v[92:93] op_sel:[1,1] op_sel_hi:[0,0] neg_lo:[0,1] neg_hi:[1,0]
	s_nop 0
	v_pk_add_f32 v[84:85], v[86:87], v[94:95]
	v_pk_add_f32 v[86:87], v[86:87], v[94:95] neg_lo:[0,1] neg_hi:[0,1]
	v_pk_add_f32 v[140:141], v[88:89], v[92:93]
	v_pk_mul_f32 v[94:95], v[86:87], s[8:9]
	v_pk_add_f32 v[88:89], v[88:89], v[92:93] neg_lo:[0,1] neg_hi:[0,1]
	v_pk_fma_f32 v[86:87], v[86:87], s[8:9], v[94:95] op_sel:[0,0,1] op_sel_hi:[1,0,0]
	v_pk_add_f32 v[94:95], v[66:67], v[90:91]
	v_pk_add_f32 v[66:67], v[66:67], v[90:91] neg_lo:[0,1] neg_hi:[0,1]
	v_pk_add_f32 v[90:91], v[68:69], v[76:77]
	v_pk_add_f32 v[68:69], v[68:69], v[76:77] neg_lo:[0,1] neg_hi:[0,1]
	v_pk_add_f32 v[92:93], v[74:75], v[86:87]
	v_pk_mul_f32 v[76:77], v[68:69], s[8:9]
	v_pk_add_f32 v[142:143], v[74:75], v[86:87] op_sel:[1,1] op_sel_hi:[0,0] neg_lo:[0,1] neg_hi:[1,0]
	v_pk_fma_f32 v[68:69], v[68:69], s[10:11], v[76:77] op_sel:[0,0,1] op_sel_hi:[1,0,0]
	v_pk_add_f32 v[76:77], v[70:71], v[78:79]
	v_pk_add_f32 v[78:79], v[70:71], v[78:79] op_sel:[1,1] op_sel_hi:[0,0] neg_lo:[0,1] neg_hi:[1,0]
	global_load_dwordx2 v[86:87], v[10:11], off
	v_pk_add_f32 v[70:71], v[72:73], v[80:81]
	v_pk_add_f32 v[72:73], v[72:73], v[80:81] neg_lo:[0,1] neg_hi:[0,1]
	v_pk_mul_f32 v[80:81], v[72:73], s[8:9]
	v_pk_fma_f32 v[72:73], v[72:73], s[8:9], v[80:81] op_sel:[0,0,1] op_sel_hi:[1,0,0]
	v_pk_add_f32 v[80:81], v[96:97], v[116:117]
	v_pk_add_f32 v[96:97], v[96:97], v[116:117] neg_lo:[0,1] neg_hi:[0,1]
	v_pk_add_f32 v[116:117], v[132:133], v[98:99]
	v_pk_add_f32 v[132:133], v[132:133], v[98:99] op_sel:[1,1] op_sel_hi:[0,0] neg_lo:[0,1] neg_hi:[1,0]
	v_pk_add_f32 v[74:75], v[94:95], v[76:77]
	v_pk_add_f32 v[98:99], v[122:123], v[126:127]
	v_pk_add_f32 v[122:123], v[122:123], v[126:127] neg_lo:[0,1] neg_hi:[0,1]
	v_pk_add_f32 v[126:127], v[108:109], v[120:121]
	v_pk_add_f32 v[120:121], v[108:109], v[120:121] op_sel:[1,1] op_sel_hi:[0,0] neg_lo:[0,1] neg_hi:[1,0]
	v_pk_add_f32 v[76:77], v[94:95], v[76:77] neg_lo:[0,1] neg_hi:[0,1]
	v_pk_add_f32 v[108:109], v[128:129], v[110:111]
	v_pk_add_f32 v[110:111], v[128:129], v[110:111] neg_lo:[0,1] neg_hi:[0,1]
	v_pk_add_f32 v[128:129], v[124:125], v[100:101]
	v_pk_add_f32 v[124:125], v[124:125], v[100:101] op_sel:[1,1] op_sel_hi:[0,0] neg_lo:[0,1] neg_hi:[1,0]
	global_load_dwordx2 v[94:95], v[12:13], off
	v_pk_add_f32 v[100:101], v[102:103], v[112:113]
	v_pk_add_f32 v[102:103], v[102:103], v[112:113] neg_lo:[0,1] neg_hi:[0,1]
	v_pk_add_f32 v[112:113], v[82:83], v[106:107]
	v_pk_add_f32 v[106:107], v[82:83], v[106:107] op_sel:[1,1] op_sel_hi:[0,0] neg_lo:[0,1] neg_hi:[1,0]
	v_pk_add_f32 v[146:147], v[66:67], v[78:79]
	v_pk_add_f32 v[82:83], v[114:115], v[118:119]
	v_pk_add_f32 v[114:115], v[114:115], v[118:119] neg_lo:[0,1] neg_hi:[0,1]
	v_pk_add_f32 v[118:119], v[130:131], v[84:85]
	v_pk_add_f32 v[130:131], v[130:131], v[84:85] op_sel:[1,1] op_sel_hi:[0,0] neg_lo:[0,1] neg_hi:[1,0]
	v_pk_add_f32 v[78:79], v[66:67], v[78:79] neg_lo:[0,1] neg_hi:[0,1]
	global_load_dwordx2 v[84:85], v[8:9], off
	v_pk_add_f32 v[152:153], v[68:69], v[72:73] op_sel:[1,1] op_sel_hi:[0,0] neg_lo:[0,1] neg_hi:[1,0]
	v_pk_add_f32 v[150:151], v[68:69], v[72:73]
	v_pk_add_f32 v[156:157], v[80:81], v[116:117]
	v_pk_add_f32 v[80:81], v[80:81], v[116:117] neg_lo:[0,1] neg_hi:[0,1]
	v_pk_add_f32 v[116:117], v[96:97], v[132:133]
	v_pk_add_f32 v[68:69], v[96:97], v[132:133] neg_lo:[0,1] neg_hi:[0,1]
	v_pk_add_f32 v[96:97], v[98:99], v[126:127]
	v_pk_add_f32 v[98:99], v[98:99], v[126:127] neg_lo:[0,1] neg_hi:[0,1]
	v_pk_add_f32 v[126:127], v[122:123], v[120:121]
	v_pk_add_f32 v[66:67], v[122:123], v[120:121] neg_lo:[0,1] neg_hi:[0,1]
	global_load_dwordx2 v[120:121], v[20:21], off
	v_pk_add_f32 v[122:123], v[108:109], v[128:129]
	v_pk_add_f32 v[108:109], v[108:109], v[128:129] neg_lo:[0,1] neg_hi:[0,1]
	v_pk_add_f32 v[128:129], v[110:111], v[124:125]
	v_pk_add_f32 v[72:73], v[110:111], v[124:125] neg_lo:[0,1] neg_hi:[0,1]
	global_load_dwordx2 v[110:111], v[22:23], off
	v_pk_add_f32 v[144:145], v[90:91], v[70:71]
	v_pk_add_f32 v[90:91], v[90:91], v[70:71] op_sel:[1,1] op_sel_hi:[0,0] neg_lo:[0,1] neg_hi:[1,0]
	v_pk_add_f32 v[124:125], v[100:101], v[112:113]
	v_pk_add_f32 v[100:101], v[100:101], v[112:113] neg_lo:[0,1] neg_hi:[0,1]
	v_pk_add_f32 v[112:113], v[102:103], v[106:107]
	v_pk_add_f32 v[70:71], v[102:103], v[106:107] neg_lo:[0,1] neg_hi:[0,1]
	global_load_dwordx2 v[102:103], v[24:25], off
	v_pk_add_f32 v[106:107], v[82:83], v[118:119]
	v_pk_add_f32 v[82:83], v[82:83], v[118:119] neg_lo:[0,1] neg_hi:[0,1]
	v_pk_add_f32 v[118:119], v[114:115], v[130:131]
	v_pk_add_f32 v[114:115], v[114:115], v[130:131] neg_lo:[0,1] neg_hi:[0,1]
	global_load_dwordx2 v[130:131], v[26:27], off
	v_pk_add_f32 v[162:163], v[76:77], v[90:91]
	v_pk_add_f32 v[76:77], v[76:77], v[90:91] neg_lo:[0,1] neg_hi:[0,1]
	v_pk_add_f32 v[90:91], v[146:147], v[150:151]
	v_pk_add_f32 v[146:147], v[146:147], v[150:151] neg_lo:[0,1] neg_hi:[0,1]
	v_pk_add_f32 v[150:151], v[78:79], v[152:153]
	v_pk_add_f32 v[78:79], v[78:79], v[152:153] neg_lo:[0,1] neg_hi:[0,1]
	global_load_dwordx2 v[152:153], v[34:35], off
	s_waitcnt vmcnt(19)
	v_xor_b32_e32 v166, 0x80000000, v135
	v_mov_b32_e32 v167, v135
	v_pk_mul_f32 v[166:167], v[166:167], v[156:157] op_sel:[0,1] op_sel_hi:[1,0]
	v_pk_add_f32 v[132:133], v[140:141], v[92:93]
	v_pk_fma_f32 v[134:135], v[156:157], v[134:135], v[166:167] op_sel_hi:[1,0,1]
	s_waitcnt vmcnt(18)
	v_xor_b32_e32 v156, 0x80000000, v137
	v_mov_b32_e32 v157, v137
	global_load_dwordx2 v[166:167], v[38:39], off
	v_pk_mul_f32 v[156:157], v[156:157], v[106:107] op_sel:[0,1] op_sel_hi:[1,0]
	v_pk_add_f32 v[92:93], v[140:141], v[92:93] neg_lo:[0,1] neg_hi:[0,1]
	v_pk_fma_f32 v[106:107], v[106:107], v[136:137], v[156:157] op_sel_hi:[1,0,1]
	s_waitcnt vmcnt(18)
	v_xor_b32_e32 v136, 0x80000000, v139
	global_load_dwordx2 v[156:157], v[40:41], off
	v_mov_b32_e32 v137, v139
	v_pk_mul_f32 v[136:137], v[136:137], v[122:123] op_sel:[0,1] op_sel_hi:[1,0]
	v_pk_add_f32 v[140:141], v[88:89], v[142:143]
	v_pk_fma_f32 v[122:123], v[122:123], v[138:139], v[136:137] op_sel_hi:[1,0,1]
	global_load_dwordx2 v[136:137], v[42:43], off
	v_pk_add_f32 v[88:89], v[88:89], v[142:143] neg_lo:[0,1] neg_hi:[0,1]
	v_pk_add_f32 v[142:143], v[74:75], v[144:145]
	v_pk_add_f32 v[74:75], v[74:75], v[144:145] neg_lo:[0,1] neg_hi:[0,1]
	global_load_dwordx2 v[144:145], v[30:31], off
	s_mov_b32 s11, s8
	s_waitcnt vmcnt(9)
	v_xor_b32_e32 v138, 0x80000000, v85
	v_mov_b32_e32 v139, v85
	v_pk_mul_f32 v[138:139], v[138:139], v[142:143] op_sel:[0,1] op_sel_hi:[1,0]
	s_nop 0
	v_pk_fma_f32 v[84:85], v[142:143], v[84:85], v[138:139] op_sel_hi:[1,0,1]
	v_xor_b32_e32 v138, 0x80000000, v87
	v_mov_b32_e32 v139, v87
	global_load_dwordx2 v[142:143], v[46:47], off
	v_pk_mul_f32 v[138:139], v[138:139], v[96:97] op_sel:[0,1] op_sel_hi:[1,0]
	s_nop 0
	v_pk_fma_f32 v[86:87], v[96:97], v[86:87], v[138:139] op_sel_hi:[1,0,1]
	v_xor_b32_e32 v96, 0x80000000, v95
	global_load_dwordx2 v[138:139], v[48:49], off
	v_mov_b32_e32 v97, v95
	v_pk_mul_f32 v[96:97], v[96:97], v[132:133] op_sel:[0,1] op_sel_hi:[1,0]
	s_nop 0
	v_pk_fma_f32 v[94:95], v[132:133], v[94:95], v[96:97] op_sel_hi:[1,0,1]
	global_load_dwordx2 v[96:97], v[50:51], off
	v_xor_b32_e32 v132, 0x80000000, v149
	v_mov_b32_e32 v133, v149
	v_pk_mul_f32 v[132:133], v[132:133], v[124:125] op_sel:[0,1] op_sel_hi:[1,0]
	s_nop 0
	v_pk_fma_f32 v[124:125], v[124:125], v[148:149], v[132:133] op_sel_hi:[1,0,1]
	v_xor_b32_e32 v132, 0x80000000, v155
	v_mov_b32_e32 v133, v155
	global_load_dwordx2 v[148:149], v[54:55], off
	v_pk_mul_f32 v[132:133], v[132:133], v[90:91] op_sel:[0,1] op_sel_hi:[1,0]
	s_nop 0
	v_pk_fma_f32 v[90:91], v[90:91], v[154:155], v[132:133] op_sel_hi:[1,0,1]
	v_xor_b32_e32 v132, 0x80000000, v159
	global_load_dwordx2 v[154:155], v[56:57], off
	v_mov_b32_e32 v133, v159
	v_pk_mul_f32 v[132:133], v[116:117], v[132:133] op_sel:[1,0] op_sel_hi:[0,1]
	v_pk_fma_f32 v[116:117], v[116:117], v[158:159], v[132:133] op_sel_hi:[1,0,1]
	global_load_dwordx2 v[132:133], v[58:59], off
	s_waitcnt vmcnt(14)
	v_xor_b32_e32 v158, 0x80000000, v121
	v_mov_b32_e32 v159, v121
	v_pk_mul_f32 v[158:159], v[118:119], v[158:159] op_sel:[1,0] op_sel_hi:[0,1]
	v_pk_fma_f32 v[118:119], v[118:119], v[120:121], v[158:159] op_sel_hi:[1,0,1]
	s_waitcnt vmcnt(13)
	v_xor_b32_e32 v120, 0x80000000, v111
	v_mov_b32_e32 v121, v111
	global_load_dwordx2 v[158:159], v[62:63], off
	v_pk_mul_f32 v[120:121], v[128:129], v[120:121] op_sel:[1,0] op_sel_hi:[0,1]
	v_pk_fma_f32 v[110:111], v[128:129], v[110:111], v[120:121] op_sel_hi:[1,0,1]
	global_load_dwordx2 v[128:129], v[64:65], off
	s_waitcnt vmcnt(14)
	v_xor_b32_e32 v120, 0x80000000, v103
	v_mov_b32_e32 v121, v103
	v_pk_mul_f32 v[120:121], v[120:121], v[162:163] op_sel:[0,1] op_sel_hi:[1,0]
	v_mov_b32 v0, 0
	s_nop 0
	v_pk_fma_f32 v[102:103], v[162:163], v[102:103], v[120:121] op_sel_hi:[1,0,1]
	s_waitcnt vmcnt(13)
	v_xor_b32_e32 v120, 0x80000000, v131
	v_mov_b32_e32 v121, v131
	v_pk_mul_f32 v[120:121], v[126:127], v[120:121] op_sel:[1,0] op_sel_hi:[0,1]
	v_pk_fma_f32 v[120:121], v[126:127], v[130:131], v[120:121] op_sel_hi:[1,0,1]
	v_xor_b32_e32 v126, 0x80000000, v161
	v_mov_b32_e32 v127, v161
	v_pk_mul_f32 v[126:127], v[140:141], v[126:127] op_sel:[1,0] op_sel_hi:[0,1]
	v_pk_fma_f32 v[126:127], v[140:141], v[160:161], v[126:127] op_sel_hi:[1,0,1]
	s_waitcnt vmcnt(12)
	v_xor_b32_e32 v140, 0x80000000, v153
	v_mov_b32_e32 v141, v153
	v_pk_mul_f32 v[140:141], v[80:81], v[140:141] op_sel:[1,0] op_sel_hi:[0,1]
	v_pk_fma_f32 v[80:81], v[80:81], v[152:153], v[140:141] op_sel_hi:[1,0,1]
	v_xor_b32_e32 v140, 0x80000000, v169
	v_mov_b32_e32 v141, v169
	v_pk_mul_f32 v[140:141], v[82:83], v[140:141] op_sel:[1,0] op_sel_hi:[0,1]
	v_pk_fma_f32 v[82:83], v[82:83], v[168:169], v[140:141] op_sel_hi:[1,0,1]
	s_waitcnt vmcnt(11)
	v_xor_b32_e32 v140, 0x80000000, v167
	v_mov_b32_e32 v141, v167
	v_pk_mul_f32 v[140:141], v[108:109], v[140:141] op_sel:[1,0] op_sel_hi:[0,1]
	v_pk_fma_f32 v[108:109], v[108:109], v[166:167], v[140:141] op_sel_hi:[1,0,1]
	s_waitcnt vmcnt(10)
	v_xor_b32_e32 v140, 0x80000000, v157
	v_mov_b32_e32 v141, v157
	v_pk_mul_f32 v[140:141], v[74:75], v[140:141] op_sel:[1,0] op_sel_hi:[0,1]
	v_pk_fma_f32 v[74:75], v[74:75], v[156:157], v[140:141] op_sel_hi:[1,0,1]
	s_waitcnt vmcnt(9)
	v_xor_b32_e32 v140, 0x80000000, v137
	v_mov_b32_e32 v141, v137
	v_pk_mul_f32 v[140:141], v[98:99], v[140:141] op_sel:[1,0] op_sel_hi:[0,1]
	v_pk_fma_f32 v[98:99], v[98:99], v[136:137], v[140:141] op_sel_hi:[1,0,1]
	v_xor_b32_e32 v136, 0x80000000, v173
	v_mov_b32_e32 v137, v173
	v_pk_mul_f32 v[136:137], v[92:93], v[136:137] op_sel:[1,0] op_sel_hi:[0,1]
	v_pk_fma_f32 v[92:93], v[92:93], v[172:173], v[136:137] op_sel_hi:[1,0,1]
	s_waitcnt vmcnt(8)
	v_xor_b32_e32 v130, 0x80000000, v145
	v_mov_b32_e32 v131, v145
	v_pk_mul_f32 v[130:131], v[112:113], v[130:131] op_sel:[1,0] op_sel_hi:[0,1]
	v_pk_fma_f32 v[112:113], v[112:113], v[144:145], v[130:131] op_sel_hi:[1,0,1]
	s_waitcnt vmcnt(7)
	v_xor_b32_e32 v136, 0x80000000, v143
	v_mov_b32_e32 v137, v143
	v_pk_mul_f32 v[136:137], v[100:101], v[136:137] op_sel:[1,0] op_sel_hi:[0,1]
	v_pk_fma_f32 v[100:101], v[100:101], v[142:143], v[136:137] op_sel_hi:[1,0,1]
	v_xor_b32_e32 v130, 0x80000000, v165
	s_waitcnt vmcnt(6)
	v_xor_b32_e32 v136, 0x80000000, v139
	v_mov_b32_e32 v137, v139
	v_pk_mul_f32 v[136:137], v[146:147], v[136:137] op_sel:[1,0] op_sel_hi:[0,1]
	v_pk_fma_f32 v[136:137], v[146:147], v[138:139], v[136:137] op_sel_hi:[1,0,1]
	v_mov_b32_e32 v131, v165
	s_waitcnt vmcnt(5)
	v_xor_b32_e32 v138, 0x80000000, v97
	v_mov_b32_e32 v139, v97
	v_pk_mul_f32 v[138:139], v[68:69], v[138:139] op_sel:[1,0] op_sel_hi:[0,1]
	v_pk_fma_f32 v[68:69], v[68:69], v[96:97], v[138:139] op_sel_hi:[1,0,1]
	v_xor_b32_e32 v96, 0x80000000, v175
	v_mov_b32_e32 v97, v175
	v_pk_mul_f32 v[96:97], v[114:115], v[96:97] op_sel:[1,0] op_sel_hi:[0,1]
	v_pk_fma_f32 v[96:97], v[114:115], v[174:175], v[96:97] op_sel_hi:[1,0,1]
	s_waitcnt vmcnt(4)
	v_xor_b32_e32 v114, 0x80000000, v149
	v_mov_b32_e32 v115, v149
	v_pk_mul_f32 v[114:115], v[72:73], v[114:115] op_sel:[1,0] op_sel_hi:[0,1]
	v_pk_fma_f32 v[72:73], v[72:73], v[148:149], v[114:115] op_sel_hi:[1,0,1]
	v_pk_mul_f32 v[130:131], v[150:151], v[130:131] op_sel:[1,0] op_sel_hi:[0,1]
	s_waitcnt vmcnt(3)
	v_xor_b32_e32 v114, 0x80000000, v155
	v_mov_b32_e32 v115, v155
	v_pk_mul_f32 v[114:115], v[76:77], v[114:115] op_sel:[1,0] op_sel_hi:[0,1]
	v_pk_fma_f32 v[76:77], v[76:77], v[154:155], v[114:115] op_sel_hi:[1,0,1]
	s_waitcnt vmcnt(2)
	v_xor_b32_e32 v114, 0x80000000, v133
	v_mov_b32_e32 v115, v133
	v_pk_mul_f32 v[114:115], v[66:67], v[114:115] op_sel:[1,0] op_sel_hi:[0,1]
	v_pk_fma_f32 v[66:67], v[66:67], v[132:133], v[114:115] op_sel_hi:[1,0,1]
	v_xor_b32_e32 v114, 0x80000000, v177
	v_mov_b32_e32 v115, v177
	v_pk_mul_f32 v[114:115], v[88:89], v[114:115] op_sel:[1,0] op_sel_hi:[0,1]
	v_pk_fma_f32 v[88:89], v[88:89], v[176:177], v[114:115] op_sel_hi:[1,0,1]
	s_waitcnt vmcnt(1)
	v_xor_b32_e32 v114, 0x80000000, v159
	v_mov_b32_e32 v115, v159
	v_pk_mul_f32 v[114:115], v[70:71], v[114:115] op_sel:[1,0] op_sel_hi:[0,1]
	v_pk_fma_f32 v[70:71], v[70:71], v[158:159], v[114:115] op_sel_hi:[1,0,1]
	s_waitcnt vmcnt(0)
	v_xor_b32_e32 v114, 0x80000000, v129
	v_mov_b32_e32 v115, v129
	v_pk_mul_f32 v[114:115], v[78:79], v[114:115] op_sel:[1,0] op_sel_hi:[0,1]
	v_pk_fma_f32 v[78:79], v[78:79], v[128:129], v[114:115] op_sel_hi:[1,0,1]
	v_pk_add_f32 v[128:129], v[106:107], v[82:83]
	v_pk_add_f32 v[82:83], v[106:107], v[82:83] neg_lo:[0,1] neg_hi:[0,1]
	v_pk_fma_f32 v[130:131], v[150:151], v[164:165], v[130:131] op_sel_hi:[1,0,1]
	v_pk_mul_f32 v[106:107], v[82:83], s[50:51]
	v_pk_add_f32 v[114:115], v[134:135], v[80:81]
	v_pk_fma_f32 v[82:83], v[82:83], s[20:21], v[106:107] op_sel:[0,0,1] op_sel_hi:[1,0,0]
	v_pk_add_f32 v[106:107], v[122:123], v[108:109]
	v_pk_add_f32 v[108:109], v[122:123], v[108:109] neg_lo:[0,1] neg_hi:[0,1]
	s_mov_b32 s21, s34
	v_pk_mul_f32 v[122:123], v[108:109], s[14:15]
	v_pk_add_f32 v[80:81], v[134:135], v[80:81] neg_lo:[0,1] neg_hi:[0,1]
	v_pk_fma_f32 v[108:109], v[108:109], s[6:7], v[122:123] op_sel:[0,0,1] op_sel_hi:[1,0,0]
	v_pk_add_f32 v[122:123], v[84:85], v[74:75]
	v_pk_add_f32 v[74:75], v[84:85], v[74:75] neg_lo:[0,1] neg_hi:[0,1]
	s_mov_b32 s7, s12
	v_pk_mul_f32 v[84:85], v[74:75], s[52:53]
	v_add_u32_e32 v0, v0, v170
	v_pk_fma_f32 v[74:75], v[74:75], s[24:25], v[84:85] op_sel:[0,0,1] op_sel_hi:[1,0,0]
	v_pk_add_f32 v[84:85], v[86:87], v[98:99]
	v_pk_add_f32 v[86:87], v[86:87], v[98:99] neg_lo:[0,1] neg_hi:[0,1]
	s_mov_b32 s25, s26
	v_pk_mul_f32 v[98:99], v[86:87], s[10:11]
	v_lshlrev_b32_e32 v105, 5, v0
	v_pk_fma_f32 v[86:87], v[86:87], s[10:11], v[98:99] op_sel:[0,0,1] op_sel_hi:[1,0,0]
	v_pk_add_f32 v[98:99], v[94:95], v[92:93]
	v_pk_add_f32 v[92:93], v[94:95], v[92:93] neg_lo:[0,1] neg_hi:[0,1]
	s_nop 0
	v_pk_mul_f32 v[94:95], v[92:93], s[24:25]
	s_nop 0
	v_pk_fma_f32 v[92:93], v[92:93], s[0:1], v[94:95] op_sel:[0,0,1] op_sel_hi:[1,0,0]
	v_pk_add_f32 v[94:95], v[124:125], v[100:101]
	v_pk_add_f32 v[100:101], v[124:125], v[100:101] neg_lo:[0,1] neg_hi:[0,1]
	s_nop 0
	v_pk_mul_f32 v[124:125], v[100:101], s[6:7]
	s_nop 0
	v_pk_fma_f32 v[100:101], v[100:101], s[14:15], v[124:125] op_sel:[0,0,1] op_sel_hi:[1,0,0]
	v_pk_add_f32 v[124:125], v[90:91], v[136:137]
	v_pk_add_f32 v[90:91], v[90:91], v[136:137] neg_lo:[0,1] neg_hi:[0,1]
	s_nop 0
	v_pk_mul_f32 v[132:133], v[90:91], s[20:21]
	s_nop 0
	v_pk_fma_f32 v[90:91], v[90:91], s[48:49], v[132:133] op_sel:[0,0,1] op_sel_hi:[1,0,0]
	v_pk_add_f32 v[132:133], v[116:117], v[68:69]
	v_pk_add_f32 v[116:117], v[116:117], v[68:69] op_sel:[1,1] op_sel_hi:[0,0] neg_lo:[1,0] neg_hi:[0,1]
	s_nop 0
	v_pk_add_f32 v[68:69], v[118:119], v[96:97]
	v_pk_add_f32 v[96:97], v[118:119], v[96:97] neg_lo:[0,1] neg_hi:[0,1]
	s_nop 0
	v_pk_mul_f32 v[118:119], v[96:97], s[20:21]
	s_nop 0
	v_pk_fma_f32 v[96:97], v[96:97], s[18:19], v[118:119] op_sel:[0,0,1] op_sel_hi:[1,0,0]
	v_pk_add_f32 v[118:119], v[110:111], v[72:73]
	v_pk_add_f32 v[72:73], v[110:111], v[72:73] neg_lo:[0,1] neg_hi:[0,1]
	s_nop 0
	v_pk_mul_f32 v[110:111], v[72:73], s[6:7]
	s_nop 0
	v_pk_fma_f32 v[72:73], v[72:73], s[4:5], v[110:111] op_sel:[0,0,1] op_sel_hi:[1,0,0]
	v_pk_add_f32 v[110:111], v[102:103], v[76:77]
	v_pk_add_f32 v[76:77], v[102:103], v[76:77] neg_lo:[0,1] neg_hi:[0,1]
	s_nop 0
	v_pk_mul_f32 v[102:103], v[76:77], s[24:25]
	s_nop 0
	v_pk_fma_f32 v[76:77], v[76:77], s[22:23], v[102:103] op_sel:[0,0,1] op_sel_hi:[1,0,0]
	v_pk_add_f32 v[102:103], v[120:121], v[66:67]
	v_pk_add_f32 v[66:67], v[120:121], v[66:67] neg_lo:[0,1] neg_hi:[0,1]
	s_nop 0
	v_pk_mul_f32 v[120:121], v[66:67], s[10:11]
	s_nop 0
	v_pk_fma_f32 v[66:67], v[66:67], s[8:9], v[120:121] op_sel:[0,0,1] op_sel_hi:[1,0,0]
	v_pk_add_f32 v[120:121], v[126:127], v[88:89]
	v_pk_add_f32 v[88:89], v[126:127], v[88:89] neg_lo:[0,1] neg_hi:[0,1]
	s_nop 0
	v_pk_mul_f32 v[126:127], v[88:89], s[52:53]
	s_nop 0
	v_pk_fma_f32 v[88:89], v[88:89], s[26:27], v[126:127] op_sel:[0,0,1] op_sel_hi:[1,0,0]
	v_pk_add_f32 v[126:127], v[112:113], v[70:71]
	v_pk_add_f32 v[70:71], v[112:113], v[70:71] neg_lo:[0,1] neg_hi:[0,1]
	s_nop 0
	v_pk_mul_f32 v[112:113], v[70:71], s[14:15]
	s_nop 0
	v_pk_fma_f32 v[70:71], v[70:71], s[12:13], v[112:113] op_sel:[0,0,1] op_sel_hi:[1,0,0]
	v_pk_add_f32 v[112:113], v[130:131], v[78:79]
	v_pk_add_f32 v[78:79], v[130:131], v[78:79] neg_lo:[0,1] neg_hi:[0,1]
	s_nop 0
	v_pk_mul_f32 v[130:131], v[78:79], s[50:51]
	s_nop 0
	v_pk_fma_f32 v[78:79], v[78:79], s[34:35], v[130:131] op_sel:[0,0,1] op_sel_hi:[1,0,0]
	v_pk_add_f32 v[130:131], v[114:115], v[132:133]
	v_pk_add_f32 v[114:115], v[114:115], v[132:133] neg_lo:[0,1] neg_hi:[0,1]
	v_pk_add_f32 v[132:133], v[128:129], v[68:69]
	v_pk_add_f32 v[68:69], v[128:129], v[68:69] neg_lo:[0,1] neg_hi:[0,1]
	s_nop 0
	v_pk_mul_f32 v[128:129], v[68:69], s[14:15]
	s_nop 0
	v_pk_fma_f32 v[68:69], v[68:69], s[6:7], v[128:129] op_sel:[0,0,1] op_sel_hi:[1,0,0]
	v_pk_add_f32 v[128:129], v[106:107], v[118:119]
	v_pk_add_f32 v[106:107], v[106:107], v[118:119] neg_lo:[0,1] neg_hi:[0,1]
	s_nop 0
	v_pk_mul_f32 v[118:119], v[106:107], s[10:11]
	s_nop 0
	v_pk_fma_f32 v[106:107], v[106:107], s[10:11], v[118:119] op_sel:[0,0,1] op_sel_hi:[1,0,0]
	v_pk_add_f32 v[118:119], v[122:123], v[110:111]
	v_pk_add_f32 v[110:111], v[122:123], v[110:111] neg_lo:[0,1] neg_hi:[0,1]
	s_nop 0
	v_pk_mul_f32 v[122:123], v[110:111], s[6:7]
	s_nop 0
	v_pk_fma_f32 v[110:111], v[110:111], s[14:15], v[122:123] op_sel:[0,0,1] op_sel_hi:[1,0,0]
	v_pk_add_f32 v[122:123], v[84:85], v[102:103]
	v_pk_add_f32 v[102:103], v[84:85], v[102:103] op_sel:[1,1] op_sel_hi:[0,0] neg_lo:[1,0] neg_hi:[0,1]
	s_nop 0
	v_pk_add_f32 v[84:85], v[98:99], v[120:121]
	v_pk_add_f32 v[98:99], v[98:99], v[120:121] neg_lo:[0,1] neg_hi:[0,1]
	s_nop 0
	v_pk_mul_f32 v[120:121], v[98:99], s[6:7]
	s_nop 0
	v_pk_fma_f32 v[98:99], v[98:99], s[4:5], v[120:121] op_sel:[0,0,1] op_sel_hi:[1,0,0]
	v_pk_add_f32 v[120:121], v[94:95], v[126:127]
	v_pk_add_f32 v[94:95], v[94:95], v[126:127] neg_lo:[0,1] neg_hi:[0,1]
	s_nop 0
	v_pk_mul_f32 v[126:127], v[94:95], s[10:11]
	s_nop 0
	v_pk_fma_f32 v[94:95], v[94:95], s[8:9], v[126:127] op_sel:[0,0,1] op_sel_hi:[1,0,0]
	v_pk_add_f32 v[126:127], v[124:125], v[112:113]
	v_pk_add_f32 v[112:113], v[124:125], v[112:113] neg_lo:[0,1] neg_hi:[0,1]
	s_nop 0
	v_pk_mul_f32 v[124:125], v[112:113], s[14:15]
	s_nop 0
	v_pk_fma_f32 v[112:113], v[112:113], s[12:13], v[124:125] op_sel:[0,0,1] op_sel_hi:[1,0,0]
	v_pk_add_f32 v[124:125], v[80:81], v[116:117]
	v_pk_add_f32 v[80:81], v[80:81], v[116:117] neg_lo:[0,1] neg_hi:[0,1]
	v_pk_add_f32 v[116:117], v[82:83], v[96:97]
	v_pk_add_f32 v[82:83], v[82:83], v[96:97] neg_lo:[0,1] neg_hi:[0,1]
	s_nop 0
	v_pk_mul_f32 v[96:97], v[82:83], s[14:15]
	s_nop 0
	v_pk_fma_f32 v[82:83], v[82:83], s[6:7], v[96:97] op_sel:[0,0,1] op_sel_hi:[1,0,0]
	v_pk_add_f32 v[96:97], v[108:109], v[72:73]
	v_pk_add_f32 v[72:73], v[108:109], v[72:73] neg_lo:[0,1] neg_hi:[0,1]
	s_nop 0
	v_pk_mul_f32 v[108:109], v[72:73], s[10:11]
	s_nop 0
	v_pk_fma_f32 v[72:73], v[72:73], s[10:11], v[108:109] op_sel:[0,0,1] op_sel_hi:[1,0,0]
	v_pk_add_f32 v[108:109], v[74:75], v[76:77]
	v_pk_add_f32 v[74:75], v[74:75], v[76:77] neg_lo:[0,1] neg_hi:[0,1]
	s_nop 0
	v_pk_mul_f32 v[76:77], v[74:75], s[6:7]
	s_nop 0
	v_pk_fma_f32 v[74:75], v[74:75], s[14:15], v[76:77] op_sel:[0,0,1] op_sel_hi:[1,0,0]
	v_pk_add_f32 v[76:77], v[86:87], v[66:67]
	v_pk_add_f32 v[86:87], v[86:87], v[66:67] op_sel:[1,1] op_sel_hi:[0,0] neg_lo:[1,0] neg_hi:[0,1]
	s_nop 0
	v_pk_add_f32 v[66:67], v[92:93], v[88:89]
	v_pk_add_f32 v[88:89], v[92:93], v[88:89] neg_lo:[0,1] neg_hi:[0,1]
	s_nop 0
	v_pk_mul_f32 v[92:93], v[88:89], s[6:7]
	s_nop 0
	v_pk_fma_f32 v[88:89], v[88:89], s[4:5], v[92:93] op_sel:[0,0,1] op_sel_hi:[1,0,0]
	v_pk_add_f32 v[92:93], v[100:101], v[70:71]
	v_pk_add_f32 v[70:71], v[100:101], v[70:71] neg_lo:[0,1] neg_hi:[0,1]
	s_nop 0
	v_pk_mul_f32 v[100:101], v[70:71], s[10:11]
	s_nop 0
	v_pk_fma_f32 v[70:71], v[70:71], s[8:9], v[100:101] op_sel:[0,0,1] op_sel_hi:[1,0,0]
	v_pk_add_f32 v[100:101], v[90:91], v[78:79]
	v_pk_add_f32 v[78:79], v[90:91], v[78:79] neg_lo:[0,1] neg_hi:[0,1]
	s_nop 0
	v_pk_mul_f32 v[90:91], v[78:79], s[14:15]
	s_nop 0
	v_pk_fma_f32 v[78:79], v[78:79], s[12:13], v[90:91] op_sel:[0,0,1] op_sel_hi:[1,0,0]
	v_pk_add_f32 v[90:91], v[130:131], v[122:123]
	v_pk_add_f32 v[122:123], v[130:131], v[122:123] neg_lo:[0,1] neg_hi:[0,1]
	v_pk_add_f32 v[130:131], v[132:133], v[84:85]
	v_pk_add_f32 v[84:85], v[132:133], v[84:85] neg_lo:[0,1] neg_hi:[0,1]
	s_nop 0
	v_pk_mul_f32 v[132:133], v[84:85], s[10:11]
	s_nop 0
	v_pk_fma_f32 v[84:85], v[84:85], s[10:11], v[132:133] op_sel:[0,0,1] op_sel_hi:[1,0,0]
	v_pk_add_f32 v[132:133], v[128:129], v[120:121]
	v_pk_add_f32 v[128:129], v[128:129], v[120:121] op_sel:[1,1] op_sel_hi:[0,0] neg_lo:[1,0] neg_hi:[0,1]
	s_nop 0
	v_pk_add_f32 v[120:121], v[118:119], v[126:127]
	v_pk_add_f32 v[118:119], v[118:119], v[126:127] neg_lo:[0,1] neg_hi:[0,1]
	s_nop 0
	v_pk_mul_f32 v[126:127], v[118:119], s[10:11]
	s_nop 0
	v_pk_fma_f32 v[118:119], v[118:119], s[8:9], v[126:127] op_sel:[0,0,1] op_sel_hi:[1,0,0]
	v_pk_add_f32 v[126:127], v[114:115], v[102:103]
	v_pk_add_f32 v[102:103], v[114:115], v[102:103] neg_lo:[0,1] neg_hi:[0,1]
	v_pk_add_f32 v[114:115], v[68:69], v[98:99]
	v_pk_add_f32 v[68:69], v[68:69], v[98:99] neg_lo:[0,1] neg_hi:[0,1]
	s_nop 0
	v_pk_mul_f32 v[98:99], v[68:69], s[10:11]
	s_nop 0
	v_pk_fma_f32 v[68:69], v[68:69], s[10:11], v[98:99] op_sel:[0,0,1] op_sel_hi:[1,0,0]
	v_pk_add_f32 v[98:99], v[106:107], v[94:95]
	v_pk_add_f32 v[106:107], v[106:107], v[94:95] op_sel:[1,1] op_sel_hi:[0,0] neg_lo:[1,0] neg_hi:[0,1]
	s_nop 0
	v_pk_add_f32 v[94:95], v[110:111], v[112:113]
	v_pk_add_f32 v[110:111], v[110:111], v[112:113] neg_lo:[0,1] neg_hi:[0,1]
	s_nop 0
	v_pk_mul_f32 v[112:113], v[110:111], s[10:11]
	s_nop 0
	v_pk_fma_f32 v[110:111], v[110:111], s[8:9], v[112:113] op_sel:[0,0,1] op_sel_hi:[1,0,0]
	v_pk_add_f32 v[112:113], v[124:125], v[76:77]
	v_pk_add_f32 v[76:77], v[124:125], v[76:77] neg_lo:[0,1] neg_hi:[0,1]
	v_pk_add_f32 v[124:125], v[116:117], v[66:67]
	v_pk_add_f32 v[66:67], v[116:117], v[66:67] neg_lo:[0,1] neg_hi:[0,1]
	s_nop 0
	v_pk_mul_f32 v[116:117], v[66:67], s[10:11]
	s_nop 0
	v_pk_fma_f32 v[66:67], v[66:67], s[10:11], v[116:117] op_sel:[0,0,1] op_sel_hi:[1,0,0]
	v_pk_add_f32 v[116:117], v[96:97], v[92:93]
	v_pk_add_f32 v[96:97], v[96:97], v[92:93] op_sel:[1,1] op_sel_hi:[0,0] neg_lo:[1,0] neg_hi:[0,1]
	v_pk_add_f32 v[134:135], v[112:113], v[116:117]
	v_pk_add_f32 v[92:93], v[108:109], v[100:101]
	v_pk_add_f32 v[100:101], v[108:109], v[100:101] neg_lo:[0,1] neg_hi:[0,1]
	v_pk_add_f32 v[112:113], v[112:113], v[116:117] neg_lo:[0,1] neg_hi:[0,1]
	v_pk_mul_f32 v[108:109], v[100:101], s[10:11]
	v_pk_add_f32 v[116:117], v[124:125], v[92:93]
	v_pk_fma_f32 v[100:101], v[100:101], s[8:9], v[108:109] op_sel:[0,0,1] op_sel_hi:[1,0,0]
	v_pk_add_f32 v[108:109], v[80:81], v[86:87]
	v_pk_add_f32 v[80:81], v[80:81], v[86:87] neg_lo:[0,1] neg_hi:[0,1]
	v_pk_add_f32 v[86:87], v[82:83], v[88:89]
	v_pk_add_f32 v[82:83], v[82:83], v[88:89] neg_lo:[0,1] neg_hi:[0,1]
	s_nop 0
	v_pk_mul_f32 v[88:89], v[82:83], s[10:11]
	s_nop 0
	v_pk_fma_f32 v[82:83], v[82:83], s[10:11], v[88:89] op_sel:[0,0,1] op_sel_hi:[1,0,0]
	v_pk_add_f32 v[88:89], v[72:73], v[70:71]
	v_pk_add_f32 v[72:73], v[72:73], v[70:71] op_sel:[1,1] op_sel_hi:[0,0] neg_lo:[1,0] neg_hi:[0,1]
	v_pk_add_f32 v[136:137], v[108:109], v[88:89]
	v_pk_add_f32 v[70:71], v[74:75], v[78:79]
	v_pk_add_f32 v[74:75], v[74:75], v[78:79] neg_lo:[0,1] neg_hi:[0,1]
	v_pk_add_f32 v[88:89], v[108:109], v[88:89] neg_lo:[0,1] neg_hi:[0,1]
	v_pk_mul_f32 v[78:79], v[74:75], s[10:11]
	v_pk_add_f32 v[108:109], v[86:87], v[70:71]
	v_pk_fma_f32 v[74:75], v[74:75], s[8:9], v[78:79] op_sel:[0,0,1] op_sel_hi:[1,0,0]
	v_pk_add_f32 v[78:79], v[90:91], v[132:133]
	v_pk_add_f32 v[90:91], v[90:91], v[132:133] neg_lo:[0,1] neg_hi:[0,1]
	v_pk_add_f32 v[132:133], v[130:131], v[120:121]
	v_pk_add_f32 v[130:131], v[130:131], v[120:121] op_sel:[1,1] op_sel_hi:[0,0] neg_lo:[1,0] neg_hi:[0,1]
	v_pk_add_f32 v[138:139], v[80:81], v[72:73] neg_lo:[0,1] neg_hi:[0,1]
	v_pk_add_f32 v[120:121], v[122:123], v[128:129]
	v_pk_add_f32 v[122:123], v[122:123], v[128:129] neg_lo:[0,1] neg_hi:[0,1]
	v_pk_add_f32 v[128:129], v[84:85], v[118:119]
	v_pk_add_f32 v[118:119], v[84:85], v[118:119] op_sel:[1,1] op_sel_hi:[0,0] neg_lo:[1,0] neg_hi:[0,1]
	v_pk_add_f32 v[140:141], v[82:83], v[74:75]
	v_pk_add_f32 v[84:85], v[126:127], v[98:99]
	v_pk_add_f32 v[98:99], v[126:127], v[98:99] neg_lo:[0,1] neg_hi:[0,1]
	v_pk_add_f32 v[126:127], v[114:115], v[94:95]
	v_pk_add_f32 v[114:115], v[114:115], v[94:95] op_sel:[1,1] op_sel_hi:[0,0] neg_lo:[1,0] neg_hi:[0,1]
	v_pk_add_f32 v[142:143], v[78:79], v[132:133]
	v_pk_add_f32 v[94:95], v[102:103], v[106:107]
	v_pk_add_f32 v[102:103], v[102:103], v[106:107] neg_lo:[0,1] neg_hi:[0,1]
	v_pk_add_f32 v[106:107], v[68:69], v[110:111]
	v_pk_add_f32 v[110:111], v[68:69], v[110:111] op_sel:[1,1] op_sel_hi:[0,0] neg_lo:[1,0] neg_hi:[0,1]
	v_pk_add_f32 v[132:133], v[78:79], v[132:133] neg_lo:[0,1] neg_hi:[0,1]
	v_pk_add_f32 v[92:93], v[124:125], v[92:93] op_sel:[1,1] op_sel_hi:[0,0] neg_lo:[1,0] neg_hi:[0,1]
	v_pk_add_f32 v[124:125], v[76:77], v[96:97]
	v_pk_add_f32 v[76:77], v[76:77], v[96:97] neg_lo:[0,1] neg_hi:[0,1]
	v_pk_add_f32 v[96:97], v[66:67], v[100:101]
	v_pk_add_f32 v[100:101], v[66:67], v[100:101] op_sel:[1,1] op_sel_hi:[0,0] neg_lo:[1,0] neg_hi:[0,1]
	v_pk_add_f32 v[70:71], v[86:87], v[70:71] op_sel:[1,1] op_sel_hi:[0,0] neg_lo:[1,0] neg_hi:[0,1]
	v_pk_add_f32 v[74:75], v[82:83], v[74:75] op_sel:[1,1] op_sel_hi:[0,0] neg_lo:[1,0] neg_hi:[0,1]
	v_pk_add_f32 v[86:87], v[80:81], v[72:73]
	v_pk_add_f32 v[144:145], v[90:91], v[130:131]
	v_pk_add_f32 v[82:83], v[90:91], v[130:131] neg_lo:[0,1] neg_hi:[0,1]
	v_pk_add_f32 v[90:91], v[120:121], v[128:129]
	v_pk_add_f32 v[120:121], v[120:121], v[128:129] neg_lo:[0,1] neg_hi:[0,1]
	v_pk_add_f32 v[128:129], v[122:123], v[118:119]
	v_pk_add_f32 v[68:69], v[122:123], v[118:119] neg_lo:[0,1] neg_hi:[0,1]
	v_pk_add_f32 v[118:119], v[84:85], v[126:127]
	v_pk_add_f32 v[122:123], v[84:85], v[126:127] neg_lo:[0,1] neg_hi:[0,1]
	v_pk_add_f32 v[126:127], v[98:99], v[114:115]
	v_pk_add_f32 v[78:79], v[98:99], v[114:115] neg_lo:[0,1] neg_hi:[0,1]
	v_pk_add_f32 v[98:99], v[94:95], v[106:107]
	v_pk_add_f32 v[94:95], v[94:95], v[106:107] neg_lo:[0,1] neg_hi:[0,1]
	v_pk_add_f32 v[106:107], v[102:103], v[110:111]
	v_pk_add_f32 v[66:67], v[102:103], v[110:111] neg_lo:[0,1] neg_hi:[0,1]
	v_pk_add_f32 v[102:103], v[134:135], v[116:117]
	v_pk_add_f32 v[110:111], v[134:135], v[116:117] neg_lo:[0,1] neg_hi:[0,1]
	v_pk_add_f32 v[116:117], v[88:89], v[70:71]
	v_pk_add_f32 v[80:81], v[88:89], v[70:71] neg_lo:[0,1] neg_hi:[0,1]
	v_lshlrev_b32_e32 v70, 4, v0
	v_and_b32_e32 v70, 0x1f0, v70
	v_pk_add_f32 v[114:115], v[112:113], v[92:93]
	v_pk_add_f32 v[84:85], v[112:113], v[92:93] neg_lo:[0,1] neg_hi:[0,1]
	v_pk_add_f32 v[112:113], v[76:77], v[100:101]
	v_pk_add_f32 v[72:73], v[76:77], v[100:101] neg_lo:[0,1] neg_hi:[0,1]
	v_cvt_f32_u32_e32 v76, v70
	v_pk_add_f32 v[92:93], v[124:125], v[96:97]
	v_pk_add_f32 v[96:97], v[124:125], v[96:97] neg_lo:[0,1] neg_hi:[0,1]
	v_pk_add_f32 v[124:125], v[138:139], v[74:75]
	v_mul_f32_e32 v76, 0x38800000, v76
	v_pk_add_f32 v[70:71], v[138:139], v[74:75] neg_lo:[0,1] neg_hi:[0,1]
	v_sin_f32_e32 v75, v76
	v_ashrrev_i32_e32 v74, 2, v105
	v_lshlrev_b32_e32 v0, 8, v0
	v_add3_u32 v0, 0, v74, v0
	v_cos_f32_e32 v74, v76
	v_xor_b32_e32 v76, 0x80000000, v75
	v_mov_b32_e32 v77, v75
	v_pk_mul_f32 v[130:131], v[76:77], v[102:103] op_sel:[0,1] op_sel_hi:[1,0]
	v_pk_add_f32 v[100:101], v[136:137], v[108:109]
	v_pk_fma_f32 v[102:103], v[102:103], v[74:75], v[130:131] op_sel_hi:[1,0,1]
	ds_write2_b64 v0, v[142:143], v[102:103] offset1:1
	v_pk_mul_f32 v[102:103], v[76:77], v[74:75] op_sel:[0,1] op_sel_hi:[1,0]
	v_pk_add_f32 v[88:89], v[86:87], v[140:141]
	v_pk_fma_f32 v[102:103], v[74:75], v[74:75], v[102:103] op_sel_hi:[1,0,1]
	v_pk_add_f32 v[108:109], v[136:137], v[108:109] neg_lo:[0,1] neg_hi:[0,1]
	v_xor_b32_e32 v130, 0x80000000, v103
	v_mov_b32_e32 v131, v103
	v_pk_mul_f32 v[130:131], v[118:119], v[130:131] op_sel:[1,0] op_sel_hi:[0,1]
	v_pk_fma_f32 v[118:119], v[118:119], v[102:103], v[130:131] op_sel_hi:[1,0,1]
	v_pk_mul_f32 v[130:131], v[76:77], v[102:103] op_sel:[0,1] op_sel_hi:[1,0]
	v_pk_add_f32 v[86:87], v[86:87], v[140:141] neg_lo:[0,1] neg_hi:[0,1]
	v_pk_fma_f32 v[102:103], v[102:103], v[74:75], v[130:131] op_sel_hi:[1,0,1]
	s_nop 0
	v_xor_b32_e32 v130, 0x80000000, v103
	v_mov_b32_e32 v131, v103
	v_pk_mul_f32 v[130:131], v[100:101], v[130:131] op_sel:[1,0] op_sel_hi:[0,1]
	v_pk_fma_f32 v[100:101], v[100:101], v[102:103], v[130:131] op_sel_hi:[1,0,1]
	ds_write2_b64 v0, v[118:119], v[100:101] offset0:2 offset1:3
	v_pk_mul_f32 v[100:101], v[76:77], v[102:103] op_sel:[0,1] op_sel_hi:[1,0]
	s_nop 0
	v_pk_fma_f32 v[100:101], v[102:103], v[74:75], v[100:101] op_sel_hi:[1,0,1]
	s_nop 0
	v_xor_b32_e32 v102, 0x80000000, v101
	v_mov_b32_e32 v103, v101
	v_pk_mul_f32 v[102:103], v[90:91], v[102:103] op_sel:[1,0] op_sel_hi:[0,1]
	v_pk_fma_f32 v[90:91], v[90:91], v[100:101], v[102:103] op_sel_hi:[1,0,1]
	v_pk_mul_f32 v[102:103], v[76:77], v[100:101] op_sel:[0,1] op_sel_hi:[1,0]
	s_nop 0
	v_pk_fma_f32 v[100:101], v[100:101], v[74:75], v[102:103] op_sel_hi:[1,0,1]
	s_nop 0
	v_xor_b32_e32 v102, 0x80000000, v101
	v_mov_b32_e32 v103, v101
	v_pk_mul_f32 v[102:103], v[92:93], v[102:103] op_sel:[1,0] op_sel_hi:[0,1]
	v_pk_fma_f32 v[92:93], v[92:93], v[100:101], v[102:103] op_sel_hi:[1,0,1]
	ds_write2_b64 v0, v[90:91], v[92:93] offset0:4 offset1:5
	v_pk_mul_f32 v[90:91], v[76:77], v[100:101] op_sel:[0,1] op_sel_hi:[1,0]
	s_nop 0
	v_pk_fma_f32 v[90:91], v[100:101], v[74:75], v[90:91] op_sel_hi:[1,0,1]
	s_nop 0
	v_xor_b32_e32 v92, 0x80000000, v91
	v_mov_b32_e32 v93, v91
	v_pk_mul_f32 v[92:93], v[98:99], v[92:93] op_sel:[1,0] op_sel_hi:[0,1]
	v_pk_fma_f32 v[92:93], v[98:99], v[90:91], v[92:93] op_sel_hi:[1,0,1]
	v_pk_mul_f32 v[98:99], v[76:77], v[90:91] op_sel:[0,1] op_sel_hi:[1,0]
	s_nop 0
	v_pk_fma_f32 v[90:91], v[90:91], v[74:75], v[98:99] op_sel_hi:[1,0,1]
	s_nop 0
	v_xor_b32_e32 v98, 0x80000000, v91
	v_mov_b32_e32 v99, v91
	v_pk_mul_f32 v[98:99], v[88:89], v[98:99] op_sel:[1,0] op_sel_hi:[0,1]
	v_pk_fma_f32 v[88:89], v[88:89], v[90:91], v[98:99] op_sel_hi:[1,0,1]
	ds_write2_b64 v0, v[92:93], v[88:89] offset0:6 offset1:7
	v_pk_mul_f32 v[88:89], v[76:77], v[90:91] op_sel:[0,1] op_sel_hi:[1,0]
	s_nop 0
	v_pk_fma_f32 v[88:89], v[90:91], v[74:75], v[88:89] op_sel_hi:[1,0,1]
	s_nop 0
	v_xor_b32_e32 v90, 0x80000000, v89
	v_mov_b32_e32 v91, v89
	v_pk_mul_f32 v[90:91], v[144:145], v[90:91] op_sel:[1,0] op_sel_hi:[0,1]
	v_pk_mul_f32 v[92:93], v[76:77], v[88:89] op_sel:[0,1] op_sel_hi:[1,0]
	v_pk_fma_f32 v[90:91], v[144:145], v[88:89], v[90:91] op_sel_hi:[1,0,1]
	v_pk_fma_f32 v[88:89], v[88:89], v[74:75], v[92:93] op_sel_hi:[1,0,1]
	s_nop 0
	v_xor_b32_e32 v92, 0x80000000, v89
	v_mov_b32_e32 v93, v89
	v_pk_mul_f32 v[92:93], v[114:115], v[92:93] op_sel:[1,0] op_sel_hi:[0,1]
	v_pk_fma_f32 v[92:93], v[114:115], v[88:89], v[92:93] op_sel_hi:[1,0,1]
	ds_write2_b64 v0, v[90:91], v[92:93] offset0:8 offset1:9
	v_pk_mul_f32 v[90:91], v[76:77], v[88:89] op_sel:[0,1] op_sel_hi:[1,0]
	s_nop 0
	v_pk_fma_f32 v[88:89], v[88:89], v[74:75], v[90:91] op_sel_hi:[1,0,1]
	s_nop 0
	v_xor_b32_e32 v90, 0x80000000, v89
	v_mov_b32_e32 v91, v89
	v_pk_mul_f32 v[90:91], v[126:127], v[90:91] op_sel:[1,0] op_sel_hi:[0,1]
	v_pk_mul_f32 v[92:93], v[76:77], v[88:89] op_sel:[0,1] op_sel_hi:[1,0]
	v_pk_fma_f32 v[90:91], v[126:127], v[88:89], v[90:91] op_sel_hi:[1,0,1]
	v_pk_fma_f32 v[88:89], v[88:89], v[74:75], v[92:93] op_sel_hi:[1,0,1]
	s_nop 0
	v_xor_b32_e32 v92, 0x80000000, v89
	v_mov_b32_e32 v93, v89
	v_pk_mul_f32 v[92:93], v[116:117], v[92:93] op_sel:[1,0] op_sel_hi:[0,1]
	v_pk_fma_f32 v[92:93], v[116:117], v[88:89], v[92:93] op_sel_hi:[1,0,1]
	ds_write2_b64 v0, v[90:91], v[92:93] offset0:10 offset1:11
	v_pk_mul_f32 v[90:91], v[76:77], v[88:89] op_sel:[0,1] op_sel_hi:[1,0]
	s_nop 0
	v_pk_fma_f32 v[88:89], v[88:89], v[74:75], v[90:91] op_sel_hi:[1,0,1]
	s_nop 0
	v_xor_b32_e32 v90, 0x80000000, v89
	v_mov_b32_e32 v91, v89
	v_pk_mul_f32 v[90:91], v[128:129], v[90:91] op_sel:[1,0] op_sel_hi:[0,1]
	v_pk_mul_f32 v[92:93], v[76:77], v[88:89] op_sel:[0,1] op_sel_hi:[1,0]
	v_pk_fma_f32 v[90:91], v[128:129], v[88:89], v[90:91] op_sel_hi:[1,0,1]
	v_pk_fma_f32 v[88:89], v[88:89], v[74:75], v[92:93] op_sel_hi:[1,0,1]
	s_nop 0
	v_xor_b32_e32 v92, 0x80000000, v89
	v_mov_b32_e32 v93, v89
	v_pk_mul_f32 v[92:93], v[112:113], v[92:93] op_sel:[1,0] op_sel_hi:[0,1]
	v_pk_fma_f32 v[92:93], v[112:113], v[88:89], v[92:93] op_sel_hi:[1,0,1]
	ds_write2_b64 v0, v[90:91], v[92:93] offset0:12 offset1:13
	v_pk_mul_f32 v[90:91], v[76:77], v[88:89] op_sel:[0,1] op_sel_hi:[1,0]
	s_nop 0
	v_pk_fma_f32 v[88:89], v[88:89], v[74:75], v[90:91] op_sel_hi:[1,0,1]
	s_nop 0
	v_xor_b32_e32 v90, 0x80000000, v89
	v_mov_b32_e32 v91, v89
	v_pk_mul_f32 v[90:91], v[106:107], v[90:91] op_sel:[1,0] op_sel_hi:[0,1]
	v_pk_mul_f32 v[92:93], v[76:77], v[88:89] op_sel:[0,1] op_sel_hi:[1,0]
	v_pk_fma_f32 v[90:91], v[106:107], v[88:89], v[90:91] op_sel_hi:[1,0,1]
	v_pk_fma_f32 v[88:89], v[88:89], v[74:75], v[92:93] op_sel_hi:[1,0,1]
	s_nop 0
	v_xor_b32_e32 v92, 0x80000000, v89
	v_mov_b32_e32 v93, v89
	v_pk_mul_f32 v[92:93], v[124:125], v[92:93] op_sel:[1,0] op_sel_hi:[0,1]
	v_pk_fma_f32 v[92:93], v[124:125], v[88:89], v[92:93] op_sel_hi:[1,0,1]
	ds_write2_b64 v0, v[90:91], v[92:93] offset0:14 offset1:15
	v_pk_mul_f32 v[90:91], v[76:77], v[88:89] op_sel:[0,1] op_sel_hi:[1,0]
	s_nop 0
	v_pk_fma_f32 v[88:89], v[88:89], v[74:75], v[90:91] op_sel_hi:[1,0,1]
	s_nop 0
	v_xor_b32_e32 v90, 0x80000000, v89
	v_mov_b32_e32 v91, v89
	v_pk_mul_f32 v[90:91], v[132:133], v[90:91] op_sel:[1,0] op_sel_hi:[0,1]
	v_pk_mul_f32 v[92:93], v[76:77], v[88:89] op_sel:[0,1] op_sel_hi:[1,0]
	v_pk_fma_f32 v[90:91], v[132:133], v[88:89], v[90:91] op_sel_hi:[1,0,1]
	v_pk_fma_f32 v[88:89], v[88:89], v[74:75], v[92:93] op_sel_hi:[1,0,1]
	s_nop 0
	v_xor_b32_e32 v92, 0x80000000, v89
	v_mov_b32_e32 v93, v89
	v_pk_mul_f32 v[92:93], v[110:111], v[92:93] op_sel:[1,0] op_sel_hi:[0,1]
	v_pk_fma_f32 v[92:93], v[110:111], v[88:89], v[92:93] op_sel_hi:[1,0,1]
	ds_write2_b64 v0, v[90:91], v[92:93] offset0:16 offset1:17
	v_pk_mul_f32 v[90:91], v[76:77], v[88:89] op_sel:[0,1] op_sel_hi:[1,0]
	s_nop 0
	v_pk_fma_f32 v[88:89], v[88:89], v[74:75], v[90:91] op_sel_hi:[1,0,1]
	s_nop 0
	v_xor_b32_e32 v90, 0x80000000, v89
	v_mov_b32_e32 v91, v89
	v_pk_mul_f32 v[90:91], v[122:123], v[90:91] op_sel:[1,0] op_sel_hi:[0,1]
	v_pk_mul_f32 v[92:93], v[76:77], v[88:89] op_sel:[0,1] op_sel_hi:[1,0]
	v_pk_fma_f32 v[90:91], v[122:123], v[88:89], v[90:91] op_sel_hi:[1,0,1]
	v_pk_fma_f32 v[88:89], v[88:89], v[74:75], v[92:93] op_sel_hi:[1,0,1]
	s_nop 0
	v_xor_b32_e32 v92, 0x80000000, v89
	v_mov_b32_e32 v93, v89
	v_pk_mul_f32 v[92:93], v[108:109], v[92:93] op_sel:[1,0] op_sel_hi:[0,1]
	v_pk_fma_f32 v[92:93], v[108:109], v[88:89], v[92:93] op_sel_hi:[1,0,1]
	ds_write2_b64 v0, v[90:91], v[92:93] offset0:18 offset1:19
	v_pk_mul_f32 v[90:91], v[76:77], v[88:89] op_sel:[0,1] op_sel_hi:[1,0]
	s_nop 0
	v_pk_fma_f32 v[88:89], v[88:89], v[74:75], v[90:91] op_sel_hi:[1,0,1]
	s_nop 0
	v_xor_b32_e32 v90, 0x80000000, v89
	v_mov_b32_e32 v91, v89
	v_pk_mul_f32 v[90:91], v[120:121], v[90:91] op_sel:[1,0] op_sel_hi:[0,1]
	v_pk_mul_f32 v[92:93], v[76:77], v[88:89] op_sel:[0,1] op_sel_hi:[1,0]
	v_pk_fma_f32 v[90:91], v[120:121], v[88:89], v[90:91] op_sel_hi:[1,0,1]
	v_pk_fma_f32 v[88:89], v[88:89], v[74:75], v[92:93] op_sel_hi:[1,0,1]
	s_nop 0
	v_xor_b32_e32 v92, 0x80000000, v89
	v_mov_b32_e32 v93, v89
	v_pk_mul_f32 v[92:93], v[96:97], v[92:93] op_sel:[1,0] op_sel_hi:[0,1]
	v_pk_fma_f32 v[92:93], v[96:97], v[88:89], v[92:93] op_sel_hi:[1,0,1]
	ds_write2_b64 v0, v[90:91], v[92:93] offset0:20 offset1:21
	v_pk_mul_f32 v[90:91], v[76:77], v[88:89] op_sel:[0,1] op_sel_hi:[1,0]
	s_nop 0
	v_pk_fma_f32 v[88:89], v[88:89], v[74:75], v[90:91] op_sel_hi:[1,0,1]
	s_nop 0
	v_xor_b32_e32 v90, 0x80000000, v89
	v_mov_b32_e32 v91, v89
	v_pk_mul_f32 v[90:91], v[94:95], v[90:91] op_sel:[1,0] op_sel_hi:[0,1]
	v_pk_mul_f32 v[92:93], v[76:77], v[88:89] op_sel:[0,1] op_sel_hi:[1,0]
	v_pk_fma_f32 v[90:91], v[94:95], v[88:89], v[90:91] op_sel_hi:[1,0,1]
	v_pk_fma_f32 v[88:89], v[88:89], v[74:75], v[92:93] op_sel_hi:[1,0,1]
	s_nop 0
	v_xor_b32_e32 v92, 0x80000000, v89
	v_mov_b32_e32 v93, v89
	v_pk_mul_f32 v[92:93], v[86:87], v[92:93] op_sel:[1,0] op_sel_hi:[0,1]
	v_pk_fma_f32 v[86:87], v[86:87], v[88:89], v[92:93] op_sel_hi:[1,0,1]
	ds_write2_b64 v0, v[90:91], v[86:87] offset0:22 offset1:23
	v_pk_mul_f32 v[86:87], v[76:77], v[88:89] op_sel:[0,1] op_sel_hi:[1,0]
	s_nop 0
	v_pk_fma_f32 v[86:87], v[88:89], v[74:75], v[86:87] op_sel_hi:[1,0,1]
	s_nop 0
	v_xor_b32_e32 v88, 0x80000000, v87
	v_mov_b32_e32 v89, v87
	v_pk_mul_f32 v[88:89], v[82:83], v[88:89] op_sel:[1,0] op_sel_hi:[0,1]
	v_pk_fma_f32 v[82:83], v[82:83], v[86:87], v[88:89] op_sel_hi:[1,0,1]
	v_pk_mul_f32 v[88:89], v[76:77], v[86:87] op_sel:[0,1] op_sel_hi:[1,0]
	s_nop 0
	v_pk_fma_f32 v[86:87], v[86:87], v[74:75], v[88:89] op_sel_hi:[1,0,1]
	s_nop 0
	v_xor_b32_e32 v88, 0x80000000, v87
	v_mov_b32_e32 v89, v87
	v_pk_mul_f32 v[88:89], v[84:85], v[88:89] op_sel:[1,0] op_sel_hi:[0,1]
	v_pk_fma_f32 v[84:85], v[84:85], v[86:87], v[88:89] op_sel_hi:[1,0,1]
	ds_write2_b64 v0, v[82:83], v[84:85] offset0:24 offset1:25
	v_pk_mul_f32 v[82:83], v[76:77], v[86:87] op_sel:[0,1] op_sel_hi:[1,0]
	s_nop 0
	v_pk_fma_f32 v[82:83], v[86:87], v[74:75], v[82:83] op_sel_hi:[1,0,1]
	s_nop 0
	v_xor_b32_e32 v84, 0x80000000, v83
	v_mov_b32_e32 v85, v83
	v_pk_mul_f32 v[84:85], v[78:79], v[84:85] op_sel:[1,0] op_sel_hi:[0,1]
	v_pk_fma_f32 v[78:79], v[78:79], v[82:83], v[84:85] op_sel_hi:[1,0,1]
	v_pk_mul_f32 v[84:85], v[76:77], v[82:83] op_sel:[0,1] op_sel_hi:[1,0]
	s_nop 0
	v_pk_fma_f32 v[82:83], v[82:83], v[74:75], v[84:85] op_sel_hi:[1,0,1]
	s_nop 0
	v_xor_b32_e32 v84, 0x80000000, v83
	v_mov_b32_e32 v85, v83
	v_pk_mul_f32 v[84:85], v[80:81], v[84:85] op_sel:[1,0] op_sel_hi:[0,1]
	v_pk_fma_f32 v[80:81], v[80:81], v[82:83], v[84:85] op_sel_hi:[1,0,1]
	ds_write2_b64 v0, v[78:79], v[80:81] offset0:26 offset1:27
	v_pk_mul_f32 v[78:79], v[76:77], v[82:83] op_sel:[0,1] op_sel_hi:[1,0]
	s_nop 0
	v_pk_fma_f32 v[78:79], v[82:83], v[74:75], v[78:79] op_sel_hi:[1,0,1]
	s_nop 0
	v_xor_b32_e32 v80, 0x80000000, v79
	v_mov_b32_e32 v81, v79
	v_pk_mul_f32 v[80:81], v[68:69], v[80:81] op_sel:[1,0] op_sel_hi:[0,1]
	v_pk_fma_f32 v[68:69], v[68:69], v[78:79], v[80:81] op_sel_hi:[1,0,1]
	v_pk_mul_f32 v[80:81], v[76:77], v[78:79] op_sel:[0,1] op_sel_hi:[1,0]
	s_nop 0
	v_pk_fma_f32 v[78:79], v[78:79], v[74:75], v[80:81] op_sel_hi:[1,0,1]
	s_nop 0
	v_xor_b32_e32 v80, 0x80000000, v79
	v_mov_b32_e32 v81, v79
	v_pk_mul_f32 v[80:81], v[72:73], v[80:81] op_sel:[1,0] op_sel_hi:[0,1]
	v_pk_fma_f32 v[72:73], v[72:73], v[78:79], v[80:81] op_sel_hi:[1,0,1]
	ds_write2_b64 v0, v[68:69], v[72:73] offset0:28 offset1:29
	v_pk_mul_f32 v[68:69], v[76:77], v[78:79] op_sel:[0,1] op_sel_hi:[1,0]
	s_nop 0
	v_pk_fma_f32 v[68:69], v[78:79], v[74:75], v[68:69] op_sel_hi:[1,0,1]
	s_nop 0
	v_xor_b32_e32 v72, 0x80000000, v69
	v_mov_b32_e32 v73, v69
	v_pk_mul_f32 v[72:73], v[66:67], v[72:73] op_sel:[1,0] op_sel_hi:[0,1]
	v_pk_fma_f32 v[66:67], v[66:67], v[68:69], v[72:73] op_sel_hi:[1,0,1]
	v_pk_mul_f32 v[72:73], v[76:77], v[68:69] op_sel:[0,1] op_sel_hi:[1,0]
	s_nop 0
	v_pk_fma_f32 v[68:69], v[68:69], v[74:75], v[72:73] op_sel_hi:[1,0,1]
	s_nop 0
	v_xor_b32_e32 v72, 0x80000000, v69
	v_mov_b32_e32 v73, v69
	v_pk_mul_f32 v[72:73], v[70:71], v[72:73] op_sel:[1,0] op_sel_hi:[0,1]
	v_pk_fma_f32 v[68:69], v[70:71], v[68:69], v[72:73] op_sel_hi:[1,0,1]
	ds_write2_b64 v0, v[66:67], v[68:69] offset0:30 offset1:31
	s_waitcnt lgkmcnt(0)
	s_barrier
	v_mov_b32 v0, 0
	s_nop 0
	v_add_u32_e32 v71, v0, v170
	v_ashrrev_i32_e32 v105, 5, v71
	v_lshlrev_b32_e32 v0, 10, v105
	v_and_b32_e32 v140, 31, v71
	v_ashrrev_i32_e32 v0, 2, v0
	v_lshlrev_b32_e32 v67, 13, v105
	v_lshlrev_b32_e32 v68, 3, v140
	v_add_u32_e32 v0, 0, v0
	v_lshl_add_u32 v66, v105, 8, 0
	v_add3_u32 v0, v0, v67, v68
	v_add3_u32 v142, v66, v67, v68
	v_add_u32_e32 v143, 0x400, v0
	v_add_u32_e32 v144, 0x800, v0
	v_add_u32_e32 v145, 0xc00, v0
	ds_read_b64 v[130:131], v142
	ds_read2_b64 v[66:69], v0 offset0:33 offset1:66
	ds_read2_b64 v[72:75], v0 offset0:99 offset1:132
	ds_read2_b64 v[76:79], v0 offset0:165 offset1:198
	ds_read2_b64 v[80:83], v143 offset0:103 offset1:136
	ds_read2_b64 v[84:87], v144 offset0:41 offset1:74
	ds_read2_b64 v[88:91], v144 offset0:107 offset1:140
	ds_read2_b64 v[92:95], v144 offset0:173 offset1:206
	ds_read2_b64 v[96:99], v145 offset0:111 offset1:144
	v_add_u32_e32 v146, 0x1000, v0
	ds_read2_b64 v[100:103], v146 offset0:49 offset1:82
	ds_read2_b64 v[106:109], v146 offset0:115 offset1:148
	ds_read2_b64 v[110:113], v146 offset0:181 offset1:214
	v_add_u32_e32 v147, 0x1400, v0
	ds_read2_b64 v[114:117], v147 offset0:119 offset1:152
	s_waitcnt lgkmcnt(4)
	v_pk_add_f32 v[134:135], v[130:131], v[98:99]
	v_pk_add_f32 v[98:99], v[130:131], v[98:99] neg_lo:[0,1] neg_hi:[0,1]
	s_waitcnt lgkmcnt(3)
	v_pk_add_f32 v[130:131], v[66:67], v[100:101]
	v_pk_add_f32 v[66:67], v[66:67], v[100:101] neg_lo:[0,1] neg_hi:[0,1]
	v_add_u32_e32 v70, 0x1800, v0
	v_pk_mul_f32 v[100:101], v[66:67], s[50:51]
	ds_read2_b64 v[118:121], v70 offset0:57 offset1:90
	ds_read2_b64 v[122:125], v70 offset0:123 offset1:156
	ds_read2_b64 v[126:129], v70 offset0:189 offset1:222
	ds_read_b64 v[132:133], v0 offset:8184
	v_pk_fma_f32 v[66:67], v[66:67], s[20:21], v[100:101] op_sel:[0,0,1] op_sel_hi:[1,0,0]
	v_pk_add_f32 v[100:101], v[68:69], v[102:103]
	v_pk_add_f32 v[68:69], v[68:69], v[102:103] neg_lo:[0,1] neg_hi:[0,1]
	v_mul_lo_u32 v105, v140, v105
	v_pk_mul_f32 v[102:103], v[68:69], s[14:15]
	v_cvt_f32_i32_e32 v105, v105
	v_pk_fma_f32 v[68:69], v[68:69], s[6:7], v[102:103] op_sel:[0,0,1] op_sel_hi:[1,0,0]
	s_waitcnt lgkmcnt(6)
	v_pk_add_f32 v[102:103], v[72:73], v[106:107]
	v_pk_add_f32 v[72:73], v[72:73], v[106:107] neg_lo:[0,1] neg_hi:[0,1]
	v_and_b32_e32 v71, 0xffffffe0, v71
	v_pk_mul_f32 v[106:107], v[72:73], s[52:53]
	v_cvt_f32_i32_e32 v71, v71
	v_pk_fma_f32 v[72:73], v[72:73], s[24:25], v[106:107] op_sel:[0,0,1] op_sel_hi:[1,0,0]
	v_pk_add_f32 v[106:107], v[74:75], v[108:109]
	v_pk_add_f32 v[74:75], v[74:75], v[108:109] neg_lo:[0,1] neg_hi:[0,1]
	v_mul_f32_e32 v71, 0x38800000, v71
	v_pk_mul_f32 v[108:109], v[74:75], s[10:11]
	s_nop 0
	v_pk_fma_f32 v[74:75], v[74:75], s[10:11], v[108:109] op_sel:[0,0,1] op_sel_hi:[1,0,0]
	s_waitcnt lgkmcnt(5)
	v_pk_add_f32 v[108:109], v[76:77], v[110:111]
	v_pk_add_f32 v[76:77], v[76:77], v[110:111] neg_lo:[0,1] neg_hi:[0,1]
	s_nop 0
	v_pk_mul_f32 v[110:111], v[76:77], s[24:25]
	s_nop 0
	v_pk_fma_f32 v[76:77], v[76:77], s[0:1], v[110:111] op_sel:[0,0,1] op_sel_hi:[1,0,0]
	v_pk_add_f32 v[110:111], v[78:79], v[112:113]
	v_pk_add_f32 v[78:79], v[78:79], v[112:113] neg_lo:[0,1] neg_hi:[0,1]
	s_nop 0
	v_pk_mul_f32 v[112:113], v[78:79], s[6:7]
	s_nop 0
	v_pk_fma_f32 v[78:79], v[78:79], s[14:15], v[112:113] op_sel:[0,0,1] op_sel_hi:[1,0,0]
	s_waitcnt lgkmcnt(4)
	v_pk_add_f32 v[112:113], v[80:81], v[114:115]
	v_pk_add_f32 v[80:81], v[80:81], v[114:115] neg_lo:[0,1] neg_hi:[0,1]
	s_nop 0
	v_pk_mul_f32 v[114:115], v[80:81], s[20:21]
	s_nop 0
	v_pk_fma_f32 v[80:81], v[80:81], s[48:49], v[114:115] op_sel:[0,0,1] op_sel_hi:[1,0,0]
	v_pk_add_f32 v[114:115], v[82:83], v[116:117]
	v_pk_add_f32 v[116:117], v[82:83], v[116:117] op_sel:[1,1] op_sel_hi:[0,0] neg_lo:[1,0] neg_hi:[0,1]
	s_mov_b64 s[48:49], -1
	s_waitcnt lgkmcnt(3)
	v_pk_add_f32 v[82:83], v[84:85], v[118:119]
	v_pk_add_f32 v[84:85], v[84:85], v[118:119] neg_lo:[0,1] neg_hi:[0,1]
	s_nop 0
	v_pk_mul_f32 v[118:119], v[84:85], s[20:21]
	s_nop 0
	v_pk_fma_f32 v[84:85], v[84:85], s[18:19], v[118:119] op_sel:[0,0,1] op_sel_hi:[1,0,0]
	v_pk_add_f32 v[118:119], v[86:87], v[120:121]
	v_pk_add_f32 v[86:87], v[86:87], v[120:121] neg_lo:[0,1] neg_hi:[0,1]
	s_nop 0
	v_pk_mul_f32 v[120:121], v[86:87], s[6:7]
	s_nop 0
	v_pk_fma_f32 v[86:87], v[86:87], s[4:5], v[120:121] op_sel:[0,0,1] op_sel_hi:[1,0,0]
	s_waitcnt lgkmcnt(2)
	v_pk_add_f32 v[120:121], v[88:89], v[122:123]
	v_pk_add_f32 v[88:89], v[88:89], v[122:123] neg_lo:[0,1] neg_hi:[0,1]
	s_nop 0
	v_pk_mul_f32 v[122:123], v[88:89], s[24:25]
	s_nop 0
	v_pk_fma_f32 v[88:89], v[88:89], s[22:23], v[122:123] op_sel:[0,0,1] op_sel_hi:[1,0,0]
	v_pk_add_f32 v[122:123], v[90:91], v[124:125]
	v_pk_add_f32 v[90:91], v[90:91], v[124:125] neg_lo:[0,1] neg_hi:[0,1]
	s_nop 0
	v_pk_mul_f32 v[124:125], v[90:91], s[10:11]
	s_nop 0
	v_pk_fma_f32 v[90:91], v[90:91], s[8:9], v[124:125] op_sel:[0,0,1] op_sel_hi:[1,0,0]
	s_waitcnt lgkmcnt(1)
	v_pk_add_f32 v[124:125], v[92:93], v[126:127]
	v_pk_add_f32 v[92:93], v[92:93], v[126:127] neg_lo:[0,1] neg_hi:[0,1]
	s_nop 0
	v_pk_mul_f32 v[126:127], v[92:93], s[52:53]
	s_nop 0
	v_pk_fma_f32 v[92:93], v[92:93], s[26:27], v[126:127] op_sel:[0,0,1] op_sel_hi:[1,0,0]
	v_pk_add_f32 v[126:127], v[94:95], v[128:129]
	v_pk_add_f32 v[94:95], v[94:95], v[128:129] neg_lo:[0,1] neg_hi:[0,1]
	s_nop 0
	v_pk_mul_f32 v[128:129], v[94:95], s[14:15]
	s_nop 0
	v_pk_fma_f32 v[94:95], v[94:95], s[12:13], v[128:129] op_sel:[0,0,1] op_sel_hi:[1,0,0]
	s_waitcnt lgkmcnt(0)
	v_pk_add_f32 v[128:129], v[96:97], v[132:133]
	v_pk_add_f32 v[96:97], v[96:97], v[132:133] neg_lo:[0,1] neg_hi:[0,1]
	s_nop 0
	v_pk_mul_f32 v[132:133], v[96:97], s[50:51]
	s_nop 0
	v_pk_fma_f32 v[96:97], v[96:97], s[34:35], v[132:133] op_sel:[0,0,1] op_sel_hi:[1,0,0]
	v_pk_add_f32 v[132:133], v[134:135], v[114:115]
	v_pk_add_f32 v[114:115], v[134:135], v[114:115] neg_lo:[0,1] neg_hi:[0,1]
	v_pk_add_f32 v[134:135], v[130:131], v[82:83]
	v_pk_add_f32 v[82:83], v[130:131], v[82:83] neg_lo:[0,1] neg_hi:[0,1]
	s_nop 0
	v_pk_mul_f32 v[130:131], v[82:83], s[14:15]
	s_nop 0
	v_pk_fma_f32 v[82:83], v[82:83], s[6:7], v[130:131] op_sel:[0,0,1] op_sel_hi:[1,0,0]
	v_pk_add_f32 v[130:131], v[100:101], v[118:119]
	v_pk_add_f32 v[100:101], v[100:101], v[118:119] neg_lo:[0,1] neg_hi:[0,1]
	s_nop 0
	v_pk_mul_f32 v[118:119], v[100:101], s[10:11]
	s_nop 0
	v_pk_fma_f32 v[100:101], v[100:101], s[10:11], v[118:119] op_sel:[0,0,1] op_sel_hi:[1,0,0]
	v_pk_add_f32 v[118:119], v[102:103], v[120:121]
	v_pk_add_f32 v[102:103], v[102:103], v[120:121] neg_lo:[0,1] neg_hi:[0,1]
	s_nop 0
	v_pk_mul_f32 v[120:121], v[102:103], s[6:7]
	s_nop 0
	v_pk_fma_f32 v[102:103], v[102:103], s[14:15], v[120:121] op_sel:[0,0,1] op_sel_hi:[1,0,0]
	v_pk_add_f32 v[120:121], v[106:107], v[122:123]
	v_pk_add_f32 v[122:123], v[106:107], v[122:123] op_sel:[1,1] op_sel_hi:[0,0] neg_lo:[1,0] neg_hi:[0,1]
	s_nop 0
	v_pk_add_f32 v[106:107], v[108:109], v[124:125]
	v_pk_add_f32 v[108:109], v[108:109], v[124:125] neg_lo:[0,1] neg_hi:[0,1]
	s_nop 0
	v_pk_mul_f32 v[124:125], v[108:109], s[6:7]
	s_nop 0
	v_pk_fma_f32 v[108:109], v[108:109], s[4:5], v[124:125] op_sel:[0,0,1] op_sel_hi:[1,0,0]
	v_pk_add_f32 v[124:125], v[110:111], v[126:127]
	v_pk_add_f32 v[110:111], v[110:111], v[126:127] neg_lo:[0,1] neg_hi:[0,1]
	s_nop 0
	v_pk_mul_f32 v[126:127], v[110:111], s[10:11]
	s_nop 0
	v_pk_fma_f32 v[110:111], v[110:111], s[8:9], v[126:127] op_sel:[0,0,1] op_sel_hi:[1,0,0]
	v_pk_add_f32 v[126:127], v[112:113], v[128:129]
	v_pk_add_f32 v[112:113], v[112:113], v[128:129] neg_lo:[0,1] neg_hi:[0,1]
	s_nop 0
	v_pk_mul_f32 v[128:129], v[112:113], s[14:15]
	s_nop 0
	v_pk_fma_f32 v[112:113], v[112:113], s[12:13], v[128:129] op_sel:[0,0,1] op_sel_hi:[1,0,0]
	v_pk_add_f32 v[128:129], v[98:99], v[116:117]
	v_pk_add_f32 v[98:99], v[98:99], v[116:117] neg_lo:[0,1] neg_hi:[0,1]
	v_pk_add_f32 v[116:117], v[66:67], v[84:85]
	v_pk_add_f32 v[66:67], v[66:67], v[84:85] neg_lo:[0,1] neg_hi:[0,1]
	s_nop 0
	v_pk_mul_f32 v[84:85], v[66:67], s[14:15]
	s_nop 0
	v_pk_fma_f32 v[66:67], v[66:67], s[6:7], v[84:85] op_sel:[0,0,1] op_sel_hi:[1,0,0]
	v_pk_add_f32 v[84:85], v[68:69], v[86:87]
	v_pk_add_f32 v[68:69], v[68:69], v[86:87] neg_lo:[0,1] neg_hi:[0,1]
	s_nop 0
	v_pk_mul_f32 v[86:87], v[68:69], s[10:11]
	s_nop 0
	v_pk_fma_f32 v[68:69], v[68:69], s[10:11], v[86:87] op_sel:[0,0,1] op_sel_hi:[1,0,0]
	v_pk_add_f32 v[86:87], v[72:73], v[88:89]
	v_pk_add_f32 v[72:73], v[72:73], v[88:89] neg_lo:[0,1] neg_hi:[0,1]
	s_nop 0
	v_pk_mul_f32 v[88:89], v[72:73], s[6:7]
	s_nop 0
	v_pk_fma_f32 v[72:73], v[72:73], s[14:15], v[88:89] op_sel:[0,0,1] op_sel_hi:[1,0,0]
	v_pk_add_f32 v[88:89], v[74:75], v[90:91]
	v_pk_add_f32 v[90:91], v[74:75], v[90:91] op_sel:[1,1] op_sel_hi:[0,0] neg_lo:[1,0] neg_hi:[0,1]
	s_nop 0
	v_pk_add_f32 v[74:75], v[76:77], v[92:93]
	v_pk_add_f32 v[76:77], v[76:77], v[92:93] neg_lo:[0,1] neg_hi:[0,1]
	s_nop 0
	v_pk_mul_f32 v[92:93], v[76:77], s[6:7]
	s_nop 0
	v_pk_fma_f32 v[76:77], v[76:77], s[4:5], v[92:93] op_sel:[0,0,1] op_sel_hi:[1,0,0]
	v_pk_add_f32 v[92:93], v[78:79], v[94:95]
	v_pk_add_f32 v[78:79], v[78:79], v[94:95] neg_lo:[0,1] neg_hi:[0,1]
	s_mov_b32 s5, 0
	v_pk_mul_f32 v[94:95], v[78:79], s[10:11]
	s_nop 0
	v_pk_fma_f32 v[78:79], v[78:79], s[8:9], v[94:95] op_sel:[0,0,1] op_sel_hi:[1,0,0]
	v_pk_add_f32 v[94:95], v[80:81], v[96:97]
	v_pk_add_f32 v[80:81], v[80:81], v[96:97] neg_lo:[0,1] neg_hi:[0,1]
	s_nop 0
	v_pk_mul_f32 v[96:97], v[80:81], s[14:15]
	s_nop 0
	v_pk_fma_f32 v[80:81], v[80:81], s[12:13], v[96:97] op_sel:[0,0,1] op_sel_hi:[1,0,0]
	v_pk_add_f32 v[96:97], v[132:133], v[120:121]
	v_pk_add_f32 v[120:121], v[132:133], v[120:121] neg_lo:[0,1] neg_hi:[0,1]
	v_pk_add_f32 v[132:133], v[134:135], v[106:107]
	v_pk_add_f32 v[106:107], v[134:135], v[106:107] neg_lo:[0,1] neg_hi:[0,1]
	s_nop 0
	v_pk_mul_f32 v[134:135], v[106:107], s[10:11]
	s_nop 0
	v_pk_fma_f32 v[106:107], v[106:107], s[10:11], v[134:135] op_sel:[0,0,1] op_sel_hi:[1,0,0]
	v_pk_add_f32 v[134:135], v[130:131], v[124:125]
	v_pk_add_f32 v[130:131], v[130:131], v[124:125] op_sel:[1,1] op_sel_hi:[0,0] neg_lo:[1,0] neg_hi:[0,1]
	s_nop 0
	v_pk_add_f32 v[124:125], v[118:119], v[126:127]
	v_pk_add_f32 v[118:119], v[118:119], v[126:127] neg_lo:[0,1] neg_hi:[0,1]
	s_nop 0
	v_pk_mul_f32 v[126:127], v[118:119], s[10:11]
	s_nop 0
	v_pk_fma_f32 v[118:119], v[118:119], s[8:9], v[126:127] op_sel:[0,0,1] op_sel_hi:[1,0,0]
	v_pk_add_f32 v[126:127], v[114:115], v[122:123]
	v_pk_add_f32 v[114:115], v[114:115], v[122:123] neg_lo:[0,1] neg_hi:[0,1]
	v_pk_add_f32 v[122:123], v[82:83], v[108:109]
	v_pk_add_f32 v[82:83], v[82:83], v[108:109] neg_lo:[0,1] neg_hi:[0,1]
	s_nop 0
	v_pk_mul_f32 v[108:109], v[82:83], s[10:11]
	s_nop 0
	v_pk_fma_f32 v[82:83], v[82:83], s[10:11], v[108:109] op_sel:[0,0,1] op_sel_hi:[1,0,0]
	v_pk_add_f32 v[108:109], v[100:101], v[110:111]
	v_pk_add_f32 v[110:111], v[100:101], v[110:111] op_sel:[1,1] op_sel_hi:[0,0] neg_lo:[1,0] neg_hi:[0,1]
	s_nop 0
	v_pk_add_f32 v[100:101], v[102:103], v[112:113]
	v_pk_add_f32 v[102:103], v[102:103], v[112:113] neg_lo:[0,1] neg_hi:[0,1]
	s_nop 0
	v_pk_mul_f32 v[112:113], v[102:103], s[10:11]
	s_nop 0
	v_pk_fma_f32 v[102:103], v[102:103], s[8:9], v[112:113] op_sel:[0,0,1] op_sel_hi:[1,0,0]
	v_pk_add_f32 v[112:113], v[128:129], v[88:89]
	v_pk_add_f32 v[88:89], v[128:129], v[88:89] neg_lo:[0,1] neg_hi:[0,1]
	v_pk_add_f32 v[128:129], v[116:117], v[74:75]
	v_pk_add_f32 v[74:75], v[116:117], v[74:75] neg_lo:[0,1] neg_hi:[0,1]
	s_nop 0
	v_pk_mul_f32 v[116:117], v[74:75], s[10:11]
	s_nop 0
	v_pk_fma_f32 v[74:75], v[74:75], s[10:11], v[116:117] op_sel:[0,0,1] op_sel_hi:[1,0,0]
	v_pk_add_f32 v[116:117], v[84:85], v[92:93]
	v_pk_add_f32 v[92:93], v[84:85], v[92:93] op_sel:[1,1] op_sel_hi:[0,0] neg_lo:[1,0] neg_hi:[0,1]
	s_nop 0
	v_pk_add_f32 v[84:85], v[86:87], v[94:95]
	v_pk_add_f32 v[86:87], v[86:87], v[94:95] neg_lo:[0,1] neg_hi:[0,1]
	s_nop 0
	v_pk_mul_f32 v[94:95], v[86:87], s[10:11]
	s_nop 0
	v_pk_fma_f32 v[86:87], v[86:87], s[8:9], v[94:95] op_sel:[0,0,1] op_sel_hi:[1,0,0]
	v_pk_add_f32 v[94:95], v[98:99], v[90:91]
	v_pk_add_f32 v[90:91], v[98:99], v[90:91] neg_lo:[0,1] neg_hi:[0,1]
	v_pk_add_f32 v[98:99], v[66:67], v[76:77]
	v_pk_add_f32 v[66:67], v[66:67], v[76:77] neg_lo:[0,1] neg_hi:[0,1]
	s_nop 0
	v_pk_mul_f32 v[76:77], v[66:67], s[10:11]
	s_nop 0
	v_pk_fma_f32 v[66:67], v[66:67], s[10:11], v[76:77] op_sel:[0,0,1] op_sel_hi:[1,0,0]
	v_pk_add_f32 v[76:77], v[68:69], v[78:79]
	v_pk_add_f32 v[78:79], v[68:69], v[78:79] op_sel:[1,1] op_sel_hi:[0,0] neg_lo:[1,0] neg_hi:[0,1]
	s_nop 0
	v_pk_add_f32 v[68:69], v[72:73], v[80:81]
	v_pk_add_f32 v[72:73], v[72:73], v[80:81] neg_lo:[0,1] neg_hi:[0,1]
	v_pk_add_f32 v[136:137], v[90:91], v[78:79]
	v_pk_mul_f32 v[80:81], v[72:73], s[10:11]
	v_pk_add_f32 v[78:79], v[90:91], v[78:79] neg_lo:[0,1] neg_hi:[0,1]
	v_pk_fma_f32 v[72:73], v[72:73], s[8:9], v[80:81] op_sel:[0,0,1] op_sel_hi:[1,0,0]
	v_pk_add_f32 v[80:81], v[96:97], v[134:135]
	v_pk_add_f32 v[96:97], v[96:97], v[134:135] neg_lo:[0,1] neg_hi:[0,1]
	v_pk_add_f32 v[134:135], v[132:133], v[124:125]
	v_pk_add_f32 v[132:133], v[132:133], v[124:125] op_sel:[1,1] op_sel_hi:[0,0] neg_lo:[1,0] neg_hi:[0,1]
	v_pk_add_f32 v[90:91], v[66:67], v[72:73]
	v_pk_add_f32 v[124:125], v[120:121], v[130:131]
	v_pk_add_f32 v[120:121], v[120:121], v[130:131] neg_lo:[0,1] neg_hi:[0,1]
	v_pk_add_f32 v[130:131], v[106:107], v[118:119]
	v_pk_add_f32 v[118:119], v[106:107], v[118:119] op_sel:[1,1] op_sel_hi:[0,0] neg_lo:[1,0] neg_hi:[0,1]
	v_pk_add_f32 v[66:67], v[66:67], v[72:73] neg_lo:[0,1] neg_hi:[0,1]
	v_pk_add_f32 v[106:107], v[126:127], v[108:109]
	v_pk_add_f32 v[108:109], v[126:127], v[108:109] neg_lo:[0,1] neg_hi:[0,1]
	v_pk_add_f32 v[126:127], v[122:123], v[100:101]
	v_pk_add_f32 v[122:123], v[122:123], v[100:101] op_sel:[1,1] op_sel_hi:[0,0] neg_lo:[1,0] neg_hi:[0,1]
	v_xor_b32_e32 v72, 0x80000000, v67
	v_pk_add_f32 v[100:101], v[114:115], v[110:111]
	v_pk_add_f32 v[110:111], v[114:115], v[110:111] neg_lo:[0,1] neg_hi:[0,1]
	v_pk_add_f32 v[114:115], v[82:83], v[102:103]
	v_pk_add_f32 v[102:103], v[82:83], v[102:103] op_sel:[1,1] op_sel_hi:[0,0] neg_lo:[1,0] neg_hi:[0,1]
	v_mov_b32_e32 v73, v66
	v_pk_add_f32 v[82:83], v[112:113], v[116:117]
	v_pk_add_f32 v[112:113], v[112:113], v[116:117] neg_lo:[0,1] neg_hi:[0,1]
	v_pk_add_f32 v[116:117], v[128:129], v[84:85]
	v_pk_add_f32 v[128:129], v[128:129], v[84:85] op_sel:[1,1] op_sel_hi:[0,0] neg_lo:[1,0] neg_hi:[0,1]
	v_pk_add_f32 v[138:139], v[80:81], v[134:135]
	v_pk_add_f32 v[84:85], v[88:89], v[92:93]
	v_pk_add_f32 v[88:89], v[88:89], v[92:93] neg_lo:[0,1] neg_hi:[0,1]
	v_pk_add_f32 v[92:93], v[74:75], v[86:87]
	v_pk_add_f32 v[86:87], v[74:75], v[86:87] op_sel:[1,1] op_sel_hi:[0,0] neg_lo:[1,0] neg_hi:[0,1]
	v_pk_add_f32 v[80:81], v[80:81], v[134:135] neg_lo:[0,1] neg_hi:[0,1]
	v_pk_add_f32 v[74:75], v[94:95], v[76:77]
	v_pk_add_f32 v[76:77], v[94:95], v[76:77] neg_lo:[0,1] neg_hi:[0,1]
	v_pk_add_f32 v[94:95], v[98:99], v[68:69]
	v_pk_add_f32 v[98:99], v[98:99], v[68:69] op_sel:[1,1] op_sel_hi:[0,0] neg_lo:[1,0] neg_hi:[0,1]
	v_pk_add_f32 v[134:135], v[96:97], v[132:133]
	v_pk_add_f32 v[96:97], v[96:97], v[132:133] neg_lo:[0,1] neg_hi:[0,1]
	v_pk_add_f32 v[132:133], v[124:125], v[130:131]
	v_pk_add_f32 v[124:125], v[124:125], v[130:131] neg_lo:[0,1] neg_hi:[0,1]
	v_pk_add_f32 v[130:131], v[120:121], v[118:119]
	v_pk_add_f32 v[68:69], v[120:121], v[118:119] neg_lo:[0,1] neg_hi:[0,1]
	v_pk_add_f32 v[118:119], v[106:107], v[126:127]
	v_pk_add_f32 v[106:107], v[106:107], v[126:127] neg_lo:[0,1] neg_hi:[0,1]
	v_pk_add_f32 v[126:127], v[78:79], v[72:73]
	v_pk_add_f32 v[72:73], v[78:79], v[72:73] neg_lo:[0,1] neg_hi:[0,1]
	v_mul_f32_e32 v78, 0x38800000, v105
	v_sin_f32_e32 v79, v78
	v_cos_f32_e32 v78, v78
	v_pk_add_f32 v[120:121], v[108:109], v[122:123]
	v_pk_add_f32 v[108:109], v[108:109], v[122:123] neg_lo:[0,1] neg_hi:[0,1]
	v_pk_add_f32 v[122:123], v[100:101], v[114:115]
	v_pk_add_f32 v[100:101], v[100:101], v[114:115] neg_lo:[0,1] neg_hi:[0,1]
	v_pk_add_f32 v[114:115], v[110:111], v[102:103]
	v_pk_add_f32 v[66:67], v[110:111], v[102:103] neg_lo:[0,1] neg_hi:[0,1]
	v_pk_add_f32 v[102:103], v[82:83], v[116:117]
	v_pk_add_f32 v[82:83], v[82:83], v[116:117] neg_lo:[0,1] neg_hi:[0,1]
	v_pk_add_f32 v[116:117], v[84:85], v[92:93]
	v_pk_add_f32 v[84:85], v[84:85], v[92:93] neg_lo:[0,1] neg_hi:[0,1]
	v_pk_add_f32 v[92:93], v[88:89], v[86:87]
	v_pk_add_f32 v[86:87], v[88:89], v[86:87] neg_lo:[0,1] neg_hi:[0,1]
	v_pk_add_f32 v[88:89], v[74:75], v[94:95]
	v_pk_add_f32 v[74:75], v[74:75], v[94:95] neg_lo:[0,1] neg_hi:[0,1]
	v_pk_add_f32 v[94:95], v[76:77], v[98:99]
	v_pk_add_f32 v[76:77], v[76:77], v[98:99] neg_lo:[0,1] neg_hi:[0,1]
	v_pk_add_f32 v[98:99], v[136:137], v[90:91]
	v_pk_add_f32 v[90:91], v[136:137], v[90:91] neg_lo:[0,1] neg_hi:[0,1]
	v_sin_f32_e32 v136, v71
	v_pk_add_f32 v[110:111], v[112:113], v[128:129]
	v_pk_add_f32 v[112:113], v[112:113], v[128:129] neg_lo:[0,1] neg_hi:[0,1]
	v_cos_f32_e32 v128, v71
	v_xor_b32_e32 v140, 0x80000000, v79
	v_mov_b32_e32 v141, v79
	v_pk_mul_f32 v[140:141], v[140:141], v[138:139] op_sel:[0,1] op_sel_hi:[1,0]
	s_nop 0
	v_pk_fma_f32 v[138:139], v[138:139], v[78:79], v[140:141] op_sel_hi:[1,0,1]
	ds_write_b64 v142, v[138:139]
	v_pk_mul_f32 v[138:139], v[136:137], v[78:79] op_sel:[0,1] op_sel_hi:[0,0] neg_lo:[1,0]
	v_pk_fma_f32 v[78:79], v[78:79], v[128:129], v[138:139] op_sel_hi:[1,0,1]
	s_nop 0
	v_xor_b32_e32 v138, 0x80000000, v79
	v_mov_b32_e32 v139, v79
	v_pk_mul_f32 v[138:139], v[138:139], v[102:103] op_sel:[0,1] op_sel_hi:[1,0]
	s_nop 0
	v_pk_fma_f32 v[102:103], v[102:103], v[78:79], v[138:139] op_sel_hi:[1,0,1]
	v_pk_mul_f32 v[138:139], v[136:137], v[78:79] op_sel:[0,1] op_sel_hi:[0,0] neg_lo:[1,0]
	v_pk_fma_f32 v[78:79], v[78:79], v[128:129], v[138:139] op_sel_hi:[1,0,1]
	s_nop 0
	v_xor_b32_e32 v138, 0x80000000, v79
	v_mov_b32_e32 v139, v79
	v_pk_mul_f32 v[138:139], v[138:139], v[118:119] op_sel:[0,1] op_sel_hi:[1,0]
	s_nop 0
	v_pk_fma_f32 v[118:119], v[118:119], v[78:79], v[138:139] op_sel_hi:[1,0,1]
	ds_write2_b64 v0, v[102:103], v[118:119] offset0:33 offset1:66
	v_pk_mul_f32 v[102:103], v[136:137], v[78:79] op_sel:[0,1] op_sel_hi:[0,0] neg_lo:[1,0]
	v_pk_fma_f32 v[78:79], v[78:79], v[128:129], v[102:103] op_sel_hi:[1,0,1]
	s_nop 0
	v_xor_b32_e32 v102, 0x80000000, v79
	v_mov_b32_e32 v103, v79
	v_pk_mul_f32 v[102:103], v[102:103], v[88:89] op_sel:[0,1] op_sel_hi:[1,0]
	s_nop 0
	v_pk_fma_f32 v[88:89], v[88:89], v[78:79], v[102:103] op_sel_hi:[1,0,1]
	v_pk_mul_f32 v[102:103], v[136:137], v[78:79] op_sel:[0,1] op_sel_hi:[0,0] neg_lo:[1,0]
	v_pk_fma_f32 v[78:79], v[78:79], v[128:129], v[102:103] op_sel_hi:[1,0,1]
	s_nop 0
	v_xor_b32_e32 v102, 0x80000000, v79
	v_mov_b32_e32 v103, v79
	v_pk_mul_f32 v[102:103], v[102:103], v[132:133] op_sel:[0,1] op_sel_hi:[1,0]
	s_nop 0
	v_pk_fma_f32 v[102:103], v[132:133], v[78:79], v[102:103] op_sel_hi:[1,0,1]
	ds_write2_b64 v0, v[88:89], v[102:103] offset0:99 offset1:132
	v_pk_mul_f32 v[88:89], v[136:137], v[78:79] op_sel:[0,1] op_sel_hi:[0,0] neg_lo:[1,0]
	v_pk_fma_f32 v[78:79], v[78:79], v[128:129], v[88:89] op_sel_hi:[1,0,1]
	s_nop 0
	v_xor_b32_e32 v88, 0x80000000, v79
	v_mov_b32_e32 v89, v79
	v_pk_mul_f32 v[88:89], v[88:89], v[116:117] op_sel:[0,1] op_sel_hi:[1,0]
	v_pk_mul_f32 v[102:103], v[136:137], v[78:79] op_sel:[0,1] op_sel_hi:[0,0] neg_lo:[1,0]
	v_pk_fma_f32 v[88:89], v[116:117], v[78:79], v[88:89] op_sel_hi:[1,0,1]
	v_pk_fma_f32 v[78:79], v[78:79], v[128:129], v[102:103] op_sel_hi:[1,0,1]
	s_nop 0
	v_xor_b32_e32 v102, 0x80000000, v79
	v_mov_b32_e32 v103, v79
	v_pk_mul_f32 v[102:103], v[102:103], v[122:123] op_sel:[0,1] op_sel_hi:[1,0]
	s_nop 0
	v_pk_fma_f32 v[102:103], v[122:123], v[78:79], v[102:103] op_sel_hi:[1,0,1]
	ds_write2_b64 v0, v[88:89], v[102:103] offset0:165 offset1:198
	v_pk_mul_f32 v[88:89], v[136:137], v[78:79] op_sel:[0,1] op_sel_hi:[0,0] neg_lo:[1,0]
	v_pk_fma_f32 v[78:79], v[78:79], v[128:129], v[88:89] op_sel_hi:[1,0,1]
	s_nop 0
	v_xor_b32_e32 v88, 0x80000000, v79
	v_mov_b32_e32 v89, v79
	v_pk_mul_f32 v[88:89], v[88:89], v[98:99] op_sel:[0,1] op_sel_hi:[1,0]
	s_nop 0
	v_pk_fma_f32 v[88:89], v[98:99], v[78:79], v[88:89] op_sel_hi:[1,0,1]
	v_pk_mul_f32 v[98:99], v[136:137], v[78:79] op_sel:[0,1] op_sel_hi:[0,0] neg_lo:[1,0]
	v_pk_fma_f32 v[78:79], v[78:79], v[128:129], v[98:99] op_sel_hi:[1,0,1]
	s_nop 0
	v_xor_b32_e32 v98, 0x80000000, v79
	v_mov_b32_e32 v99, v79
	v_pk_mul_f32 v[98:99], v[98:99], v[134:135] op_sel:[0,1] op_sel_hi:[1,0]
	s_nop 0
	v_pk_fma_f32 v[98:99], v[134:135], v[78:79], v[98:99] op_sel_hi:[1,0,1]
	ds_write2_b64 v143, v[88:89], v[98:99] offset0:103 offset1:136
	v_pk_mul_f32 v[88:89], v[136:137], v[78:79] op_sel:[0,1] op_sel_hi:[0,0] neg_lo:[1,0]
	v_pk_fma_f32 v[78:79], v[78:79], v[128:129], v[88:89] op_sel_hi:[1,0,1]
	s_nop 0
	v_xor_b32_e32 v88, 0x80000000, v79
	v_mov_b32_e32 v89, v79
	v_pk_mul_f32 v[88:89], v[88:89], v[110:111] op_sel:[0,1] op_sel_hi:[1,0]
	v_pk_mul_f32 v[98:99], v[136:137], v[78:79] op_sel:[0,1] op_sel_hi:[0,0] neg_lo:[1,0]
	v_pk_fma_f32 v[88:89], v[110:111], v[78:79], v[88:89] op_sel_hi:[1,0,1]
	v_pk_fma_f32 v[78:79], v[78:79], v[128:129], v[98:99] op_sel_hi:[1,0,1]
	s_nop 0
	v_xor_b32_e32 v98, 0x80000000, v79
	v_mov_b32_e32 v99, v79
	v_pk_mul_f32 v[98:99], v[98:99], v[120:121] op_sel:[0,1] op_sel_hi:[1,0]
	s_nop 0
	v_pk_fma_f32 v[98:99], v[120:121], v[78:79], v[98:99] op_sel_hi:[1,0,1]
	ds_write2_b64 v144, v[88:89], v[98:99] offset0:41 offset1:74
	v_pk_mul_f32 v[88:89], v[136:137], v[78:79] op_sel:[0,1] op_sel_hi:[0,0] neg_lo:[1,0]
	v_pk_fma_f32 v[78:79], v[78:79], v[128:129], v[88:89] op_sel_hi:[1,0,1]
	s_nop 0
	v_xor_b32_e32 v88, 0x80000000, v79
	v_mov_b32_e32 v89, v79
	v_pk_mul_f32 v[88:89], v[88:89], v[94:95] op_sel:[0,1] op_sel_hi:[1,0]
	s_nop 0
	v_pk_fma_f32 v[88:89], v[94:95], v[78:79], v[88:89] op_sel_hi:[1,0,1]
	v_pk_mul_f32 v[94:95], v[136:137], v[78:79] op_sel:[0,1] op_sel_hi:[0,0] neg_lo:[1,0]
	v_pk_fma_f32 v[78:79], v[78:79], v[128:129], v[94:95] op_sel_hi:[1,0,1]
	s_nop 0
	v_xor_b32_e32 v94, 0x80000000, v79
	v_mov_b32_e32 v95, v79
	v_pk_mul_f32 v[94:95], v[130:131], v[94:95] op_sel:[1,0] op_sel_hi:[0,1]
	v_pk_fma_f32 v[94:95], v[130:131], v[78:79], v[94:95] op_sel_hi:[1,0,1]
	ds_write2_b64 v144, v[88:89], v[94:95] offset0:107 offset1:140
	v_pk_mul_f32 v[88:89], v[136:137], v[78:79] op_sel:[0,1] op_sel_hi:[0,0] neg_lo:[1,0]
	v_pk_fma_f32 v[78:79], v[78:79], v[128:129], v[88:89] op_sel_hi:[1,0,1]
	s_nop 0
	v_xor_b32_e32 v88, 0x80000000, v79
	v_mov_b32_e32 v89, v79
	v_pk_mul_f32 v[88:89], v[92:93], v[88:89] op_sel:[1,0] op_sel_hi:[0,1]
	v_pk_fma_f32 v[88:89], v[92:93], v[78:79], v[88:89] op_sel_hi:[1,0,1]
	v_pk_mul_f32 v[92:93], v[136:137], v[78:79] op_sel:[0,1] op_sel_hi:[0,0] neg_lo:[1,0]
	v_pk_fma_f32 v[78:79], v[78:79], v[128:129], v[92:93] op_sel_hi:[1,0,1]
	s_nop 0
	v_xor_b32_e32 v92, 0x80000000, v79
	v_mov_b32_e32 v93, v79
	v_pk_mul_f32 v[92:93], v[114:115], v[92:93] op_sel:[1,0] op_sel_hi:[0,1]
	v_pk_fma_f32 v[92:93], v[114:115], v[78:79], v[92:93] op_sel_hi:[1,0,1]
	ds_write2_b64 v144, v[88:89], v[92:93] offset0:173 offset1:206
	v_pk_mul_f32 v[88:89], v[136:137], v[78:79] op_sel:[0,1] op_sel_hi:[0,0] neg_lo:[1,0]
	v_pk_fma_f32 v[78:79], v[78:79], v[128:129], v[88:89] op_sel_hi:[1,0,1]
	s_nop 0
	v_xor_b32_e32 v88, 0x80000000, v79
	v_mov_b32_e32 v89, v79
	v_pk_mul_f32 v[88:89], v[126:127], v[88:89] op_sel:[1,0] op_sel_hi:[0,1]
	v_pk_mul_f32 v[92:93], v[136:137], v[78:79] op_sel:[0,1] op_sel_hi:[0,0] neg_lo:[1,0]
	v_pk_fma_f32 v[88:89], v[126:127], v[78:79], v[88:89] op_sel_hi:[1,0,1]
	v_pk_fma_f32 v[78:79], v[78:79], v[128:129], v[92:93] op_sel_hi:[1,0,1]
	s_nop 0
	v_xor_b32_e32 v92, 0x80000000, v79
	v_mov_b32_e32 v93, v79
	v_pk_mul_f32 v[92:93], v[80:81], v[92:93] op_sel:[1,0] op_sel_hi:[0,1]
	v_pk_fma_f32 v[80:81], v[80:81], v[78:79], v[92:93] op_sel_hi:[1,0,1]
	ds_write2_b64 v145, v[88:89], v[80:81] offset0:111 offset1:144
	v_pk_mul_f32 v[80:81], v[136:137], v[78:79] op_sel:[0,1] op_sel_hi:[0,0] neg_lo:[1,0]
	v_pk_fma_f32 v[78:79], v[78:79], v[128:129], v[80:81] op_sel_hi:[1,0,1]
	s_nop 0
	v_xor_b32_e32 v80, 0x80000000, v79
	v_mov_b32_e32 v81, v79
	v_pk_mul_f32 v[80:81], v[82:83], v[80:81] op_sel:[1,0] op_sel_hi:[0,1]
	v_pk_fma_f32 v[80:81], v[82:83], v[78:79], v[80:81] op_sel_hi:[1,0,1]
	v_pk_mul_f32 v[82:83], v[136:137], v[78:79] op_sel:[0,1] op_sel_hi:[0,0] neg_lo:[1,0]
	v_pk_fma_f32 v[78:79], v[78:79], v[128:129], v[82:83] op_sel_hi:[1,0,1]
	s_nop 0
	v_xor_b32_e32 v82, 0x80000000, v79
	v_mov_b32_e32 v83, v79
	v_pk_mul_f32 v[82:83], v[106:107], v[82:83] op_sel:[1,0] op_sel_hi:[0,1]
	v_pk_fma_f32 v[82:83], v[106:107], v[78:79], v[82:83] op_sel_hi:[1,0,1]
	ds_write2_b64 v146, v[80:81], v[82:83] offset0:49 offset1:82
	v_pk_mul_f32 v[80:81], v[136:137], v[78:79] op_sel:[0,1] op_sel_hi:[0,0] neg_lo:[1,0]
	v_pk_fma_f32 v[78:79], v[78:79], v[128:129], v[80:81] op_sel_hi:[1,0,1]
	s_nop 0
	v_xor_b32_e32 v80, 0x80000000, v79
	v_mov_b32_e32 v81, v79
	v_pk_mul_f32 v[80:81], v[74:75], v[80:81] op_sel:[1,0] op_sel_hi:[0,1]
	v_pk_fma_f32 v[74:75], v[74:75], v[78:79], v[80:81] op_sel_hi:[1,0,1]
	v_pk_mul_f32 v[80:81], v[136:137], v[78:79] op_sel:[0,1] op_sel_hi:[0,0] neg_lo:[1,0]
	v_pk_fma_f32 v[78:79], v[78:79], v[128:129], v[80:81] op_sel_hi:[1,0,1]
	s_nop 0
	v_xor_b32_e32 v80, 0x80000000, v79
	v_mov_b32_e32 v81, v79
	v_pk_mul_f32 v[80:81], v[124:125], v[80:81] op_sel:[1,0] op_sel_hi:[0,1]
	v_pk_fma_f32 v[80:81], v[124:125], v[78:79], v[80:81] op_sel_hi:[1,0,1]
	ds_write2_b64 v146, v[74:75], v[80:81] offset0:115 offset1:148
	v_pk_mul_f32 v[74:75], v[136:137], v[78:79] op_sel:[0,1] op_sel_hi:[0,0] neg_lo:[1,0]
	v_pk_fma_f32 v[74:75], v[78:79], v[128:129], v[74:75] op_sel_hi:[1,0,1]
	s_nop 0
	v_xor_b32_e32 v78, 0x80000000, v75
	v_mov_b32_e32 v79, v75
	v_pk_mul_f32 v[78:79], v[84:85], v[78:79] op_sel:[1,0] op_sel_hi:[0,1]
	v_pk_mul_f32 v[80:81], v[136:137], v[74:75] op_sel:[0,1] op_sel_hi:[0,0] neg_lo:[1,0]
	v_pk_fma_f32 v[78:79], v[84:85], v[74:75], v[78:79] op_sel_hi:[1,0,1]
	v_pk_fma_f32 v[74:75], v[74:75], v[128:129], v[80:81] op_sel_hi:[1,0,1]
	s_nop 0
	v_xor_b32_e32 v80, 0x80000000, v75
	v_mov_b32_e32 v81, v75
	v_pk_mul_f32 v[80:81], v[100:101], v[80:81] op_sel:[1,0] op_sel_hi:[0,1]
	v_pk_fma_f32 v[80:81], v[100:101], v[74:75], v[80:81] op_sel_hi:[1,0,1]
	ds_write2_b64 v146, v[78:79], v[80:81] offset0:181 offset1:214
	v_pk_mul_f32 v[78:79], v[136:137], v[74:75] op_sel:[0,1] op_sel_hi:[0,0] neg_lo:[1,0]
	v_pk_fma_f32 v[74:75], v[74:75], v[128:129], v[78:79] op_sel_hi:[1,0,1]
	s_nop 0
	v_xor_b32_e32 v78, 0x80000000, v75
	v_mov_b32_e32 v79, v75
	v_pk_mul_f32 v[78:79], v[90:91], v[78:79] op_sel:[1,0] op_sel_hi:[0,1]
	v_pk_mul_f32 v[80:81], v[136:137], v[74:75] op_sel:[0,1] op_sel_hi:[0,0] neg_lo:[1,0]
	v_pk_fma_f32 v[78:79], v[90:91], v[74:75], v[78:79] op_sel_hi:[1,0,1]
	v_pk_fma_f32 v[74:75], v[74:75], v[128:129], v[80:81] op_sel_hi:[1,0,1]
	s_nop 0
	v_xor_b32_e32 v80, 0x80000000, v75
	v_mov_b32_e32 v81, v75
	v_pk_mul_f32 v[80:81], v[96:97], v[80:81] op_sel:[1,0] op_sel_hi:[0,1]
	v_pk_fma_f32 v[80:81], v[96:97], v[74:75], v[80:81] op_sel_hi:[1,0,1]
	ds_write2_b64 v147, v[78:79], v[80:81] offset0:119 offset1:152
	v_pk_mul_f32 v[78:79], v[136:137], v[74:75] op_sel:[0,1] op_sel_hi:[0,0] neg_lo:[1,0]
	v_pk_fma_f32 v[74:75], v[74:75], v[128:129], v[78:79] op_sel_hi:[1,0,1]
	s_nop 0
	v_xor_b32_e32 v78, 0x80000000, v75
	v_mov_b32_e32 v79, v75
	v_pk_mul_f32 v[78:79], v[112:113], v[78:79] op_sel:[1,0] op_sel_hi:[0,1]
	v_pk_mul_f32 v[80:81], v[136:137], v[74:75] op_sel:[0,1] op_sel_hi:[0,0] neg_lo:[1,0]
	v_pk_fma_f32 v[78:79], v[112:113], v[74:75], v[78:79] op_sel_hi:[1,0,1]
	v_pk_fma_f32 v[74:75], v[74:75], v[128:129], v[80:81] op_sel_hi:[1,0,1]
	s_nop 0
	v_xor_b32_e32 v80, 0x80000000, v75
	v_mov_b32_e32 v81, v75
	v_pk_mul_f32 v[80:81], v[108:109], v[80:81] op_sel:[1,0] op_sel_hi:[0,1]
	v_pk_fma_f32 v[80:81], v[108:109], v[74:75], v[80:81] op_sel_hi:[1,0,1]
	ds_write2_b64 v70, v[78:79], v[80:81] offset0:57 offset1:90
	v_pk_mul_f32 v[78:79], v[136:137], v[74:75] op_sel:[0,1] op_sel_hi:[0,0] neg_lo:[1,0]
	v_pk_fma_f32 v[74:75], v[74:75], v[128:129], v[78:79] op_sel_hi:[1,0,1]
	s_nop 0
	v_xor_b32_e32 v78, 0x80000000, v75
	v_mov_b32_e32 v79, v75
	v_pk_mul_f32 v[78:79], v[76:77], v[78:79] op_sel:[1,0] op_sel_hi:[0,1]
	v_pk_fma_f32 v[76:77], v[76:77], v[74:75], v[78:79] op_sel_hi:[1,0,1]
	v_pk_mul_f32 v[78:79], v[136:137], v[74:75] op_sel:[0,1] op_sel_hi:[0,0] neg_lo:[1,0]
	v_pk_fma_f32 v[74:75], v[74:75], v[128:129], v[78:79] op_sel_hi:[1,0,1]
	s_nop 0
	v_xor_b32_e32 v78, 0x80000000, v75
	v_mov_b32_e32 v79, v75
	v_pk_mul_f32 v[78:79], v[68:69], v[78:79] op_sel:[1,0] op_sel_hi:[0,1]
	v_pk_fma_f32 v[68:69], v[68:69], v[74:75], v[78:79] op_sel_hi:[1,0,1]
	ds_write2_b64 v70, v[76:77], v[68:69] offset0:123 offset1:156
	v_pk_mul_f32 v[68:69], v[136:137], v[74:75] op_sel:[0,1] op_sel_hi:[0,0] neg_lo:[1,0]
	v_pk_fma_f32 v[68:69], v[74:75], v[128:129], v[68:69] op_sel_hi:[1,0,1]
	s_nop 0
	v_xor_b32_e32 v74, 0x80000000, v69
	v_mov_b32_e32 v75, v69
	v_pk_mul_f32 v[74:75], v[86:87], v[74:75] op_sel:[1,0] op_sel_hi:[0,1]
	v_pk_mul_f32 v[76:77], v[136:137], v[68:69] op_sel:[0,1] op_sel_hi:[0,0] neg_lo:[1,0]
	v_pk_fma_f32 v[74:75], v[86:87], v[68:69], v[74:75] op_sel_hi:[1,0,1]
	v_pk_fma_f32 v[68:69], v[68:69], v[128:129], v[76:77] op_sel_hi:[1,0,1]
	s_nop 0
	v_xor_b32_e32 v76, 0x80000000, v69
	v_mov_b32_e32 v77, v69
	v_pk_mul_f32 v[76:77], v[66:67], v[76:77] op_sel:[1,0] op_sel_hi:[0,1]
	v_pk_fma_f32 v[66:67], v[66:67], v[68:69], v[76:77] op_sel_hi:[1,0,1]
	ds_write2_b64 v70, v[74:75], v[66:67] offset0:189 offset1:222
	v_pk_mul_f32 v[66:67], v[136:137], v[68:69] op_sel:[0,1] op_sel_hi:[0,0] neg_lo:[1,0]
	v_pk_fma_f32 v[66:67], v[68:69], v[128:129], v[66:67] op_sel_hi:[1,0,1]
	s_nop 0
	v_xor_b32_e32 v68, 0x80000000, v67
	v_mov_b32_e32 v69, v67
	v_pk_mul_f32 v[68:69], v[72:73], v[68:69] op_sel:[1,0] op_sel_hi:[0,1]
	v_pk_fma_f32 v[66:67], v[72:73], v[66:67], v[68:69] op_sel_hi:[1,0,1]
	ds_write_b64 v0, v[66:67] offset:8184
	s_waitcnt lgkmcnt(0)
	s_barrier
.LBB0_364:
	v_mov_b32 v66, 0
	v_cndmask_b32_e64 v0, 0, 1, s[48:49]
	v_add3_u32 v66, s5, v170, v66
	v_add_u32_e32 v68, 0x400, v66
	v_add_u32_e32 v69, 0x800, v66
	v_add_u32_e32 v71, 0xc00, v66
	v_add_u32_e32 v72, 0x1000, v66
	v_add_u32_e32 v73, 0x1400, v66
	v_add_u32_e32 v74, 0x1800, v66
	v_add_u32_e32 v75, 0x1c00, v66
	v_add_u32_e32 v76, 0x2000, v66
	v_add_u32_e32 v77, 0x2400, v66
	v_add_u32_e32 v78, 0x2800, v66
	v_add_u32_e32 v81, 0x3400, v66
	v_add_u32_e32 v82, 0x3800, v66
	v_add_u32_e32 v83, 0x3c00, v66
	v_cmp_ne_u32_e64 s[0:1], 1, v0
	v_ashrrev_i32_e32 v0, 5, v66
	v_add_u32_e32 v79, 0x2c00, v66
	v_add_u32_e32 v80, 0x3000, v66
	v_ashrrev_i32_e32 v68, 5, v68
	v_ashrrev_i32_e32 v69, 5, v69
	v_ashrrev_i32_e32 v71, 5, v71
	v_ashrrev_i32_e32 v72, 5, v72
	v_ashrrev_i32_e32 v73, 5, v73
	v_ashrrev_i32_e32 v74, 5, v74
	v_ashrrev_i32_e32 v75, 5, v75
	v_ashrrev_i32_e32 v84, 5, v76
	v_ashrrev_i32_e32 v85, 5, v77
	v_ashrrev_i32_e32 v86, 5, v78
	v_ashrrev_i32_e32 v89, 5, v81
	v_ashrrev_i32_e32 v90, 5, v82
	v_ashrrev_i32_e32 v91, 5, v83
	v_lshlrev_b32_e32 v70, 3, v66
	v_lshlrev_b32_e32 v0, 3, v0
	v_lshlrev_b32_e32 v76, 3, v76
	v_lshlrev_b32_e32 v77, 3, v77
	v_lshlrev_b32_e32 v78, 3, v78
	v_ashrrev_i32_e32 v87, 5, v79
	v_ashrrev_i32_e32 v88, 5, v80
	v_lshlrev_b32_e32 v81, 3, v81
	v_lshlrev_b32_e32 v82, 3, v82
	v_lshlrev_b32_e32 v83, 3, v83
	v_lshlrev_b32_e32 v92, 3, v68
	v_lshlrev_b32_e32 v93, 3, v69
	v_lshlrev_b32_e32 v71, 3, v71
	v_lshlrev_b32_e32 v72, 3, v72
	v_lshlrev_b32_e32 v73, 3, v73
	v_lshlrev_b32_e32 v74, 3, v74
	v_lshlrev_b32_e32 v75, 3, v75
	v_lshlrev_b32_e32 v84, 3, v84
	v_lshlrev_b32_e32 v85, 3, v85
	v_lshlrev_b32_e32 v86, 3, v86
	v_lshlrev_b32_e32 v89, 3, v89
	v_lshlrev_b32_e32 v90, 3, v90
	v_lshlrev_b32_e32 v91, 3, v91
	v_ashrrev_i32_e32 v67, 31, v66
	v_lshlrev_b32_e32 v79, 3, v79
	v_lshlrev_b32_e32 v80, 3, v80
	v_add3_u32 v0, 0, v0, v70
	v_lshlrev_b32_e32 v87, 3, v87
	v_lshlrev_b32_e32 v88, 3, v88
	v_add3_u32 v92, 0, v92, v70
	v_add3_u32 v93, 0, v93, v70
	v_add3_u32 v94, 0, v71, v70
	v_add3_u32 v95, 0, v72, v70
	v_add3_u32 v96, 0, v73, v70
	v_add3_u32 v97, 0, v74, v70
	v_add3_u32 v98, 0, v75, v70
	v_add3_u32 v99, 0, v84, v76
	v_add3_u32 v100, 0, v85, v77
	v_add3_u32 v101, 0, v86, v78
	v_add3_u32 v108, 0, v89, v81
	v_add3_u32 v110, 0, v90, v82
	v_add3_u32 v112, 0, v91, v83
	v_lshlrev_b64 v[66:67], 1, v[66:67]
	v_add3_u32 v79, 0, v87, v79
	v_add3_u32 v105, 0, v88, v80
	ds_read_b64 v[80:81], v0
	ds_read_b64 v[82:83], v92 offset:8192
	ds_read_b64 v[84:85], v93 offset:16384
	ds_read_b64 v[86:87], v94 offset:24576
	ds_read_b64 v[88:89], v95 offset:32768
	ds_read_b64 v[90:91], v96 offset:40960
	ds_read_b64 v[92:93], v97 offset:49152
	ds_read_b64 v[94:95], v98 offset:57344
	ds_read_b64 v[96:97], v99
	ds_read_b64 v[98:99], v100
	ds_read_b64 v[100:101], v101
	ds_read_b64 v[102:103], v79
	ds_read_b64 v[106:107], v105
	ds_read_b64 v[108:109], v108
	ds_read_b64 v[110:111], v110
	ds_read_b64 v[112:113], v112
	v_lshl_add_u64 v[68:69], s[44:45], 0, v[66:67]
	v_add_co_u32_e32 v70, vcc, s58, v68
	v_lshl_add_u64 v[66:67], s[46:47], 0, v[66:67]
	s_nop 0
	v_addc_co_u32_e32 v71, vcc, 0, v69, vcc
	v_add_co_u32_e32 v72, vcc, s59, v68
	s_waitcnt lgkmcnt(7)
	v_pk_add_f32 v[116:117], v[80:81], v[96:97]
	v_addc_co_u32_e32 v73, vcc, 0, v69, vcc
	v_pk_add_f32 v[80:81], v[80:81], v[96:97] neg_lo:[0,1] neg_hi:[0,1]
	s_waitcnt lgkmcnt(6)
	v_pk_add_f32 v[96:97], v[82:83], v[98:99]
	v_pk_add_f32 v[82:83], v[82:83], v[98:99] neg_lo:[0,1] neg_hi:[0,1]
	s_waitcnt lgkmcnt(5)
	v_pk_add_f32 v[98:99], v[84:85], v[100:101]
	v_pk_add_f32 v[84:85], v[84:85], v[100:101] neg_lo:[0,1] neg_hi:[0,1]
	s_waitcnt lgkmcnt(4)
	v_pk_add_f32 v[100:101], v[86:87], v[102:103]
	v_pk_add_f32 v[86:87], v[86:87], v[102:103] neg_lo:[0,1] neg_hi:[0,1]
	s_waitcnt lgkmcnt(3)
	v_pk_add_f32 v[102:103], v[88:89], v[106:107]
	v_pk_add_f32 v[122:123], v[88:89], v[106:107] op_sel:[1,1] op_sel_hi:[0,0] neg_lo:[1,0] neg_hi:[0,1]
	s_waitcnt lgkmcnt(2)
	v_pk_add_f32 v[106:107], v[90:91], v[108:109]
	v_pk_add_f32 v[90:91], v[90:91], v[108:109] neg_lo:[0,1] neg_hi:[0,1]
	s_waitcnt lgkmcnt(1)
	v_pk_add_f32 v[108:109], v[92:93], v[110:111]
	v_pk_add_f32 v[92:93], v[92:93], v[110:111] neg_lo:[0,1] neg_hi:[0,1]
	s_waitcnt lgkmcnt(0)
	v_pk_add_f32 v[110:111], v[94:95], v[112:113]
	v_pk_add_f32 v[94:95], v[94:95], v[112:113] neg_lo:[0,1] neg_hi:[0,1]
	s_movk_i32 s5, 0x200
	v_add_co_u32_e32 v74, vcc, s58, v66
	v_pk_mul_f32 v[112:113], v[82:83], s[14:15]
	v_pk_mul_f32 v[118:119], v[84:85], s[10:11]
	v_pk_mul_f32 v[120:121], v[86:87], s[6:7]
	v_pk_mul_f32 v[88:89], v[90:91], s[6:7]
	v_pk_mul_f32 v[124:125], v[92:93], s[10:11]
	v_pk_mul_f32 v[126:127], v[94:95], s[14:15]
	v_pk_add_f32 v[128:129], v[116:117], v[102:103]
	v_pk_add_f32 v[102:103], v[116:117], v[102:103] neg_lo:[0,1] neg_hi:[0,1]
	v_pk_add_f32 v[116:117], v[96:97], v[106:107]
	v_pk_add_f32 v[96:97], v[96:97], v[106:107] neg_lo:[0,1] neg_hi:[0,1]
	v_pk_add_f32 v[106:107], v[98:99], v[108:109]
	v_pk_add_f32 v[98:99], v[98:99], v[108:109] neg_lo:[0,1] neg_hi:[0,1]
	v_pk_add_f32 v[108:109], v[100:101], v[110:111]
	v_pk_add_f32 v[100:101], v[100:101], v[110:111] neg_lo:[0,1] neg_hi:[0,1]
	v_addc_co_u32_e32 v75, vcc, 0, v67, vcc
	v_pk_fma_f32 v[82:83], v[82:83], s[6:7], v[112:113] op_sel:[0,0,1] op_sel_hi:[1,0,0]
	v_pk_fma_f32 v[84:85], v[84:85], s[10:11], v[118:119] op_sel:[0,0,1] op_sel_hi:[1,0,0]
	v_pk_fma_f32 v[86:87], v[86:87], s[14:15], v[120:121] op_sel:[0,0,1] op_sel_hi:[1,0,0]
	v_pk_fma_f32 v[88:89], v[90:91], s[4:5], v[88:89] op_sel:[0,0,1] op_sel_hi:[1,0,0]
	v_pk_fma_f32 v[90:91], v[92:93], s[8:9], v[124:125] op_sel:[0,0,1] op_sel_hi:[1,0,0]
	v_pk_fma_f32 v[92:93], v[94:95], s[12:13], v[126:127] op_sel:[0,0,1] op_sel_hi:[1,0,0]
	v_pk_mul_f32 v[94:95], v[96:97], s[10:11]
	v_xor_b32_e32 v110, 0x80000000, v99
	v_mov_b32_e32 v111, v98
	v_pk_mul_f32 v[98:99], v[100:101], s[10:11]
	v_add_co_u32_e32 v76, vcc, s59, v66
	v_pk_add_f32 v[118:119], v[128:129], v[106:107]
	v_pk_add_f32 v[120:121], v[116:117], v[108:109]
	v_pk_add_f32 v[108:109], v[116:117], v[108:109] neg_lo:[0,1] neg_hi:[0,1]
	v_pk_fma_f32 v[94:95], v[96:97], s[10:11], v[94:95] op_sel:[0,0,1] op_sel_hi:[1,0,0]
	v_pk_fma_f32 v[96:97], v[100:101], s[8:9], v[98:99] op_sel:[0,0,1] op_sel_hi:[1,0,0]
	v_pk_add_f32 v[98:99], v[82:83], v[88:89]
	v_pk_add_f32 v[82:83], v[82:83], v[88:89] neg_lo:[0,1] neg_hi:[0,1]
	v_pk_add_f32 v[88:89], v[84:85], v[90:91]
	v_pk_add_f32 v[116:117], v[84:85], v[90:91] op_sel:[1,1] op_sel_hi:[0,0] neg_lo:[1,0] neg_hi:[0,1]
	v_pk_add_f32 v[90:91], v[86:87], v[92:93]
	v_pk_add_f32 v[86:87], v[86:87], v[92:93] neg_lo:[0,1] neg_hi:[0,1]
	v_addc_co_u32_e32 v77, vcc, 0, v67, vcc
	v_pk_add_f32 v[112:113], v[80:81], v[122:123]
	v_pk_add_f32 v[106:107], v[128:129], v[106:107] neg_lo:[0,1] neg_hi:[0,1]
	v_xor_b32_e32 v92, 0x80000000, v109
	v_mov_b32_e32 v93, v108
	v_pk_add_f32 v[100:101], v[102:103], v[110:111]
	v_pk_add_f32 v[102:103], v[102:103], v[110:111] neg_lo:[0,1] neg_hi:[0,1]
	v_pk_add_f32 v[108:109], v[118:119], v[120:121]
	v_pk_mul_f32 v[110:111], v[82:83], s[10:11]
	v_pk_mul_f32 v[84:85], v[86:87], s[10:11]
	v_add_co_u32_e32 v78, vcc, s60, v68
	v_pk_add_f32 v[118:119], v[94:95], v[96:97]
	v_pk_add_f32 v[94:95], v[94:95], v[96:97] neg_lo:[0,1] neg_hi:[0,1]
	v_pk_add_f32 v[96:97], v[112:113], v[88:89]
	v_pk_add_f32 v[88:89], v[112:113], v[88:89] neg_lo:[0,1] neg_hi:[0,1]
	v_pk_add_f32 v[112:113], v[98:99], v[90:91]
	v_pk_add_f32 v[90:91], v[98:99], v[90:91] neg_lo:[0,1] neg_hi:[0,1]
	v_pk_add_f32 v[92:93], v[106:107], v[92:93]
	v_cvt_pk_bf16_f32 v0, v108, s0
	v_pk_fma_f32 v[82:83], v[82:83], s[10:11], v[110:111] op_sel:[0,0,1] op_sel_hi:[1,0,0]
	v_pk_fma_f32 v[84:85], v[86:87], s[8:9], v[84:85] op_sel:[0,0,1] op_sel_hi:[1,0,0]
	v_addc_co_u32_e32 v79, vcc, 0, v69, vcc
	v_pk_add_f32 v[80:81], v[80:81], v[122:123] neg_lo:[0,1] neg_hi:[0,1]
	v_cvt_pk_bf16_f32 v105, v109, s0
	v_xor_b32_e32 v86, 0x80000000, v95
	v_mov_b32_e32 v87, v94
	v_xor_b32_e32 v94, 0x80000000, v91
	v_mov_b32_e32 v95, v90
	v_pk_add_f32 v[98:99], v[100:101], v[118:119]
	v_pk_add_f32 v[96:97], v[96:97], v[112:113]
	global_store_short v[68:69], v0, off
	global_store_short v[66:67], v105, off
	v_cvt_pk_bf16_f32 v0, v92, s0
	v_cvt_pk_bf16_f32 v100, v93, s0
	v_pk_add_f32 v[92:93], v[82:83], v[84:85]
	v_pk_add_f32 v[82:83], v[82:83], v[84:85] neg_lo:[0,1] neg_hi:[0,1]
	v_add_co_u32_e32 v114, vcc, 0x3000, v66
	v_pk_add_f32 v[90:91], v[80:81], v[116:117]
	v_pk_add_f32 v[80:81], v[80:81], v[116:117] neg_lo:[0,1] neg_hi:[0,1]
	v_pk_add_f32 v[84:85], v[102:103], v[86:87]
	v_pk_add_f32 v[86:87], v[88:89], v[94:95]
	v_cvt_pk_bf16_f32 v94, v96, s0
	v_xor_b32_e32 v88, 0x80000000, v83
	v_mov_b32_e32 v89, v82
	v_addc_co_u32_e32 v115, vcc, 0, v67, vcc
	v_cvt_pk_bf16_f32 v95, v97, s0
	v_cvt_pk_bf16_f32 v96, v98, s0
	v_cvt_pk_bf16_f32 v97, v99, s0
	global_store_short v[72:73], v0, off
	global_store_short v[76:77], v100, off
	v_pk_add_f32 v[82:83], v[90:91], v[92:93]
	global_store_short v[68:69], v94, off offset:2048
	global_store_short v[66:67], v95, off offset:2048
	global_store_short v[72:73], v96, off offset:-4096
	global_store_short v[76:77], v97, off offset:-4096
	v_cvt_pk_bf16_f32 v0, v86, s0
	v_pk_add_f32 v[66:67], v[80:81], v[88:89]
	s_mov_b64 s[48:49], 0
	s_and_b64 vcc, exec, s[0:1]
	v_cvt_pk_bf16_f32 v68, v87, s0
	v_cvt_pk_bf16_f32 v69, v84, s0
	v_cvt_pk_bf16_f32 v84, v85, s0
	v_cvt_pk_bf16_f32 v80, v82, s0
	v_cvt_pk_bf16_f32 v81, v83, s0
	global_store_short v[72:73], v0, off offset:2048
	global_store_short v[76:77], v68, off offset:2048
	global_store_short v[78:79], v69, off
	global_store_short v[114:115], v84, off
	global_store_short v[70:71], v80, off offset:2048
	global_store_short v[74:75], v81, off offset:2048
	v_cvt_pk_bf16_f32 v0, v66, s0
	v_cvt_pk_bf16_f32 v66, v67, s0
	global_store_short v[78:79], v0, off offset:2048
	global_store_short v[114:115], v66, off offset:2048
	s_cbranch_vccz .LBB0_364
	s_mov_b64 s[0:1], 0x4000
	s_mov_b64 s[44:45], 0
	s_and_b64 vcc, exec, s[42:43]
	s_cbranch_vccz .LBB0_361
	s_add_i32 s40, s40, s30
	s_cmpk_gt_i32 s40, 0x3ff
	s_barrier
	s_cbranch_scc0 .LBB0_358
